# row loops (norm x3, comb, scan) de-serialised with up-front loads and next-row prefetch; residual GEMM epilogues (4 instances) prefetch x rows per round, gate loaded once
# speedup vs baseline: 1.0254x; 1.0254x over previous
; DI unsigned cvtpk(float lo, float hi) { unsigned r; asm volatile("v_cvt_pk_bf16_f32 %0, %1, %2" : "=v"(r) : "v"(lo), "v"(hi)); return r; }
; DI int otid() { int t = threadIdx.x; asm volatile("" : "+v"(t)); return t; }
; DI int obid() { int b = blockIdx.x; asm volatile("" : "+s"(b)); return b; }
; DI float ex2(float x) { return __builtin_amdgcn_exp2f(x); }
; DI KParams kp() { KParams k = (KParams)__builtin_amdgcn_kernarg_segment_ptr(); asm volatile("" : "+s"(k)); return k; }
; DI void phase_ret_scan() {
;   KParams P = kp(); char* ws = P->ws;
;   const int nb = gridDim.x, bid = obid(), tid = otid();
;   const float* dec = WSP(float, OFF_DEC);
;   u16* Bcat = GBP(u16, G_BCAT);
;   for (int i = bid * 512 + tid; i < 16 * 512 * 64; i += nb * 512) {
;     const int sh = i >> 15, e = (i >> 6) & 511, c = i & 63, dir = c >> 5, hh = sh & 3;
;     const float dk = ex2(dec[dir * 4 + hh] * 256.f);
;     u16* base = Bcat + ((size_t)(sh * 16) * 512 + e) * 768 + 256 + c * 8;
;     float S[8];
; #pragma unroll
;     for (int j = 0; j < 8; ++j) S[j] = 0.f;
; #pragma unroll
;     for (int k = 0; k < 16; ++k) {
;       const int sc = dir ? (15 - k) : k;
;       u16* pp = base + (size_t)sc * 393216;
;       const u32x4 uu = *(const u32x4*)pp;
;       u32x4 w = {cvtpk(S[0], S[1]), cvtpk(S[2], S[3]), cvtpk(S[4], S[5]), cvtpk(S[6], S[7])};
;       *(u32x4*)pp = w;
; #pragma unroll
;       for (int j = 0; j < 4; ++j) {
;         S[2 * j] = S[2 * j] * dk + __uint_as_float(uu[j] << 16);
;         S[2 * j + 1] = S[2 * j + 1] * dk + __uint_as_float(uu[j] & 0xffff0000u);
;       }
;     }
.LBB0_424:
	s_or_b64 exec, exec, s[8:9]
	v_readlane_b32 s10, v255, 0
	v_readlane_b32 s11, v255, 1
	s_mov_b32 s0, s80
	s_waitcnt lgkmcnt(0)
	v_mov_b32_e32 v0, v182
	s_barrier
	s_nop 0
	v_lshl_add_u32 v36, s0, 9, v0
	v_cmp_gt_i32_e32 vcc, s88, v36
	s_and_saveexec_b64 s[8:9], vcc
	s_mov_b64 s[16:17], 0x1362c300
	s_cbranch_execz .LBB0_427
	s_load_dwordx2 s[10:11], s[10:11], 0x98
	v_and_b32_e32 v1, 63, v0
	v_lshlrev_b32_e32 v0, 3, v1
	v_cmp_gt_u32_e32 vcc, 32, v1
	v_mov_b32_e32 v1, 0x5a0000
	v_mov_b32_e32 v3, 0x540000
	v_mov_b32_e32 v5, 0x60000
	v_mov_b32_e32 v7, 0x4e0000
	v_mov_b32_e32 v9, 0xc0000
	v_mov_b32_e32 v11, 0x480000
	v_mov_b32_e32 v13, 0x120000
	v_mov_b32_e32 v15, 0x420000
	v_mov_b32_e32 v17, 0x180000
	v_mov_b32_e32 v19, 0x3c0000
	v_mov_b32_e32 v21, 0x1e0000
	v_mov_b32_e32 v20, 0x360000
	v_mov_b32_e32 v22, 0x240000
	v_mov_b32_e32 v18, 0x300000
	v_cndmask_b32_e64 v2, v1, 0, vcc
	s_waitcnt lgkmcnt(0)
	s_add_u32 s12, s10, 0x362c000
	v_cndmask_b32_e32 v4, v3, v5, vcc
	v_cndmask_b32_e32 v6, v7, v9, vcc
	v_cndmask_b32_e32 v8, v11, v13, vcc
	v_cndmask_b32_e32 v10, v15, v17, vcc
	v_cndmask_b32_e32 v12, v19, v21, vcc
	v_cndmask_b32_e32 v14, v20, v22, vcc
	v_cndmask_b32_e32 v16, v18, v159, vcc
	v_cndmask_b32_e32 v18, v159, v18, vcc
	v_cndmask_b32_e32 v20, v22, v20, vcc
	v_cndmask_b32_e32 v22, v21, v19, vcc
	v_cndmask_b32_e32 v24, v17, v15, vcc
	v_cndmask_b32_e32 v26, v13, v11, vcc
	v_cndmask_b32_e32 v28, v9, v7, vcc
	v_cndmask_b32_e32 v30, v5, v3, vcc
	v_cndmask_b32_e32 v32, 0, v1, vcc
	s_addc_u32 s13, s11, 0
	s_mov_b64 s[68:69], 0
	v_lshlrev_b32_e32 v128, 1, v0
	v_lshlrev_b32_e32 v0, 1, v2
	v_lshlrev_b32_e32 v2, 1, v4
	v_lshlrev_b32_e32 v4, 1, v6
	v_lshlrev_b32_e32 v6, 1, v8
	v_lshlrev_b32_e32 v8, 1, v10
	v_lshlrev_b32_e32 v10, 1, v12
	v_lshlrev_b32_e32 v12, 1, v14
	v_lshlrev_b32_e32 v14, 1, v16
	v_lshlrev_b32_e32 v16, 1, v18
	v_lshlrev_b32_e32 v18, 1, v20
	v_lshlrev_b32_e32 v20, 1, v22
	v_lshlrev_b32_e32 v22, 1, v24
	v_lshlrev_b32_e32 v24, 1, v26
	v_lshlrev_b32_e32 v26, 1, v28
	v_lshlrev_b32_e32 v28, 1, v30
	v_lshlrev_b32_e32 v30, 1, v32
	s_and_b64 vcc, exec, s[4:5]
	s_cbranch_vccz .LBB0_426
	v_ashrrev_i32_e32 v57, 15, v36
	v_lshrrev_b32_e32 v58, 3, v36
	v_and_b32_e32 v57, 3, v57
	v_and_or_b32 v57, v58, 4, v57
	v_lshlrev_b32_e32 v57, 2, v57
	global_load_dword v56, v57, s[12:13]
	v_readfirstlane_b32 vcc_lo, v36
	v_add_u32_e32 v1, v128, v0
	v_add_u32_e32 v3, v128, v2
	v_add_u32_e32 v5, v128, v4
	v_add_u32_e32 v7, v128, v6
	v_add_u32_e32 v9, v128, v8
	v_add_u32_e32 v11, v128, v10
	v_add_u32_e32 v13, v128, v12
	v_add_u32_e32 v15, v128, v14
	v_add_u32_e32 v17, v128, v16
	v_add_u32_e32 v19, v128, v18
	v_add_u32_e32 v21, v128, v20
	v_add_u32_e32 v23, v128, v22
	v_add_u32_e32 v25, v128, v24
	v_add_u32_e32 v27, v128, v26
	v_add_u32_e32 v29, v128, v28
	v_add_u32_e32 v31, v128, v30
	s_bfe_u32 vcc_hi, vcc_lo, 0x90006
	s_lshr_b32 vcc_lo, vcc_lo, 15
	s_lshl_b32 vcc_lo, vcc_lo, 13
	s_or_b32 vcc_lo, vcc_lo, vcc_hi
	s_mul_i32 vcc_lo, vcc_lo, 0x600
	s_add_u32 s68, s10, vcc_lo
	s_addc_u32 s69, s11, 0
	s_add_u32 s68, s68, s16
	s_addc_u32 s69, s69, s17
	s_add_u32 s0, s68, 0x3000000
	s_addc_u32 s1, s69, 0
	global_load_dwordx4 v[64:67], v1, s[68:69]
	global_load_dwordx4 v[68:71], v3, s[68:69]
	global_load_dwordx4 v[72:75], v5, s[68:69]
	global_load_dwordx4 v[76:79], v7, s[68:69]
	global_load_dwordx4 v[80:83], v9, s[68:69]
	global_load_dwordx4 v[84:87], v11, s[68:69]
	global_load_dwordx4 v[88:91], v13, s[68:69]
	global_load_dwordx4 v[92:95], v15, s[68:69]
	global_load_dwordx4 v[96:99], v17, s[68:69]
	global_load_dwordx4 v[100:103], v19, s[68:69]
	global_load_dwordx4 v[104:107], v21, s[68:69]
	global_load_dwordx4 v[108:111], v23, s[68:69]
	global_load_dwordx4 v[112:115], v25, s[68:69]
	global_load_dwordx4 v[116:119], v27, s[68:69]
	global_load_dwordx4 v[120:123], v29, s[68:69]
	global_load_dwordx4 v[124:127], v31, s[68:69]
	s_waitcnt vmcnt(16)
	v_mul_f32_e32 v56, 0x43800000, v56
	v_exp_f32_e32 v56, v56
	v_mov_b32_e32 v32, 0
	v_mov_b32_e32 v33, 0
	v_mov_b32_e32 v34, 0
	v_mov_b32_e32 v35, 0
	v_mov_b32_e32 v36, 0
	v_mov_b32_e32 v37, 0
	v_mov_b32_e32 v38, 0
	v_mov_b32_e32 v39, 0
	s_waitcnt vmcnt(15)
	v_cvt_pk_bf16_f32 v48, v32, v33
	v_cvt_pk_bf16_f32 v49, v34, v35
	v_cvt_pk_bf16_f32 v50, v36, v37
	v_cvt_pk_bf16_f32 v51, v38, v39
	global_store_dwordx4 v1, v[48:51], s[68:69]
	v_lshlrev_b32_e32 v40, 16, v64
	v_and_b32_e32 v41, 0xffff0000, v64
	v_lshlrev_b32_e32 v42, 16, v65
	v_and_b32_e32 v43, 0xffff0000, v65
	v_lshlrev_b32_e32 v44, 16, v66
	v_and_b32_e32 v45, 0xffff0000, v66
	v_lshlrev_b32_e32 v46, 16, v67
	v_and_b32_e32 v47, 0xffff0000, v67
	v_fmac_f32_e32 v40, v56, v32
	v_fmac_f32_e32 v41, v56, v33
	v_fmac_f32_e32 v42, v56, v34
	v_fmac_f32_e32 v43, v56, v35
	v_fmac_f32_e32 v44, v56, v36
	v_fmac_f32_e32 v45, v56, v37
	v_fmac_f32_e32 v46, v56, v38
	v_fmac_f32_e32 v47, v56, v39
	global_load_dwordx4 v[64:67], v1, s[0:1]
	s_waitcnt vmcnt(16)
	v_cvt_pk_bf16_f32 v52, v40, v41
	v_cvt_pk_bf16_f32 v53, v42, v43
	v_cvt_pk_bf16_f32 v54, v44, v45
	v_cvt_pk_bf16_f32 v55, v46, v47
	global_store_dwordx4 v3, v[52:55], s[68:69]
	v_lshlrev_b32_e32 v32, 16, v68
	v_and_b32_e32 v33, 0xffff0000, v68
	v_lshlrev_b32_e32 v34, 16, v69
	v_and_b32_e32 v35, 0xffff0000, v69
	v_lshlrev_b32_e32 v36, 16, v70
	v_and_b32_e32 v37, 0xffff0000, v70
	v_lshlrev_b32_e32 v38, 16, v71
	v_and_b32_e32 v39, 0xffff0000, v71
	v_fmac_f32_e32 v32, v56, v40
	v_fmac_f32_e32 v33, v56, v41
	v_fmac_f32_e32 v34, v56, v42
	v_fmac_f32_e32 v35, v56, v43
	v_fmac_f32_e32 v36, v56, v44
	v_fmac_f32_e32 v37, v56, v45
	v_fmac_f32_e32 v38, v56, v46
	v_fmac_f32_e32 v39, v56, v47
	global_load_dwordx4 v[68:71], v3, s[0:1]
	s_waitcnt vmcnt(17)
; DI unsigned cvtpk(float lo, float hi) { unsigned r; asm volatile("v_cvt_pk_bf16_f32 %0, %1, %2" : "=v"(r) : "v"(lo), "v"(hi)); return r; }
; DI void phase_ret_scan() {
;     ...
;     for (int k = 0; k < 16; ++k) {
;       const int sc = dir ? (15 - k) : k;
;       u16* pp = base + (size_t)sc * 393216;
;       const u32x4 uu = *(const u32x4*)pp;
;       u32x4 w = {cvtpk(S[0], S[1]), cvtpk(S[2], S[3]), cvtpk(S[4], S[5]), cvtpk(S[6], S[7])};
;       *(u32x4*)pp = w;
; #pragma unroll
;       for (int j = 0; j < 4; ++j) {
;         S[2 * j] = S[2 * j] * dk + __uint_as_float(uu[j] << 16);
;         S[2 * j + 1] = S[2 * j + 1] * dk + __uint_as_float(uu[j] & 0xffff0000u);
;       }
;     }
	v_cvt_pk_bf16_f32 v48, v32, v33
	v_cvt_pk_bf16_f32 v49, v34, v35
	v_cvt_pk_bf16_f32 v50, v36, v37
	v_cvt_pk_bf16_f32 v51, v38, v39
	global_store_dwordx4 v5, v[48:51], s[68:69]
	v_lshlrev_b32_e32 v40, 16, v72
	v_and_b32_e32 v41, 0xffff0000, v72
	v_lshlrev_b32_e32 v42, 16, v73
	v_and_b32_e32 v43, 0xffff0000, v73
	v_lshlrev_b32_e32 v44, 16, v74
	v_and_b32_e32 v45, 0xffff0000, v74
	v_lshlrev_b32_e32 v46, 16, v75
	v_and_b32_e32 v47, 0xffff0000, v75
	v_fmac_f32_e32 v40, v56, v32
	v_fmac_f32_e32 v41, v56, v33
	v_fmac_f32_e32 v42, v56, v34
	v_fmac_f32_e32 v43, v56, v35
	v_fmac_f32_e32 v44, v56, v36
	v_fmac_f32_e32 v45, v56, v37
	v_fmac_f32_e32 v46, v56, v38
	v_fmac_f32_e32 v47, v56, v39
	global_load_dwordx4 v[72:75], v5, s[0:1]
	s_waitcnt vmcnt(18)
	v_cvt_pk_bf16_f32 v52, v40, v41
	v_cvt_pk_bf16_f32 v53, v42, v43
	v_cvt_pk_bf16_f32 v54, v44, v45
	v_cvt_pk_bf16_f32 v55, v46, v47
	global_store_dwordx4 v7, v[52:55], s[68:69]
	v_lshlrev_b32_e32 v32, 16, v76
	v_and_b32_e32 v33, 0xffff0000, v76
	v_lshlrev_b32_e32 v34, 16, v77
	v_and_b32_e32 v35, 0xffff0000, v77
	v_lshlrev_b32_e32 v36, 16, v78
	v_and_b32_e32 v37, 0xffff0000, v78
	v_lshlrev_b32_e32 v38, 16, v79
	v_and_b32_e32 v39, 0xffff0000, v79
	v_fmac_f32_e32 v32, v56, v40
	v_fmac_f32_e32 v33, v56, v41
	v_fmac_f32_e32 v34, v56, v42
	v_fmac_f32_e32 v35, v56, v43
	v_fmac_f32_e32 v36, v56, v44
	v_fmac_f32_e32 v37, v56, v45
	v_fmac_f32_e32 v38, v56, v46
	v_fmac_f32_e32 v39, v56, v47
	global_load_dwordx4 v[76:79], v7, s[0:1]
	s_waitcnt vmcnt(19)
	v_cvt_pk_bf16_f32 v48, v32, v33
	v_cvt_pk_bf16_f32 v49, v34, v35
	v_cvt_pk_bf16_f32 v50, v36, v37
	v_cvt_pk_bf16_f32 v51, v38, v39
	global_store_dwordx4 v9, v[48:51], s[68:69]
	v_lshlrev_b32_e32 v40, 16, v80
	v_and_b32_e32 v41, 0xffff0000, v80
	v_lshlrev_b32_e32 v42, 16, v81
	v_and_b32_e32 v43, 0xffff0000, v81
	v_lshlrev_b32_e32 v44, 16, v82
	v_and_b32_e32 v45, 0xffff0000, v82
	v_lshlrev_b32_e32 v46, 16, v83
	v_and_b32_e32 v47, 0xffff0000, v83
	v_fmac_f32_e32 v40, v56, v32
	v_fmac_f32_e32 v41, v56, v33
	v_fmac_f32_e32 v42, v56, v34
	v_fmac_f32_e32 v43, v56, v35
	v_fmac_f32_e32 v44, v56, v36
	v_fmac_f32_e32 v45, v56, v37
	v_fmac_f32_e32 v46, v56, v38
	v_fmac_f32_e32 v47, v56, v39
	global_load_dwordx4 v[80:83], v9, s[0:1]
	s_waitcnt vmcnt(20)
	v_cvt_pk_bf16_f32 v52, v40, v41
	v_cvt_pk_bf16_f32 v53, v42, v43
	v_cvt_pk_bf16_f32 v54, v44, v45
	v_cvt_pk_bf16_f32 v55, v46, v47
	global_store_dwordx4 v11, v[52:55], s[68:69]
	v_lshlrev_b32_e32 v32, 16, v84
	v_and_b32_e32 v33, 0xffff0000, v84
	v_lshlrev_b32_e32 v34, 16, v85
	v_and_b32_e32 v35, 0xffff0000, v85
	v_lshlrev_b32_e32 v36, 16, v86
	v_and_b32_e32 v37, 0xffff0000, v86
	v_lshlrev_b32_e32 v38, 16, v87
	v_and_b32_e32 v39, 0xffff0000, v87
	v_fmac_f32_e32 v32, v56, v40
	v_fmac_f32_e32 v33, v56, v41
	v_fmac_f32_e32 v34, v56, v42
	v_fmac_f32_e32 v35, v56, v43
	v_fmac_f32_e32 v36, v56, v44
	v_fmac_f32_e32 v37, v56, v45
	v_fmac_f32_e32 v38, v56, v46
	v_fmac_f32_e32 v39, v56, v47
	global_load_dwordx4 v[84:87], v11, s[0:1]
	s_waitcnt vmcnt(21)
	v_cvt_pk_bf16_f32 v48, v32, v33
	v_cvt_pk_bf16_f32 v49, v34, v35
	v_cvt_pk_bf16_f32 v50, v36, v37
	v_cvt_pk_bf16_f32 v51, v38, v39
	global_store_dwordx4 v13, v[48:51], s[68:69]
	v_lshlrev_b32_e32 v40, 16, v88
	v_and_b32_e32 v41, 0xffff0000, v88
	v_lshlrev_b32_e32 v42, 16, v89
	v_and_b32_e32 v43, 0xffff0000, v89
	v_lshlrev_b32_e32 v44, 16, v90
	v_and_b32_e32 v45, 0xffff0000, v90
	v_lshlrev_b32_e32 v46, 16, v91
	v_and_b32_e32 v47, 0xffff0000, v91
	v_fmac_f32_e32 v40, v56, v32
	v_fmac_f32_e32 v41, v56, v33
	v_fmac_f32_e32 v42, v56, v34
	v_fmac_f32_e32 v43, v56, v35
	v_fmac_f32_e32 v44, v56, v36
	v_fmac_f32_e32 v45, v56, v37
	v_fmac_f32_e32 v46, v56, v38
	v_fmac_f32_e32 v47, v56, v39
	global_load_dwordx4 v[88:91], v13, s[0:1]
	s_waitcnt vmcnt(22)
	v_cvt_pk_bf16_f32 v52, v40, v41
	v_cvt_pk_bf16_f32 v53, v42, v43
	v_cvt_pk_bf16_f32 v54, v44, v45
	v_cvt_pk_bf16_f32 v55, v46, v47
	global_store_dwordx4 v15, v[52:55], s[68:69]
	v_lshlrev_b32_e32 v32, 16, v92
	v_and_b32_e32 v33, 0xffff0000, v92
	v_lshlrev_b32_e32 v34, 16, v93
	v_and_b32_e32 v35, 0xffff0000, v93
	v_lshlrev_b32_e32 v36, 16, v94
	v_and_b32_e32 v37, 0xffff0000, v94
	v_lshlrev_b32_e32 v38, 16, v95
	v_and_b32_e32 v39, 0xffff0000, v95
	v_fmac_f32_e32 v32, v56, v40
	v_fmac_f32_e32 v33, v56, v41
	v_fmac_f32_e32 v34, v56, v42
	v_fmac_f32_e32 v35, v56, v43
	v_fmac_f32_e32 v36, v56, v44
	v_fmac_f32_e32 v37, v56, v45
	v_fmac_f32_e32 v38, v56, v46
	v_fmac_f32_e32 v39, v56, v47
	global_load_dwordx4 v[92:95], v15, s[0:1]
	s_waitcnt vmcnt(23)
	v_cvt_pk_bf16_f32 v48, v32, v33
	v_cvt_pk_bf16_f32 v49, v34, v35
	v_cvt_pk_bf16_f32 v50, v36, v37
	v_cvt_pk_bf16_f32 v51, v38, v39
	global_store_dwordx4 v17, v[48:51], s[68:69]
	v_lshlrev_b32_e32 v40, 16, v96
	v_and_b32_e32 v41, 0xffff0000, v96
	v_lshlrev_b32_e32 v42, 16, v97
	v_and_b32_e32 v43, 0xffff0000, v97
	v_lshlrev_b32_e32 v44, 16, v98
	v_and_b32_e32 v45, 0xffff0000, v98
	v_lshlrev_b32_e32 v46, 16, v99
	v_and_b32_e32 v47, 0xffff0000, v99
	v_fmac_f32_e32 v40, v56, v32
	v_fmac_f32_e32 v41, v56, v33
	v_fmac_f32_e32 v42, v56, v34
	v_fmac_f32_e32 v43, v56, v35
	v_fmac_f32_e32 v44, v56, v36
	v_fmac_f32_e32 v45, v56, v37
	v_fmac_f32_e32 v46, v56, v38
	v_fmac_f32_e32 v47, v56, v39
	global_load_dwordx4 v[96:99], v17, s[0:1]
	s_waitcnt vmcnt(24)
; DI unsigned cvtpk(float lo, float hi) { unsigned r; asm volatile("v_cvt_pk_bf16_f32 %0, %1, %2" : "=v"(r) : "v"(lo), "v"(hi)); return r; }
; DI float ex2(float x) { return __builtin_amdgcn_exp2f(x); }
; DI void phase_ret_scan() {
;     ...
;   for (int i = bid * 512 + tid; i < 16 * 512 * 64; i += nb * 512) {
;     const int sh = i >> 15, e = (i >> 6) & 511, c = i & 63, dir = c >> 5, hh = sh & 3;
;     const float dk = ex2(dec[dir * 4 + hh] * 256.f);
;     u16* base = Bcat + ((size_t)(sh * 16) * 512 + e) * 768 + 256 + c * 8;
;     float S[8];
; #pragma unroll
;     for (int j = 0; j < 8; ++j) S[j] = 0.f;
; #pragma unroll
;     for (int k = 0; k < 16; ++k) {
;       const int sc = dir ? (15 - k) : k;
;       u16* pp = base + (size_t)sc * 393216;
;       const u32x4 uu = *(const u32x4*)pp;
;       u32x4 w = {cvtpk(S[0], S[1]), cvtpk(S[2], S[3]), cvtpk(S[4], S[5]), cvtpk(S[6], S[7])};
;       *(u32x4*)pp = w;
; #pragma unroll
;       for (int j = 0; j < 4; ++j) {
;         S[2 * j] = S[2 * j] * dk + __uint_as_float(uu[j] << 16);
;         S[2 * j + 1] = S[2 * j + 1] * dk + __uint_as_float(uu[j] & 0xffff0000u);
;       }
;     }
	v_cvt_pk_bf16_f32 v52, v40, v41
	v_cvt_pk_bf16_f32 v53, v42, v43
	v_cvt_pk_bf16_f32 v54, v44, v45
	v_cvt_pk_bf16_f32 v55, v46, v47
	global_store_dwordx4 v19, v[52:55], s[68:69]
	v_lshlrev_b32_e32 v32, 16, v100
	v_and_b32_e32 v33, 0xffff0000, v100
	v_lshlrev_b32_e32 v34, 16, v101
	v_and_b32_e32 v35, 0xffff0000, v101
	v_lshlrev_b32_e32 v36, 16, v102
	v_and_b32_e32 v37, 0xffff0000, v102
	v_lshlrev_b32_e32 v38, 16, v103
	v_and_b32_e32 v39, 0xffff0000, v103
	v_fmac_f32_e32 v32, v56, v40
	v_fmac_f32_e32 v33, v56, v41
	v_fmac_f32_e32 v34, v56, v42
	v_fmac_f32_e32 v35, v56, v43
	v_fmac_f32_e32 v36, v56, v44
	v_fmac_f32_e32 v37, v56, v45
	v_fmac_f32_e32 v38, v56, v46
	v_fmac_f32_e32 v39, v56, v47
	global_load_dwordx4 v[100:103], v19, s[0:1]
	s_waitcnt vmcnt(25)
	v_cvt_pk_bf16_f32 v48, v32, v33
	v_cvt_pk_bf16_f32 v49, v34, v35
	v_cvt_pk_bf16_f32 v50, v36, v37
	v_cvt_pk_bf16_f32 v51, v38, v39
	global_store_dwordx4 v21, v[48:51], s[68:69]
	v_lshlrev_b32_e32 v40, 16, v104
	v_and_b32_e32 v41, 0xffff0000, v104
	v_lshlrev_b32_e32 v42, 16, v105
	v_and_b32_e32 v43, 0xffff0000, v105
	v_lshlrev_b32_e32 v44, 16, v106
	v_and_b32_e32 v45, 0xffff0000, v106
	v_lshlrev_b32_e32 v46, 16, v107
	v_and_b32_e32 v47, 0xffff0000, v107
	v_fmac_f32_e32 v40, v56, v32
	v_fmac_f32_e32 v41, v56, v33
	v_fmac_f32_e32 v42, v56, v34
	v_fmac_f32_e32 v43, v56, v35
	v_fmac_f32_e32 v44, v56, v36
	v_fmac_f32_e32 v45, v56, v37
	v_fmac_f32_e32 v46, v56, v38
	v_fmac_f32_e32 v47, v56, v39
	global_load_dwordx4 v[104:107], v21, s[0:1]
	s_waitcnt vmcnt(26)
	v_cvt_pk_bf16_f32 v52, v40, v41
	v_cvt_pk_bf16_f32 v53, v42, v43
	v_cvt_pk_bf16_f32 v54, v44, v45
	v_cvt_pk_bf16_f32 v55, v46, v47
	global_store_dwordx4 v23, v[52:55], s[68:69]
	v_lshlrev_b32_e32 v32, 16, v108
	v_and_b32_e32 v33, 0xffff0000, v108
	v_lshlrev_b32_e32 v34, 16, v109
	v_and_b32_e32 v35, 0xffff0000, v109
	v_lshlrev_b32_e32 v36, 16, v110
	v_and_b32_e32 v37, 0xffff0000, v110
	v_lshlrev_b32_e32 v38, 16, v111
	v_and_b32_e32 v39, 0xffff0000, v111
	v_fmac_f32_e32 v32, v56, v40
	v_fmac_f32_e32 v33, v56, v41
	v_fmac_f32_e32 v34, v56, v42
	v_fmac_f32_e32 v35, v56, v43
	v_fmac_f32_e32 v36, v56, v44
	v_fmac_f32_e32 v37, v56, v45
	v_fmac_f32_e32 v38, v56, v46
	v_fmac_f32_e32 v39, v56, v47
	global_load_dwordx4 v[108:111], v23, s[0:1]
	s_waitcnt vmcnt(27)
	v_cvt_pk_bf16_f32 v48, v32, v33
	v_cvt_pk_bf16_f32 v49, v34, v35
	v_cvt_pk_bf16_f32 v50, v36, v37
	v_cvt_pk_bf16_f32 v51, v38, v39
	global_store_dwordx4 v25, v[48:51], s[68:69]
	v_lshlrev_b32_e32 v40, 16, v112
	v_and_b32_e32 v41, 0xffff0000, v112
	v_lshlrev_b32_e32 v42, 16, v113
	v_and_b32_e32 v43, 0xffff0000, v113
	v_lshlrev_b32_e32 v44, 16, v114
	v_and_b32_e32 v45, 0xffff0000, v114
	v_lshlrev_b32_e32 v46, 16, v115
	v_and_b32_e32 v47, 0xffff0000, v115
	v_fmac_f32_e32 v40, v56, v32
	v_fmac_f32_e32 v41, v56, v33
	v_fmac_f32_e32 v42, v56, v34
	v_fmac_f32_e32 v43, v56, v35
	v_fmac_f32_e32 v44, v56, v36
	v_fmac_f32_e32 v45, v56, v37
	v_fmac_f32_e32 v46, v56, v38
	v_fmac_f32_e32 v47, v56, v39
	global_load_dwordx4 v[112:115], v25, s[0:1]
	s_waitcnt vmcnt(28)
	v_cvt_pk_bf16_f32 v52, v40, v41
	v_cvt_pk_bf16_f32 v53, v42, v43
	v_cvt_pk_bf16_f32 v54, v44, v45
	v_cvt_pk_bf16_f32 v55, v46, v47
	global_store_dwordx4 v27, v[52:55], s[68:69]
	v_lshlrev_b32_e32 v32, 16, v116
	v_and_b32_e32 v33, 0xffff0000, v116
	v_lshlrev_b32_e32 v34, 16, v117
	v_and_b32_e32 v35, 0xffff0000, v117
	v_lshlrev_b32_e32 v36, 16, v118
	v_and_b32_e32 v37, 0xffff0000, v118
	v_lshlrev_b32_e32 v38, 16, v119
	v_and_b32_e32 v39, 0xffff0000, v119
	v_fmac_f32_e32 v32, v56, v40
	v_fmac_f32_e32 v33, v56, v41
	v_fmac_f32_e32 v34, v56, v42
	v_fmac_f32_e32 v35, v56, v43
	v_fmac_f32_e32 v36, v56, v44
	v_fmac_f32_e32 v37, v56, v45
	v_fmac_f32_e32 v38, v56, v46
	v_fmac_f32_e32 v39, v56, v47
	global_load_dwordx4 v[116:119], v27, s[0:1]
	s_waitcnt vmcnt(29)
	v_cvt_pk_bf16_f32 v48, v32, v33
	v_cvt_pk_bf16_f32 v49, v34, v35
	v_cvt_pk_bf16_f32 v50, v36, v37
	v_cvt_pk_bf16_f32 v51, v38, v39
	global_store_dwordx4 v29, v[48:51], s[68:69]
	v_lshlrev_b32_e32 v40, 16, v120
	v_and_b32_e32 v41, 0xffff0000, v120
	v_lshlrev_b32_e32 v42, 16, v121
	v_and_b32_e32 v43, 0xffff0000, v121
	v_lshlrev_b32_e32 v44, 16, v122
	v_and_b32_e32 v45, 0xffff0000, v122
	v_lshlrev_b32_e32 v46, 16, v123
	v_and_b32_e32 v47, 0xffff0000, v123
	v_fmac_f32_e32 v40, v56, v32
	v_fmac_f32_e32 v41, v56, v33
	v_fmac_f32_e32 v42, v56, v34
	v_fmac_f32_e32 v43, v56, v35
	v_fmac_f32_e32 v44, v56, v36
	v_fmac_f32_e32 v45, v56, v37
	v_fmac_f32_e32 v46, v56, v38
	v_fmac_f32_e32 v47, v56, v39
	global_load_dwordx4 v[120:123], v29, s[0:1]
	s_waitcnt vmcnt(30)
	v_cvt_pk_bf16_f32 v52, v40, v41
	v_cvt_pk_bf16_f32 v53, v42, v43
	v_cvt_pk_bf16_f32 v54, v44, v45
	v_cvt_pk_bf16_f32 v55, v46, v47
	global_store_dwordx4 v31, v[52:55], s[68:69]
	global_load_dwordx4 v[124:127], v31, s[0:1]
	s_mov_b32 s68, s0
	s_mov_b32 s69, s1
	s_add_u32 s0, s0, 0x3000000
	s_addc_u32 s1, s1, 0
	v_mov_b32_e32 v32, 0
	v_mov_b32_e32 v33, 0
	v_mov_b32_e32 v34, 0
	v_mov_b32_e32 v35, 0
	v_mov_b32_e32 v36, 0
	v_mov_b32_e32 v37, 0
	v_mov_b32_e32 v38, 0
	v_mov_b32_e32 v39, 0
	s_waitcnt vmcnt(30)
	v_cvt_pk_bf16_f32 v48, v32, v33
	v_cvt_pk_bf16_f32 v49, v34, v35
	v_cvt_pk_bf16_f32 v50, v36, v37
	v_cvt_pk_bf16_f32 v51, v38, v39
	global_store_dwordx4 v1, v[48:51], s[68:69]
	v_lshlrev_b32_e32 v40, 16, v64
	v_and_b32_e32 v41, 0xffff0000, v64
	v_lshlrev_b32_e32 v42, 16, v65
	v_and_b32_e32 v43, 0xffff0000, v65
	v_lshlrev_b32_e32 v44, 16, v66
	v_and_b32_e32 v45, 0xffff0000, v66
	v_lshlrev_b32_e32 v46, 16, v67
	v_and_b32_e32 v47, 0xffff0000, v67
	v_fmac_f32_e32 v40, v56, v32
	v_fmac_f32_e32 v41, v56, v33
	v_fmac_f32_e32 v42, v56, v34
	v_fmac_f32_e32 v43, v56, v35
	v_fmac_f32_e32 v44, v56, v36
	v_fmac_f32_e32 v45, v56, v37
	v_fmac_f32_e32 v46, v56, v38
	v_fmac_f32_e32 v47, v56, v39
	global_load_dwordx4 v[64:67], v1, s[0:1]
	s_waitcnt vmcnt(30)
; DI unsigned cvtpk(float lo, float hi) { unsigned r; asm volatile("v_cvt_pk_bf16_f32 %0, %1, %2" : "=v"(r) : "v"(lo), "v"(hi)); return r; }
; DI void phase_ret_scan() {
;     ...
;     for (int k = 0; k < 16; ++k) {
;       const int sc = dir ? (15 - k) : k;
;       u16* pp = base + (size_t)sc * 393216;
;       const u32x4 uu = *(const u32x4*)pp;
;       u32x4 w = {cvtpk(S[0], S[1]), cvtpk(S[2], S[3]), cvtpk(S[4], S[5]), cvtpk(S[6], S[7])};
;       *(u32x4*)pp = w;
; #pragma unroll
;       for (int j = 0; j < 4; ++j) {
;         S[2 * j] = S[2 * j] * dk + __uint_as_float(uu[j] << 16);
;         S[2 * j + 1] = S[2 * j + 1] * dk + __uint_as_float(uu[j] & 0xffff0000u);
;       }
;     }
	v_cvt_pk_bf16_f32 v52, v40, v41
	v_cvt_pk_bf16_f32 v53, v42, v43
	v_cvt_pk_bf16_f32 v54, v44, v45
	v_cvt_pk_bf16_f32 v55, v46, v47
	global_store_dwordx4 v3, v[52:55], s[68:69]
	v_lshlrev_b32_e32 v32, 16, v68
	v_and_b32_e32 v33, 0xffff0000, v68
	v_lshlrev_b32_e32 v34, 16, v69
	v_and_b32_e32 v35, 0xffff0000, v69
	v_lshlrev_b32_e32 v36, 16, v70
	v_and_b32_e32 v37, 0xffff0000, v70
	v_lshlrev_b32_e32 v38, 16, v71
	v_and_b32_e32 v39, 0xffff0000, v71
	v_fmac_f32_e32 v32, v56, v40
	v_fmac_f32_e32 v33, v56, v41
	v_fmac_f32_e32 v34, v56, v42
	v_fmac_f32_e32 v35, v56, v43
	v_fmac_f32_e32 v36, v56, v44
	v_fmac_f32_e32 v37, v56, v45
	v_fmac_f32_e32 v38, v56, v46
	v_fmac_f32_e32 v39, v56, v47
	global_load_dwordx4 v[68:71], v3, s[0:1]
	s_waitcnt vmcnt(30)
	v_cvt_pk_bf16_f32 v48, v32, v33
	v_cvt_pk_bf16_f32 v49, v34, v35
	v_cvt_pk_bf16_f32 v50, v36, v37
	v_cvt_pk_bf16_f32 v51, v38, v39
	global_store_dwordx4 v5, v[48:51], s[68:69]
	v_lshlrev_b32_e32 v40, 16, v72
	v_and_b32_e32 v41, 0xffff0000, v72
	v_lshlrev_b32_e32 v42, 16, v73
	v_and_b32_e32 v43, 0xffff0000, v73
	v_lshlrev_b32_e32 v44, 16, v74
	v_and_b32_e32 v45, 0xffff0000, v74
	v_lshlrev_b32_e32 v46, 16, v75
	v_and_b32_e32 v47, 0xffff0000, v75
	v_fmac_f32_e32 v40, v56, v32
	v_fmac_f32_e32 v41, v56, v33
	v_fmac_f32_e32 v42, v56, v34
	v_fmac_f32_e32 v43, v56, v35
	v_fmac_f32_e32 v44, v56, v36
	v_fmac_f32_e32 v45, v56, v37
	v_fmac_f32_e32 v46, v56, v38
	v_fmac_f32_e32 v47, v56, v39
	global_load_dwordx4 v[72:75], v5, s[0:1]
	s_waitcnt vmcnt(30)
	v_cvt_pk_bf16_f32 v52, v40, v41
	v_cvt_pk_bf16_f32 v53, v42, v43
	v_cvt_pk_bf16_f32 v54, v44, v45
	v_cvt_pk_bf16_f32 v55, v46, v47
	global_store_dwordx4 v7, v[52:55], s[68:69]
	v_lshlrev_b32_e32 v32, 16, v76
	v_and_b32_e32 v33, 0xffff0000, v76
	v_lshlrev_b32_e32 v34, 16, v77
	v_and_b32_e32 v35, 0xffff0000, v77
	v_lshlrev_b32_e32 v36, 16, v78
	v_and_b32_e32 v37, 0xffff0000, v78
	v_lshlrev_b32_e32 v38, 16, v79
	v_and_b32_e32 v39, 0xffff0000, v79
	v_fmac_f32_e32 v32, v56, v40
	v_fmac_f32_e32 v33, v56, v41
	v_fmac_f32_e32 v34, v56, v42
	v_fmac_f32_e32 v35, v56, v43
	v_fmac_f32_e32 v36, v56, v44
	v_fmac_f32_e32 v37, v56, v45
	v_fmac_f32_e32 v38, v56, v46
	v_fmac_f32_e32 v39, v56, v47
	global_load_dwordx4 v[76:79], v7, s[0:1]
	s_waitcnt vmcnt(30)
	v_cvt_pk_bf16_f32 v48, v32, v33
	v_cvt_pk_bf16_f32 v49, v34, v35
	v_cvt_pk_bf16_f32 v50, v36, v37
	v_cvt_pk_bf16_f32 v51, v38, v39
	global_store_dwordx4 v9, v[48:51], s[68:69]
	v_lshlrev_b32_e32 v40, 16, v80
	v_and_b32_e32 v41, 0xffff0000, v80
	v_lshlrev_b32_e32 v42, 16, v81
	v_and_b32_e32 v43, 0xffff0000, v81
	v_lshlrev_b32_e32 v44, 16, v82
	v_and_b32_e32 v45, 0xffff0000, v82
	v_lshlrev_b32_e32 v46, 16, v83
	v_and_b32_e32 v47, 0xffff0000, v83
	v_fmac_f32_e32 v40, v56, v32
	v_fmac_f32_e32 v41, v56, v33
	v_fmac_f32_e32 v42, v56, v34
	v_fmac_f32_e32 v43, v56, v35
	v_fmac_f32_e32 v44, v56, v36
	v_fmac_f32_e32 v45, v56, v37
	v_fmac_f32_e32 v46, v56, v38
	v_fmac_f32_e32 v47, v56, v39
	global_load_dwordx4 v[80:83], v9, s[0:1]
	s_waitcnt vmcnt(30)
	v_cvt_pk_bf16_f32 v52, v40, v41
	v_cvt_pk_bf16_f32 v53, v42, v43
	v_cvt_pk_bf16_f32 v54, v44, v45
	v_cvt_pk_bf16_f32 v55, v46, v47
	global_store_dwordx4 v11, v[52:55], s[68:69]
	v_lshlrev_b32_e32 v32, 16, v84
	v_and_b32_e32 v33, 0xffff0000, v84
	v_lshlrev_b32_e32 v34, 16, v85
	v_and_b32_e32 v35, 0xffff0000, v85
	v_lshlrev_b32_e32 v36, 16, v86
	v_and_b32_e32 v37, 0xffff0000, v86
	v_lshlrev_b32_e32 v38, 16, v87
	v_and_b32_e32 v39, 0xffff0000, v87
	v_fmac_f32_e32 v32, v56, v40
	v_fmac_f32_e32 v33, v56, v41
	v_fmac_f32_e32 v34, v56, v42
	v_fmac_f32_e32 v35, v56, v43
	v_fmac_f32_e32 v36, v56, v44
	v_fmac_f32_e32 v37, v56, v45
	v_fmac_f32_e32 v38, v56, v46
	v_fmac_f32_e32 v39, v56, v47
	global_load_dwordx4 v[84:87], v11, s[0:1]
	s_waitcnt vmcnt(30)
	v_cvt_pk_bf16_f32 v48, v32, v33
	v_cvt_pk_bf16_f32 v49, v34, v35
	v_cvt_pk_bf16_f32 v50, v36, v37
	v_cvt_pk_bf16_f32 v51, v38, v39
	global_store_dwordx4 v13, v[48:51], s[68:69]
	v_lshlrev_b32_e32 v40, 16, v88
	v_and_b32_e32 v41, 0xffff0000, v88
	v_lshlrev_b32_e32 v42, 16, v89
	v_and_b32_e32 v43, 0xffff0000, v89
	v_lshlrev_b32_e32 v44, 16, v90
	v_and_b32_e32 v45, 0xffff0000, v90
	v_lshlrev_b32_e32 v46, 16, v91
	v_and_b32_e32 v47, 0xffff0000, v91
	v_fmac_f32_e32 v40, v56, v32
	v_fmac_f32_e32 v41, v56, v33
	v_fmac_f32_e32 v42, v56, v34
	v_fmac_f32_e32 v43, v56, v35
	v_fmac_f32_e32 v44, v56, v36
	v_fmac_f32_e32 v45, v56, v37
	v_fmac_f32_e32 v46, v56, v38
	v_fmac_f32_e32 v47, v56, v39
	global_load_dwordx4 v[88:91], v13, s[0:1]
	s_waitcnt vmcnt(30)
	v_cvt_pk_bf16_f32 v52, v40, v41
	v_cvt_pk_bf16_f32 v53, v42, v43
	v_cvt_pk_bf16_f32 v54, v44, v45
	v_cvt_pk_bf16_f32 v55, v46, v47
	global_store_dwordx4 v15, v[52:55], s[68:69]
	v_lshlrev_b32_e32 v32, 16, v92
	v_and_b32_e32 v33, 0xffff0000, v92
	v_lshlrev_b32_e32 v34, 16, v93
	v_and_b32_e32 v35, 0xffff0000, v93
	v_lshlrev_b32_e32 v36, 16, v94
	v_and_b32_e32 v37, 0xffff0000, v94
	v_lshlrev_b32_e32 v38, 16, v95
	v_and_b32_e32 v39, 0xffff0000, v95
	v_fmac_f32_e32 v32, v56, v40
	v_fmac_f32_e32 v33, v56, v41
	v_fmac_f32_e32 v34, v56, v42
	v_fmac_f32_e32 v35, v56, v43
	v_fmac_f32_e32 v36, v56, v44
	v_fmac_f32_e32 v37, v56, v45
	v_fmac_f32_e32 v38, v56, v46
	v_fmac_f32_e32 v39, v56, v47
	global_load_dwordx4 v[92:95], v15, s[0:1]
	s_waitcnt vmcnt(30)
; DI unsigned cvtpk(float lo, float hi) { unsigned r; asm volatile("v_cvt_pk_bf16_f32 %0, %1, %2" : "=v"(r) : "v"(lo), "v"(hi)); return r; }
; DI float ex2(float x) { return __builtin_amdgcn_exp2f(x); }
; DI void phase_ret_scan() {
;     ...
;   for (int i = bid * 512 + tid; i < 16 * 512 * 64; i += nb * 512) {
;     const int sh = i >> 15, e = (i >> 6) & 511, c = i & 63, dir = c >> 5, hh = sh & 3;
;     const float dk = ex2(dec[dir * 4 + hh] * 256.f);
;     u16* base = Bcat + ((size_t)(sh * 16) * 512 + e) * 768 + 256 + c * 8;
;     float S[8];
; #pragma unroll
;     for (int j = 0; j < 8; ++j) S[j] = 0.f;
; #pragma unroll
;     for (int k = 0; k < 16; ++k) {
;       const int sc = dir ? (15 - k) : k;
;       u16* pp = base + (size_t)sc * 393216;
;       const u32x4 uu = *(const u32x4*)pp;
;       u32x4 w = {cvtpk(S[0], S[1]), cvtpk(S[2], S[3]), cvtpk(S[4], S[5]), cvtpk(S[6], S[7])};
;       *(u32x4*)pp = w;
; #pragma unroll
;       for (int j = 0; j < 4; ++j) {
;         S[2 * j] = S[2 * j] * dk + __uint_as_float(uu[j] << 16);
;         S[2 * j + 1] = S[2 * j + 1] * dk + __uint_as_float(uu[j] & 0xffff0000u);
;       }
;     }
	v_cvt_pk_bf16_f32 v48, v32, v33
	v_cvt_pk_bf16_f32 v49, v34, v35
	v_cvt_pk_bf16_f32 v50, v36, v37
	v_cvt_pk_bf16_f32 v51, v38, v39
	global_store_dwordx4 v17, v[48:51], s[68:69]
	v_lshlrev_b32_e32 v40, 16, v96
	v_and_b32_e32 v41, 0xffff0000, v96
	v_lshlrev_b32_e32 v42, 16, v97
	v_and_b32_e32 v43, 0xffff0000, v97
	v_lshlrev_b32_e32 v44, 16, v98
	v_and_b32_e32 v45, 0xffff0000, v98
	v_lshlrev_b32_e32 v46, 16, v99
	v_and_b32_e32 v47, 0xffff0000, v99
	v_fmac_f32_e32 v40, v56, v32
	v_fmac_f32_e32 v41, v56, v33
	v_fmac_f32_e32 v42, v56, v34
	v_fmac_f32_e32 v43, v56, v35
	v_fmac_f32_e32 v44, v56, v36
	v_fmac_f32_e32 v45, v56, v37
	v_fmac_f32_e32 v46, v56, v38
	v_fmac_f32_e32 v47, v56, v39
	global_load_dwordx4 v[96:99], v17, s[0:1]
	s_waitcnt vmcnt(30)
	v_cvt_pk_bf16_f32 v52, v40, v41
	v_cvt_pk_bf16_f32 v53, v42, v43
	v_cvt_pk_bf16_f32 v54, v44, v45
	v_cvt_pk_bf16_f32 v55, v46, v47
	global_store_dwordx4 v19, v[52:55], s[68:69]
	v_lshlrev_b32_e32 v32, 16, v100
	v_and_b32_e32 v33, 0xffff0000, v100
	v_lshlrev_b32_e32 v34, 16, v101
	v_and_b32_e32 v35, 0xffff0000, v101
	v_lshlrev_b32_e32 v36, 16, v102
	v_and_b32_e32 v37, 0xffff0000, v102
	v_lshlrev_b32_e32 v38, 16, v103
	v_and_b32_e32 v39, 0xffff0000, v103
	v_fmac_f32_e32 v32, v56, v40
	v_fmac_f32_e32 v33, v56, v41
	v_fmac_f32_e32 v34, v56, v42
	v_fmac_f32_e32 v35, v56, v43
	v_fmac_f32_e32 v36, v56, v44
	v_fmac_f32_e32 v37, v56, v45
	v_fmac_f32_e32 v38, v56, v46
	v_fmac_f32_e32 v39, v56, v47
	global_load_dwordx4 v[100:103], v19, s[0:1]
	s_waitcnt vmcnt(30)
	v_cvt_pk_bf16_f32 v48, v32, v33
	v_cvt_pk_bf16_f32 v49, v34, v35
	v_cvt_pk_bf16_f32 v50, v36, v37
	v_cvt_pk_bf16_f32 v51, v38, v39
	global_store_dwordx4 v21, v[48:51], s[68:69]
	v_lshlrev_b32_e32 v40, 16, v104
	v_and_b32_e32 v41, 0xffff0000, v104
	v_lshlrev_b32_e32 v42, 16, v105
	v_and_b32_e32 v43, 0xffff0000, v105
	v_lshlrev_b32_e32 v44, 16, v106
	v_and_b32_e32 v45, 0xffff0000, v106
	v_lshlrev_b32_e32 v46, 16, v107
	v_and_b32_e32 v47, 0xffff0000, v107
	v_fmac_f32_e32 v40, v56, v32
	v_fmac_f32_e32 v41, v56, v33
	v_fmac_f32_e32 v42, v56, v34
	v_fmac_f32_e32 v43, v56, v35
	v_fmac_f32_e32 v44, v56, v36
	v_fmac_f32_e32 v45, v56, v37
	v_fmac_f32_e32 v46, v56, v38
	v_fmac_f32_e32 v47, v56, v39
	global_load_dwordx4 v[104:107], v21, s[0:1]
	s_waitcnt vmcnt(30)
	v_cvt_pk_bf16_f32 v52, v40, v41
	v_cvt_pk_bf16_f32 v53, v42, v43
	v_cvt_pk_bf16_f32 v54, v44, v45
	v_cvt_pk_bf16_f32 v55, v46, v47
	global_store_dwordx4 v23, v[52:55], s[68:69]
	v_lshlrev_b32_e32 v32, 16, v108
	v_and_b32_e32 v33, 0xffff0000, v108
	v_lshlrev_b32_e32 v34, 16, v109
	v_and_b32_e32 v35, 0xffff0000, v109
	v_lshlrev_b32_e32 v36, 16, v110
	v_and_b32_e32 v37, 0xffff0000, v110
	v_lshlrev_b32_e32 v38, 16, v111
	v_and_b32_e32 v39, 0xffff0000, v111
	v_fmac_f32_e32 v32, v56, v40
	v_fmac_f32_e32 v33, v56, v41
	v_fmac_f32_e32 v34, v56, v42
	v_fmac_f32_e32 v35, v56, v43
	v_fmac_f32_e32 v36, v56, v44
	v_fmac_f32_e32 v37, v56, v45
	v_fmac_f32_e32 v38, v56, v46
	v_fmac_f32_e32 v39, v56, v47
	global_load_dwordx4 v[108:111], v23, s[0:1]
	s_waitcnt vmcnt(30)
	v_cvt_pk_bf16_f32 v48, v32, v33
	v_cvt_pk_bf16_f32 v49, v34, v35
	v_cvt_pk_bf16_f32 v50, v36, v37
	v_cvt_pk_bf16_f32 v51, v38, v39
	global_store_dwordx4 v25, v[48:51], s[68:69]
	v_lshlrev_b32_e32 v40, 16, v112
	v_and_b32_e32 v41, 0xffff0000, v112
	v_lshlrev_b32_e32 v42, 16, v113
	v_and_b32_e32 v43, 0xffff0000, v113
	v_lshlrev_b32_e32 v44, 16, v114
	v_and_b32_e32 v45, 0xffff0000, v114
	v_lshlrev_b32_e32 v46, 16, v115
	v_and_b32_e32 v47, 0xffff0000, v115
	v_fmac_f32_e32 v40, v56, v32
	v_fmac_f32_e32 v41, v56, v33
	v_fmac_f32_e32 v42, v56, v34
	v_fmac_f32_e32 v43, v56, v35
	v_fmac_f32_e32 v44, v56, v36
	v_fmac_f32_e32 v45, v56, v37
	v_fmac_f32_e32 v46, v56, v38
	v_fmac_f32_e32 v47, v56, v39
	global_load_dwordx4 v[112:115], v25, s[0:1]
	s_waitcnt vmcnt(30)
	v_cvt_pk_bf16_f32 v52, v40, v41
	v_cvt_pk_bf16_f32 v53, v42, v43
	v_cvt_pk_bf16_f32 v54, v44, v45
	v_cvt_pk_bf16_f32 v55, v46, v47
	global_store_dwordx4 v27, v[52:55], s[68:69]
	v_lshlrev_b32_e32 v32, 16, v116
	v_and_b32_e32 v33, 0xffff0000, v116
	v_lshlrev_b32_e32 v34, 16, v117
	v_and_b32_e32 v35, 0xffff0000, v117
	v_lshlrev_b32_e32 v36, 16, v118
	v_and_b32_e32 v37, 0xffff0000, v118
	v_lshlrev_b32_e32 v38, 16, v119
	v_and_b32_e32 v39, 0xffff0000, v119
	v_fmac_f32_e32 v32, v56, v40
	v_fmac_f32_e32 v33, v56, v41
	v_fmac_f32_e32 v34, v56, v42
	v_fmac_f32_e32 v35, v56, v43
	v_fmac_f32_e32 v36, v56, v44
	v_fmac_f32_e32 v37, v56, v45
	v_fmac_f32_e32 v38, v56, v46
	v_fmac_f32_e32 v39, v56, v47
	global_load_dwordx4 v[116:119], v27, s[0:1]
	s_waitcnt vmcnt(30)
	v_cvt_pk_bf16_f32 v48, v32, v33
	v_cvt_pk_bf16_f32 v49, v34, v35
	v_cvt_pk_bf16_f32 v50, v36, v37
	v_cvt_pk_bf16_f32 v51, v38, v39
	global_store_dwordx4 v29, v[48:51], s[68:69]
	v_lshlrev_b32_e32 v40, 16, v120
	v_and_b32_e32 v41, 0xffff0000, v120
	v_lshlrev_b32_e32 v42, 16, v121
	v_and_b32_e32 v43, 0xffff0000, v121
	v_lshlrev_b32_e32 v44, 16, v122
	v_and_b32_e32 v45, 0xffff0000, v122
	v_lshlrev_b32_e32 v46, 16, v123
	v_and_b32_e32 v47, 0xffff0000, v123
	v_fmac_f32_e32 v40, v56, v32
	v_fmac_f32_e32 v41, v56, v33
	v_fmac_f32_e32 v42, v56, v34
	v_fmac_f32_e32 v43, v56, v35
	v_fmac_f32_e32 v44, v56, v36
	v_fmac_f32_e32 v45, v56, v37
	v_fmac_f32_e32 v46, v56, v38
	v_fmac_f32_e32 v47, v56, v39
	global_load_dwordx4 v[120:123], v29, s[0:1]
	s_waitcnt vmcnt(30)
	v_cvt_pk_bf16_f32 v52, v40, v41
	v_cvt_pk_bf16_f32 v53, v42, v43
	v_cvt_pk_bf16_f32 v54, v44, v45
	v_cvt_pk_bf16_f32 v55, v46, v47
	global_store_dwordx4 v31, v[52:55], s[68:69]
	global_load_dwordx4 v[124:127], v31, s[0:1]
	s_mov_b32 s68, s0
	s_mov_b32 s69, s1
	s_add_u32 s0, s0, 0x3000000
	s_addc_u32 s1, s1, 0
	v_mov_b32_e32 v32, 0
	v_mov_b32_e32 v33, 0
	v_mov_b32_e32 v34, 0
	v_mov_b32_e32 v35, 0
	v_mov_b32_e32 v36, 0
	v_mov_b32_e32 v37, 0
	v_mov_b32_e32 v38, 0
	v_mov_b32_e32 v39, 0
	s_waitcnt vmcnt(30)
; DI unsigned cvtpk(float lo, float hi) { unsigned r; asm volatile("v_cvt_pk_bf16_f32 %0, %1, %2" : "=v"(r) : "v"(lo), "v"(hi)); return r; }
; DI void phase_ret_scan() {
;     ...
;     for (int k = 0; k < 16; ++k) {
;       const int sc = dir ? (15 - k) : k;
;       u16* pp = base + (size_t)sc * 393216;
;       const u32x4 uu = *(const u32x4*)pp;
;       u32x4 w = {cvtpk(S[0], S[1]), cvtpk(S[2], S[3]), cvtpk(S[4], S[5]), cvtpk(S[6], S[7])};
;       *(u32x4*)pp = w;
; #pragma unroll
;       for (int j = 0; j < 4; ++j) {
;         S[2 * j] = S[2 * j] * dk + __uint_as_float(uu[j] << 16);
;         S[2 * j + 1] = S[2 * j + 1] * dk + __uint_as_float(uu[j] & 0xffff0000u);
;       }
;     }
	v_cvt_pk_bf16_f32 v48, v32, v33
	v_cvt_pk_bf16_f32 v49, v34, v35
	v_cvt_pk_bf16_f32 v50, v36, v37
	v_cvt_pk_bf16_f32 v51, v38, v39
	global_store_dwordx4 v1, v[48:51], s[68:69]
	v_lshlrev_b32_e32 v40, 16, v64
	v_and_b32_e32 v41, 0xffff0000, v64
	v_lshlrev_b32_e32 v42, 16, v65
	v_and_b32_e32 v43, 0xffff0000, v65
	v_lshlrev_b32_e32 v44, 16, v66
	v_and_b32_e32 v45, 0xffff0000, v66
	v_lshlrev_b32_e32 v46, 16, v67
	v_and_b32_e32 v47, 0xffff0000, v67
	v_fmac_f32_e32 v40, v56, v32
	v_fmac_f32_e32 v41, v56, v33
	v_fmac_f32_e32 v42, v56, v34
	v_fmac_f32_e32 v43, v56, v35
	v_fmac_f32_e32 v44, v56, v36
	v_fmac_f32_e32 v45, v56, v37
	v_fmac_f32_e32 v46, v56, v38
	v_fmac_f32_e32 v47, v56, v39
	global_load_dwordx4 v[64:67], v1, s[0:1]
	s_waitcnt vmcnt(30)
	v_cvt_pk_bf16_f32 v52, v40, v41
	v_cvt_pk_bf16_f32 v53, v42, v43
	v_cvt_pk_bf16_f32 v54, v44, v45
	v_cvt_pk_bf16_f32 v55, v46, v47
	global_store_dwordx4 v3, v[52:55], s[68:69]
	v_lshlrev_b32_e32 v32, 16, v68
	v_and_b32_e32 v33, 0xffff0000, v68
	v_lshlrev_b32_e32 v34, 16, v69
	v_and_b32_e32 v35, 0xffff0000, v69
	v_lshlrev_b32_e32 v36, 16, v70
	v_and_b32_e32 v37, 0xffff0000, v70
	v_lshlrev_b32_e32 v38, 16, v71
	v_and_b32_e32 v39, 0xffff0000, v71
	v_fmac_f32_e32 v32, v56, v40
	v_fmac_f32_e32 v33, v56, v41
	v_fmac_f32_e32 v34, v56, v42
	v_fmac_f32_e32 v35, v56, v43
	v_fmac_f32_e32 v36, v56, v44
	v_fmac_f32_e32 v37, v56, v45
	v_fmac_f32_e32 v38, v56, v46
	v_fmac_f32_e32 v39, v56, v47
	global_load_dwordx4 v[68:71], v3, s[0:1]
	s_waitcnt vmcnt(30)
	v_cvt_pk_bf16_f32 v48, v32, v33
	v_cvt_pk_bf16_f32 v49, v34, v35
	v_cvt_pk_bf16_f32 v50, v36, v37
	v_cvt_pk_bf16_f32 v51, v38, v39
	global_store_dwordx4 v5, v[48:51], s[68:69]
	v_lshlrev_b32_e32 v40, 16, v72
	v_and_b32_e32 v41, 0xffff0000, v72
	v_lshlrev_b32_e32 v42, 16, v73
	v_and_b32_e32 v43, 0xffff0000, v73
	v_lshlrev_b32_e32 v44, 16, v74
	v_and_b32_e32 v45, 0xffff0000, v74
	v_lshlrev_b32_e32 v46, 16, v75
	v_and_b32_e32 v47, 0xffff0000, v75
	v_fmac_f32_e32 v40, v56, v32
	v_fmac_f32_e32 v41, v56, v33
	v_fmac_f32_e32 v42, v56, v34
	v_fmac_f32_e32 v43, v56, v35
	v_fmac_f32_e32 v44, v56, v36
	v_fmac_f32_e32 v45, v56, v37
	v_fmac_f32_e32 v46, v56, v38
	v_fmac_f32_e32 v47, v56, v39
	global_load_dwordx4 v[72:75], v5, s[0:1]
	s_waitcnt vmcnt(30)
	v_cvt_pk_bf16_f32 v52, v40, v41
	v_cvt_pk_bf16_f32 v53, v42, v43
	v_cvt_pk_bf16_f32 v54, v44, v45
	v_cvt_pk_bf16_f32 v55, v46, v47
	global_store_dwordx4 v7, v[52:55], s[68:69]
	v_lshlrev_b32_e32 v32, 16, v76
	v_and_b32_e32 v33, 0xffff0000, v76
	v_lshlrev_b32_e32 v34, 16, v77
	v_and_b32_e32 v35, 0xffff0000, v77
	v_lshlrev_b32_e32 v36, 16, v78
	v_and_b32_e32 v37, 0xffff0000, v78
	v_lshlrev_b32_e32 v38, 16, v79
	v_and_b32_e32 v39, 0xffff0000, v79
	v_fmac_f32_e32 v32, v56, v40
	v_fmac_f32_e32 v33, v56, v41
	v_fmac_f32_e32 v34, v56, v42
	v_fmac_f32_e32 v35, v56, v43
	v_fmac_f32_e32 v36, v56, v44
	v_fmac_f32_e32 v37, v56, v45
	v_fmac_f32_e32 v38, v56, v46
	v_fmac_f32_e32 v39, v56, v47
	global_load_dwordx4 v[76:79], v7, s[0:1]
	s_waitcnt vmcnt(30)
	v_cvt_pk_bf16_f32 v48, v32, v33
	v_cvt_pk_bf16_f32 v49, v34, v35
	v_cvt_pk_bf16_f32 v50, v36, v37
	v_cvt_pk_bf16_f32 v51, v38, v39
	global_store_dwordx4 v9, v[48:51], s[68:69]
	v_lshlrev_b32_e32 v40, 16, v80
	v_and_b32_e32 v41, 0xffff0000, v80
	v_lshlrev_b32_e32 v42, 16, v81
	v_and_b32_e32 v43, 0xffff0000, v81
	v_lshlrev_b32_e32 v44, 16, v82
	v_and_b32_e32 v45, 0xffff0000, v82
	v_lshlrev_b32_e32 v46, 16, v83
	v_and_b32_e32 v47, 0xffff0000, v83
	v_fmac_f32_e32 v40, v56, v32
	v_fmac_f32_e32 v41, v56, v33
	v_fmac_f32_e32 v42, v56, v34
	v_fmac_f32_e32 v43, v56, v35
	v_fmac_f32_e32 v44, v56, v36
	v_fmac_f32_e32 v45, v56, v37
	v_fmac_f32_e32 v46, v56, v38
	v_fmac_f32_e32 v47, v56, v39
	global_load_dwordx4 v[80:83], v9, s[0:1]
	s_waitcnt vmcnt(30)
	v_cvt_pk_bf16_f32 v52, v40, v41
	v_cvt_pk_bf16_f32 v53, v42, v43
	v_cvt_pk_bf16_f32 v54, v44, v45
	v_cvt_pk_bf16_f32 v55, v46, v47
	global_store_dwordx4 v11, v[52:55], s[68:69]
	v_lshlrev_b32_e32 v32, 16, v84
	v_and_b32_e32 v33, 0xffff0000, v84
	v_lshlrev_b32_e32 v34, 16, v85
	v_and_b32_e32 v35, 0xffff0000, v85
	v_lshlrev_b32_e32 v36, 16, v86
	v_and_b32_e32 v37, 0xffff0000, v86
	v_lshlrev_b32_e32 v38, 16, v87
	v_and_b32_e32 v39, 0xffff0000, v87
	v_fmac_f32_e32 v32, v56, v40
	v_fmac_f32_e32 v33, v56, v41
	v_fmac_f32_e32 v34, v56, v42
	v_fmac_f32_e32 v35, v56, v43
	v_fmac_f32_e32 v36, v56, v44
	v_fmac_f32_e32 v37, v56, v45
	v_fmac_f32_e32 v38, v56, v46
	v_fmac_f32_e32 v39, v56, v47
	global_load_dwordx4 v[84:87], v11, s[0:1]
	s_waitcnt vmcnt(30)
	v_cvt_pk_bf16_f32 v48, v32, v33
	v_cvt_pk_bf16_f32 v49, v34, v35
	v_cvt_pk_bf16_f32 v50, v36, v37
	v_cvt_pk_bf16_f32 v51, v38, v39
	global_store_dwordx4 v13, v[48:51], s[68:69]
	v_lshlrev_b32_e32 v40, 16, v88
	v_and_b32_e32 v41, 0xffff0000, v88
	v_lshlrev_b32_e32 v42, 16, v89
	v_and_b32_e32 v43, 0xffff0000, v89
	v_lshlrev_b32_e32 v44, 16, v90
	v_and_b32_e32 v45, 0xffff0000, v90
	v_lshlrev_b32_e32 v46, 16, v91
	v_and_b32_e32 v47, 0xffff0000, v91
	v_fmac_f32_e32 v40, v56, v32
	v_fmac_f32_e32 v41, v56, v33
	v_fmac_f32_e32 v42, v56, v34
	v_fmac_f32_e32 v43, v56, v35
	v_fmac_f32_e32 v44, v56, v36
	v_fmac_f32_e32 v45, v56, v37
	v_fmac_f32_e32 v46, v56, v38
	v_fmac_f32_e32 v47, v56, v39
	global_load_dwordx4 v[88:91], v13, s[0:1]
	s_waitcnt vmcnt(30)
; DI unsigned cvtpk(float lo, float hi) { unsigned r; asm volatile("v_cvt_pk_bf16_f32 %0, %1, %2" : "=v"(r) : "v"(lo), "v"(hi)); return r; }
; DI void phase_ret_scan() {
;     ...
;     for (int k = 0; k < 16; ++k) {
;       const int sc = dir ? (15 - k) : k;
;       u16* pp = base + (size_t)sc * 393216;
;       const u32x4 uu = *(const u32x4*)pp;
;       u32x4 w = {cvtpk(S[0], S[1]), cvtpk(S[2], S[3]), cvtpk(S[4], S[5]), cvtpk(S[6], S[7])};
;       *(u32x4*)pp = w;
; #pragma unroll
;       for (int j = 0; j < 4; ++j) {
;         S[2 * j] = S[2 * j] * dk + __uint_as_float(uu[j] << 16);
;         S[2 * j + 1] = S[2 * j + 1] * dk + __uint_as_float(uu[j] & 0xffff0000u);
;       }
;     }
	v_cvt_pk_bf16_f32 v52, v40, v41
	v_cvt_pk_bf16_f32 v53, v42, v43
	v_cvt_pk_bf16_f32 v54, v44, v45
	v_cvt_pk_bf16_f32 v55, v46, v47
	global_store_dwordx4 v15, v[52:55], s[68:69]
	v_lshlrev_b32_e32 v32, 16, v92
	v_and_b32_e32 v33, 0xffff0000, v92
	v_lshlrev_b32_e32 v34, 16, v93
	v_and_b32_e32 v35, 0xffff0000, v93
	v_lshlrev_b32_e32 v36, 16, v94
	v_and_b32_e32 v37, 0xffff0000, v94
	v_lshlrev_b32_e32 v38, 16, v95
	v_and_b32_e32 v39, 0xffff0000, v95
	v_fmac_f32_e32 v32, v56, v40
	v_fmac_f32_e32 v33, v56, v41
	v_fmac_f32_e32 v34, v56, v42
	v_fmac_f32_e32 v35, v56, v43
	v_fmac_f32_e32 v36, v56, v44
	v_fmac_f32_e32 v37, v56, v45
	v_fmac_f32_e32 v38, v56, v46
	v_fmac_f32_e32 v39, v56, v47
	global_load_dwordx4 v[92:95], v15, s[0:1]
	s_waitcnt vmcnt(30)
	v_cvt_pk_bf16_f32 v48, v32, v33
	v_cvt_pk_bf16_f32 v49, v34, v35
	v_cvt_pk_bf16_f32 v50, v36, v37
	v_cvt_pk_bf16_f32 v51, v38, v39
	global_store_dwordx4 v17, v[48:51], s[68:69]
	v_lshlrev_b32_e32 v40, 16, v96
	v_and_b32_e32 v41, 0xffff0000, v96
	v_lshlrev_b32_e32 v42, 16, v97
	v_and_b32_e32 v43, 0xffff0000, v97
	v_lshlrev_b32_e32 v44, 16, v98
	v_and_b32_e32 v45, 0xffff0000, v98
	v_lshlrev_b32_e32 v46, 16, v99
	v_and_b32_e32 v47, 0xffff0000, v99
	v_fmac_f32_e32 v40, v56, v32
	v_fmac_f32_e32 v41, v56, v33
	v_fmac_f32_e32 v42, v56, v34
	v_fmac_f32_e32 v43, v56, v35
	v_fmac_f32_e32 v44, v56, v36
	v_fmac_f32_e32 v45, v56, v37
	v_fmac_f32_e32 v46, v56, v38
	v_fmac_f32_e32 v47, v56, v39
	global_load_dwordx4 v[96:99], v17, s[0:1]
	s_waitcnt vmcnt(30)
	v_cvt_pk_bf16_f32 v52, v40, v41
	v_cvt_pk_bf16_f32 v53, v42, v43
	v_cvt_pk_bf16_f32 v54, v44, v45
	v_cvt_pk_bf16_f32 v55, v46, v47
	global_store_dwordx4 v19, v[52:55], s[68:69]
	v_lshlrev_b32_e32 v32, 16, v100
	v_and_b32_e32 v33, 0xffff0000, v100
	v_lshlrev_b32_e32 v34, 16, v101
	v_and_b32_e32 v35, 0xffff0000, v101
	v_lshlrev_b32_e32 v36, 16, v102
	v_and_b32_e32 v37, 0xffff0000, v102
	v_lshlrev_b32_e32 v38, 16, v103
	v_and_b32_e32 v39, 0xffff0000, v103
	v_fmac_f32_e32 v32, v56, v40
	v_fmac_f32_e32 v33, v56, v41
	v_fmac_f32_e32 v34, v56, v42
	v_fmac_f32_e32 v35, v56, v43
	v_fmac_f32_e32 v36, v56, v44
	v_fmac_f32_e32 v37, v56, v45
	v_fmac_f32_e32 v38, v56, v46
	v_fmac_f32_e32 v39, v56, v47
	global_load_dwordx4 v[100:103], v19, s[0:1]
	s_waitcnt vmcnt(30)
	v_cvt_pk_bf16_f32 v48, v32, v33
	v_cvt_pk_bf16_f32 v49, v34, v35
	v_cvt_pk_bf16_f32 v50, v36, v37
	v_cvt_pk_bf16_f32 v51, v38, v39
	global_store_dwordx4 v21, v[48:51], s[68:69]
	v_lshlrev_b32_e32 v40, 16, v104
	v_and_b32_e32 v41, 0xffff0000, v104
	v_lshlrev_b32_e32 v42, 16, v105
	v_and_b32_e32 v43, 0xffff0000, v105
	v_lshlrev_b32_e32 v44, 16, v106
	v_and_b32_e32 v45, 0xffff0000, v106
	v_lshlrev_b32_e32 v46, 16, v107
	v_and_b32_e32 v47, 0xffff0000, v107
	v_fmac_f32_e32 v40, v56, v32
	v_fmac_f32_e32 v41, v56, v33
	v_fmac_f32_e32 v42, v56, v34
	v_fmac_f32_e32 v43, v56, v35
	v_fmac_f32_e32 v44, v56, v36
	v_fmac_f32_e32 v45, v56, v37
	v_fmac_f32_e32 v46, v56, v38
	v_fmac_f32_e32 v47, v56, v39
	global_load_dwordx4 v[104:107], v21, s[0:1]
	s_waitcnt vmcnt(30)
	v_cvt_pk_bf16_f32 v52, v40, v41
	v_cvt_pk_bf16_f32 v53, v42, v43
	v_cvt_pk_bf16_f32 v54, v44, v45
	v_cvt_pk_bf16_f32 v55, v46, v47
	global_store_dwordx4 v23, v[52:55], s[68:69]
	v_lshlrev_b32_e32 v32, 16, v108
	v_and_b32_e32 v33, 0xffff0000, v108
	v_lshlrev_b32_e32 v34, 16, v109
	v_and_b32_e32 v35, 0xffff0000, v109
	v_lshlrev_b32_e32 v36, 16, v110
	v_and_b32_e32 v37, 0xffff0000, v110
	v_lshlrev_b32_e32 v38, 16, v111
	v_and_b32_e32 v39, 0xffff0000, v111
	v_fmac_f32_e32 v32, v56, v40
	v_fmac_f32_e32 v33, v56, v41
	v_fmac_f32_e32 v34, v56, v42
	v_fmac_f32_e32 v35, v56, v43
	v_fmac_f32_e32 v36, v56, v44
	v_fmac_f32_e32 v37, v56, v45
	v_fmac_f32_e32 v38, v56, v46
	v_fmac_f32_e32 v39, v56, v47
	global_load_dwordx4 v[108:111], v23, s[0:1]
	s_waitcnt vmcnt(30)
	v_cvt_pk_bf16_f32 v48, v32, v33
	v_cvt_pk_bf16_f32 v49, v34, v35
	v_cvt_pk_bf16_f32 v50, v36, v37
	v_cvt_pk_bf16_f32 v51, v38, v39
	global_store_dwordx4 v25, v[48:51], s[68:69]
	v_lshlrev_b32_e32 v40, 16, v112
	v_and_b32_e32 v41, 0xffff0000, v112
	v_lshlrev_b32_e32 v42, 16, v113
	v_and_b32_e32 v43, 0xffff0000, v113
	v_lshlrev_b32_e32 v44, 16, v114
	v_and_b32_e32 v45, 0xffff0000, v114
	v_lshlrev_b32_e32 v46, 16, v115
	v_and_b32_e32 v47, 0xffff0000, v115
	v_fmac_f32_e32 v40, v56, v32
	v_fmac_f32_e32 v41, v56, v33
	v_fmac_f32_e32 v42, v56, v34
	v_fmac_f32_e32 v43, v56, v35
	v_fmac_f32_e32 v44, v56, v36
	v_fmac_f32_e32 v45, v56, v37
	v_fmac_f32_e32 v46, v56, v38
	v_fmac_f32_e32 v47, v56, v39
	global_load_dwordx4 v[112:115], v25, s[0:1]
	s_waitcnt vmcnt(30)
	v_cvt_pk_bf16_f32 v52, v40, v41
	v_cvt_pk_bf16_f32 v53, v42, v43
	v_cvt_pk_bf16_f32 v54, v44, v45
	v_cvt_pk_bf16_f32 v55, v46, v47
	global_store_dwordx4 v27, v[52:55], s[68:69]
	v_lshlrev_b32_e32 v32, 16, v116
	v_and_b32_e32 v33, 0xffff0000, v116
	v_lshlrev_b32_e32 v34, 16, v117
	v_and_b32_e32 v35, 0xffff0000, v117
	v_lshlrev_b32_e32 v36, 16, v118
	v_and_b32_e32 v37, 0xffff0000, v118
	v_lshlrev_b32_e32 v38, 16, v119
	v_and_b32_e32 v39, 0xffff0000, v119
	v_fmac_f32_e32 v32, v56, v40
	v_fmac_f32_e32 v33, v56, v41
	v_fmac_f32_e32 v34, v56, v42
	v_fmac_f32_e32 v35, v56, v43
	v_fmac_f32_e32 v36, v56, v44
	v_fmac_f32_e32 v37, v56, v45
	v_fmac_f32_e32 v38, v56, v46
	v_fmac_f32_e32 v39, v56, v47
	global_load_dwordx4 v[116:119], v27, s[0:1]
	s_waitcnt vmcnt(30)
; DI unsigned cvtpk(float lo, float hi) { unsigned r; asm volatile("v_cvt_pk_bf16_f32 %0, %1, %2" : "=v"(r) : "v"(lo), "v"(hi)); return r; }
; DI float ex2(float x) { return __builtin_amdgcn_exp2f(x); }
; DI void phase_ret_scan() {
;     ...
;   for (int i = bid * 512 + tid; i < 16 * 512 * 64; i += nb * 512) {
;     const int sh = i >> 15, e = (i >> 6) & 511, c = i & 63, dir = c >> 5, hh = sh & 3;
;     const float dk = ex2(dec[dir * 4 + hh] * 256.f);
;     u16* base = Bcat + ((size_t)(sh * 16) * 512 + e) * 768 + 256 + c * 8;
;     float S[8];
; #pragma unroll
;     for (int j = 0; j < 8; ++j) S[j] = 0.f;
; #pragma unroll
;     for (int k = 0; k < 16; ++k) {
;       const int sc = dir ? (15 - k) : k;
;       u16* pp = base + (size_t)sc * 393216;
;       const u32x4 uu = *(const u32x4*)pp;
;       u32x4 w = {cvtpk(S[0], S[1]), cvtpk(S[2], S[3]), cvtpk(S[4], S[5]), cvtpk(S[6], S[7])};
;       *(u32x4*)pp = w;
; #pragma unroll
;       for (int j = 0; j < 4; ++j) {
;         S[2 * j] = S[2 * j] * dk + __uint_as_float(uu[j] << 16);
;         S[2 * j + 1] = S[2 * j + 1] * dk + __uint_as_float(uu[j] & 0xffff0000u);
;       }
;     }
	v_cvt_pk_bf16_f32 v48, v32, v33
	v_cvt_pk_bf16_f32 v49, v34, v35
	v_cvt_pk_bf16_f32 v50, v36, v37
	v_cvt_pk_bf16_f32 v51, v38, v39
	global_store_dwordx4 v29, v[48:51], s[68:69]
	v_lshlrev_b32_e32 v40, 16, v120
	v_and_b32_e32 v41, 0xffff0000, v120
	v_lshlrev_b32_e32 v42, 16, v121
	v_and_b32_e32 v43, 0xffff0000, v121
	v_lshlrev_b32_e32 v44, 16, v122
	v_and_b32_e32 v45, 0xffff0000, v122
	v_lshlrev_b32_e32 v46, 16, v123
	v_and_b32_e32 v47, 0xffff0000, v123
	v_fmac_f32_e32 v40, v56, v32
	v_fmac_f32_e32 v41, v56, v33
	v_fmac_f32_e32 v42, v56, v34
	v_fmac_f32_e32 v43, v56, v35
	v_fmac_f32_e32 v44, v56, v36
	v_fmac_f32_e32 v45, v56, v37
	v_fmac_f32_e32 v46, v56, v38
	v_fmac_f32_e32 v47, v56, v39
	global_load_dwordx4 v[120:123], v29, s[0:1]
	s_waitcnt vmcnt(30)
	v_cvt_pk_bf16_f32 v52, v40, v41
	v_cvt_pk_bf16_f32 v53, v42, v43
	v_cvt_pk_bf16_f32 v54, v44, v45
	v_cvt_pk_bf16_f32 v55, v46, v47
	global_store_dwordx4 v31, v[52:55], s[68:69]
	global_load_dwordx4 v[124:127], v31, s[0:1]
	s_mov_b32 s68, s0
	s_mov_b32 s69, s1
	s_add_u32 s0, s0, 0x3000000
	s_addc_u32 s1, s1, 0
	v_mov_b32_e32 v32, 0
	v_mov_b32_e32 v33, 0
	v_mov_b32_e32 v34, 0
	v_mov_b32_e32 v35, 0
	v_mov_b32_e32 v36, 0
	v_mov_b32_e32 v37, 0
	v_mov_b32_e32 v38, 0
	v_mov_b32_e32 v39, 0
	s_waitcnt vmcnt(30)
	v_cvt_pk_bf16_f32 v48, v32, v33
	v_cvt_pk_bf16_f32 v49, v34, v35
	v_cvt_pk_bf16_f32 v50, v36, v37
	v_cvt_pk_bf16_f32 v51, v38, v39
	global_store_dwordx4 v1, v[48:51], s[68:69]
	v_lshlrev_b32_e32 v40, 16, v64
	v_and_b32_e32 v41, 0xffff0000, v64
	v_lshlrev_b32_e32 v42, 16, v65
	v_and_b32_e32 v43, 0xffff0000, v65
	v_lshlrev_b32_e32 v44, 16, v66
	v_and_b32_e32 v45, 0xffff0000, v66
	v_lshlrev_b32_e32 v46, 16, v67
	v_and_b32_e32 v47, 0xffff0000, v67
	v_fmac_f32_e32 v40, v56, v32
	v_fmac_f32_e32 v41, v56, v33
	v_fmac_f32_e32 v42, v56, v34
	v_fmac_f32_e32 v43, v56, v35
	v_fmac_f32_e32 v44, v56, v36
	v_fmac_f32_e32 v45, v56, v37
	v_fmac_f32_e32 v46, v56, v38
	v_fmac_f32_e32 v47, v56, v39
	s_waitcnt vmcnt(29)
	v_cvt_pk_bf16_f32 v52, v40, v41
	v_cvt_pk_bf16_f32 v53, v42, v43
	v_cvt_pk_bf16_f32 v54, v44, v45
	v_cvt_pk_bf16_f32 v55, v46, v47
	global_store_dwordx4 v3, v[52:55], s[68:69]
	v_lshlrev_b32_e32 v32, 16, v68
	v_and_b32_e32 v33, 0xffff0000, v68
	v_lshlrev_b32_e32 v34, 16, v69
	v_and_b32_e32 v35, 0xffff0000, v69
	v_lshlrev_b32_e32 v36, 16, v70
	v_and_b32_e32 v37, 0xffff0000, v70
	v_lshlrev_b32_e32 v38, 16, v71
	v_and_b32_e32 v39, 0xffff0000, v71
	v_fmac_f32_e32 v32, v56, v40
	v_fmac_f32_e32 v33, v56, v41
	v_fmac_f32_e32 v34, v56, v42
	v_fmac_f32_e32 v35, v56, v43
	v_fmac_f32_e32 v36, v56, v44
	v_fmac_f32_e32 v37, v56, v45
	v_fmac_f32_e32 v38, v56, v46
	v_fmac_f32_e32 v39, v56, v47
	s_waitcnt vmcnt(28)
	v_cvt_pk_bf16_f32 v48, v32, v33
	v_cvt_pk_bf16_f32 v49, v34, v35
	v_cvt_pk_bf16_f32 v50, v36, v37
	v_cvt_pk_bf16_f32 v51, v38, v39
	global_store_dwordx4 v5, v[48:51], s[68:69]
	v_lshlrev_b32_e32 v40, 16, v72
	v_and_b32_e32 v41, 0xffff0000, v72
	v_lshlrev_b32_e32 v42, 16, v73
	v_and_b32_e32 v43, 0xffff0000, v73
	v_lshlrev_b32_e32 v44, 16, v74
	v_and_b32_e32 v45, 0xffff0000, v74
	v_lshlrev_b32_e32 v46, 16, v75
	v_and_b32_e32 v47, 0xffff0000, v75
	v_fmac_f32_e32 v40, v56, v32
	v_fmac_f32_e32 v41, v56, v33
	v_fmac_f32_e32 v42, v56, v34
	v_fmac_f32_e32 v43, v56, v35
	v_fmac_f32_e32 v44, v56, v36
	v_fmac_f32_e32 v45, v56, v37
	v_fmac_f32_e32 v46, v56, v38
	v_fmac_f32_e32 v47, v56, v39
	s_waitcnt vmcnt(27)
	v_cvt_pk_bf16_f32 v52, v40, v41
	v_cvt_pk_bf16_f32 v53, v42, v43
	v_cvt_pk_bf16_f32 v54, v44, v45
	v_cvt_pk_bf16_f32 v55, v46, v47
	global_store_dwordx4 v7, v[52:55], s[68:69]
	v_lshlrev_b32_e32 v32, 16, v76
	v_and_b32_e32 v33, 0xffff0000, v76
	v_lshlrev_b32_e32 v34, 16, v77
	v_and_b32_e32 v35, 0xffff0000, v77
	v_lshlrev_b32_e32 v36, 16, v78
	v_and_b32_e32 v37, 0xffff0000, v78
	v_lshlrev_b32_e32 v38, 16, v79
	v_and_b32_e32 v39, 0xffff0000, v79
	v_fmac_f32_e32 v32, v56, v40
	v_fmac_f32_e32 v33, v56, v41
	v_fmac_f32_e32 v34, v56, v42
	v_fmac_f32_e32 v35, v56, v43
	v_fmac_f32_e32 v36, v56, v44
	v_fmac_f32_e32 v37, v56, v45
	v_fmac_f32_e32 v38, v56, v46
	v_fmac_f32_e32 v39, v56, v47
	s_waitcnt vmcnt(26)
	v_cvt_pk_bf16_f32 v48, v32, v33
	v_cvt_pk_bf16_f32 v49, v34, v35
	v_cvt_pk_bf16_f32 v50, v36, v37
	v_cvt_pk_bf16_f32 v51, v38, v39
	global_store_dwordx4 v9, v[48:51], s[68:69]
	v_lshlrev_b32_e32 v40, 16, v80
	v_and_b32_e32 v41, 0xffff0000, v80
	v_lshlrev_b32_e32 v42, 16, v81
	v_and_b32_e32 v43, 0xffff0000, v81
	v_lshlrev_b32_e32 v44, 16, v82
	v_and_b32_e32 v45, 0xffff0000, v82
	v_lshlrev_b32_e32 v46, 16, v83
	v_and_b32_e32 v47, 0xffff0000, v83
	v_fmac_f32_e32 v40, v56, v32
	v_fmac_f32_e32 v41, v56, v33
	v_fmac_f32_e32 v42, v56, v34
	v_fmac_f32_e32 v43, v56, v35
	v_fmac_f32_e32 v44, v56, v36
	v_fmac_f32_e32 v45, v56, v37
	v_fmac_f32_e32 v46, v56, v38
	v_fmac_f32_e32 v47, v56, v39
	s_waitcnt vmcnt(25)
	v_cvt_pk_bf16_f32 v52, v40, v41
	v_cvt_pk_bf16_f32 v53, v42, v43
	v_cvt_pk_bf16_f32 v54, v44, v45
	v_cvt_pk_bf16_f32 v55, v46, v47
	global_store_dwordx4 v11, v[52:55], s[68:69]
	v_lshlrev_b32_e32 v32, 16, v84
	v_and_b32_e32 v33, 0xffff0000, v84
	v_lshlrev_b32_e32 v34, 16, v85
	v_and_b32_e32 v35, 0xffff0000, v85
	v_lshlrev_b32_e32 v36, 16, v86
	v_and_b32_e32 v37, 0xffff0000, v86
	v_lshlrev_b32_e32 v38, 16, v87
	v_and_b32_e32 v39, 0xffff0000, v87
	v_fmac_f32_e32 v32, v56, v40
	v_fmac_f32_e32 v33, v56, v41
	v_fmac_f32_e32 v34, v56, v42
	v_fmac_f32_e32 v35, v56, v43
	v_fmac_f32_e32 v36, v56, v44
	v_fmac_f32_e32 v37, v56, v45
	v_fmac_f32_e32 v38, v56, v46
	v_fmac_f32_e32 v39, v56, v47
	s_waitcnt vmcnt(24)
; DI unsigned cvtpk(float lo, float hi) { unsigned r; asm volatile("v_cvt_pk_bf16_f32 %0, %1, %2" : "=v"(r) : "v"(lo), "v"(hi)); return r; }
; DI void phase_ret_scan() {
;     ...
;     for (int k = 0; k < 16; ++k) {
;       const int sc = dir ? (15 - k) : k;
;       u16* pp = base + (size_t)sc * 393216;
;       const u32x4 uu = *(const u32x4*)pp;
;       u32x4 w = {cvtpk(S[0], S[1]), cvtpk(S[2], S[3]), cvtpk(S[4], S[5]), cvtpk(S[6], S[7])};
;       *(u32x4*)pp = w;
; #pragma unroll
;       for (int j = 0; j < 4; ++j) {
;         S[2 * j] = S[2 * j] * dk + __uint_as_float(uu[j] << 16);
;         S[2 * j + 1] = S[2 * j + 1] * dk + __uint_as_float(uu[j] & 0xffff0000u);
;       }
;     }
	v_cvt_pk_bf16_f32 v48, v32, v33
	v_cvt_pk_bf16_f32 v49, v34, v35
	v_cvt_pk_bf16_f32 v50, v36, v37
	v_cvt_pk_bf16_f32 v51, v38, v39
	global_store_dwordx4 v13, v[48:51], s[68:69]
	v_lshlrev_b32_e32 v40, 16, v88
	v_and_b32_e32 v41, 0xffff0000, v88
	v_lshlrev_b32_e32 v42, 16, v89
	v_and_b32_e32 v43, 0xffff0000, v89
	v_lshlrev_b32_e32 v44, 16, v90
	v_and_b32_e32 v45, 0xffff0000, v90
	v_lshlrev_b32_e32 v46, 16, v91
	v_and_b32_e32 v47, 0xffff0000, v91
	v_fmac_f32_e32 v40, v56, v32
	v_fmac_f32_e32 v41, v56, v33
	v_fmac_f32_e32 v42, v56, v34
	v_fmac_f32_e32 v43, v56, v35
	v_fmac_f32_e32 v44, v56, v36
	v_fmac_f32_e32 v45, v56, v37
	v_fmac_f32_e32 v46, v56, v38
	v_fmac_f32_e32 v47, v56, v39
	s_waitcnt vmcnt(23)
	v_cvt_pk_bf16_f32 v52, v40, v41
	v_cvt_pk_bf16_f32 v53, v42, v43
	v_cvt_pk_bf16_f32 v54, v44, v45
	v_cvt_pk_bf16_f32 v55, v46, v47
	global_store_dwordx4 v15, v[52:55], s[68:69]
	v_lshlrev_b32_e32 v32, 16, v92
	v_and_b32_e32 v33, 0xffff0000, v92
	v_lshlrev_b32_e32 v34, 16, v93
	v_and_b32_e32 v35, 0xffff0000, v93
	v_lshlrev_b32_e32 v36, 16, v94
	v_and_b32_e32 v37, 0xffff0000, v94
	v_lshlrev_b32_e32 v38, 16, v95
	v_and_b32_e32 v39, 0xffff0000, v95
	v_fmac_f32_e32 v32, v56, v40
	v_fmac_f32_e32 v33, v56, v41
	v_fmac_f32_e32 v34, v56, v42
	v_fmac_f32_e32 v35, v56, v43
	v_fmac_f32_e32 v36, v56, v44
	v_fmac_f32_e32 v37, v56, v45
	v_fmac_f32_e32 v38, v56, v46
	v_fmac_f32_e32 v39, v56, v47
	s_waitcnt vmcnt(22)
	v_cvt_pk_bf16_f32 v48, v32, v33
	v_cvt_pk_bf16_f32 v49, v34, v35
	v_cvt_pk_bf16_f32 v50, v36, v37
	v_cvt_pk_bf16_f32 v51, v38, v39
	global_store_dwordx4 v17, v[48:51], s[68:69]
	v_lshlrev_b32_e32 v40, 16, v96
	v_and_b32_e32 v41, 0xffff0000, v96
	v_lshlrev_b32_e32 v42, 16, v97
	v_and_b32_e32 v43, 0xffff0000, v97
	v_lshlrev_b32_e32 v44, 16, v98
	v_and_b32_e32 v45, 0xffff0000, v98
	v_lshlrev_b32_e32 v46, 16, v99
	v_and_b32_e32 v47, 0xffff0000, v99
	v_fmac_f32_e32 v40, v56, v32
	v_fmac_f32_e32 v41, v56, v33
	v_fmac_f32_e32 v42, v56, v34
	v_fmac_f32_e32 v43, v56, v35
	v_fmac_f32_e32 v44, v56, v36
	v_fmac_f32_e32 v45, v56, v37
	v_fmac_f32_e32 v46, v56, v38
	v_fmac_f32_e32 v47, v56, v39
	s_waitcnt vmcnt(21)
	v_cvt_pk_bf16_f32 v52, v40, v41
	v_cvt_pk_bf16_f32 v53, v42, v43
	v_cvt_pk_bf16_f32 v54, v44, v45
	v_cvt_pk_bf16_f32 v55, v46, v47
	global_store_dwordx4 v19, v[52:55], s[68:69]
	v_lshlrev_b32_e32 v32, 16, v100
	v_and_b32_e32 v33, 0xffff0000, v100
	v_lshlrev_b32_e32 v34, 16, v101
	v_and_b32_e32 v35, 0xffff0000, v101
	v_lshlrev_b32_e32 v36, 16, v102
	v_and_b32_e32 v37, 0xffff0000, v102
	v_lshlrev_b32_e32 v38, 16, v103
	v_and_b32_e32 v39, 0xffff0000, v103
	v_fmac_f32_e32 v32, v56, v40
	v_fmac_f32_e32 v33, v56, v41
	v_fmac_f32_e32 v34, v56, v42
	v_fmac_f32_e32 v35, v56, v43
	v_fmac_f32_e32 v36, v56, v44
	v_fmac_f32_e32 v37, v56, v45
	v_fmac_f32_e32 v38, v56, v46
	v_fmac_f32_e32 v39, v56, v47
	s_waitcnt vmcnt(20)
	v_cvt_pk_bf16_f32 v48, v32, v33
	v_cvt_pk_bf16_f32 v49, v34, v35
	v_cvt_pk_bf16_f32 v50, v36, v37
	v_cvt_pk_bf16_f32 v51, v38, v39
	global_store_dwordx4 v21, v[48:51], s[68:69]
	v_lshlrev_b32_e32 v40, 16, v104
	v_and_b32_e32 v41, 0xffff0000, v104
	v_lshlrev_b32_e32 v42, 16, v105
	v_and_b32_e32 v43, 0xffff0000, v105
	v_lshlrev_b32_e32 v44, 16, v106
	v_and_b32_e32 v45, 0xffff0000, v106
	v_lshlrev_b32_e32 v46, 16, v107
	v_and_b32_e32 v47, 0xffff0000, v107
	v_fmac_f32_e32 v40, v56, v32
	v_fmac_f32_e32 v41, v56, v33
	v_fmac_f32_e32 v42, v56, v34
	v_fmac_f32_e32 v43, v56, v35
	v_fmac_f32_e32 v44, v56, v36
	v_fmac_f32_e32 v45, v56, v37
	v_fmac_f32_e32 v46, v56, v38
	v_fmac_f32_e32 v47, v56, v39
	s_waitcnt vmcnt(19)
	v_cvt_pk_bf16_f32 v52, v40, v41
	v_cvt_pk_bf16_f32 v53, v42, v43
	v_cvt_pk_bf16_f32 v54, v44, v45
	v_cvt_pk_bf16_f32 v55, v46, v47
	global_store_dwordx4 v23, v[52:55], s[68:69]
	v_lshlrev_b32_e32 v32, 16, v108
	v_and_b32_e32 v33, 0xffff0000, v108
	v_lshlrev_b32_e32 v34, 16, v109
	v_and_b32_e32 v35, 0xffff0000, v109
	v_lshlrev_b32_e32 v36, 16, v110
	v_and_b32_e32 v37, 0xffff0000, v110
	v_lshlrev_b32_e32 v38, 16, v111
	v_and_b32_e32 v39, 0xffff0000, v111
	v_fmac_f32_e32 v32, v56, v40
	v_fmac_f32_e32 v33, v56, v41
	v_fmac_f32_e32 v34, v56, v42
	v_fmac_f32_e32 v35, v56, v43
	v_fmac_f32_e32 v36, v56, v44
	v_fmac_f32_e32 v37, v56, v45
	v_fmac_f32_e32 v38, v56, v46
	v_fmac_f32_e32 v39, v56, v47
	s_waitcnt vmcnt(18)
	v_cvt_pk_bf16_f32 v48, v32, v33
	v_cvt_pk_bf16_f32 v49, v34, v35
	v_cvt_pk_bf16_f32 v50, v36, v37
	v_cvt_pk_bf16_f32 v51, v38, v39
	global_store_dwordx4 v25, v[48:51], s[68:69]
	v_lshlrev_b32_e32 v40, 16, v112
	v_and_b32_e32 v41, 0xffff0000, v112
	v_lshlrev_b32_e32 v42, 16, v113
	v_and_b32_e32 v43, 0xffff0000, v113
	v_lshlrev_b32_e32 v44, 16, v114
	v_and_b32_e32 v45, 0xffff0000, v114
	v_lshlrev_b32_e32 v46, 16, v115
	v_and_b32_e32 v47, 0xffff0000, v115
	v_fmac_f32_e32 v40, v56, v32
	v_fmac_f32_e32 v41, v56, v33
	v_fmac_f32_e32 v42, v56, v34
	v_fmac_f32_e32 v43, v56, v35
	v_fmac_f32_e32 v44, v56, v36
	v_fmac_f32_e32 v45, v56, v37
	v_fmac_f32_e32 v46, v56, v38
	v_fmac_f32_e32 v47, v56, v39
	s_waitcnt vmcnt(17)
	v_cvt_pk_bf16_f32 v52, v40, v41
	v_cvt_pk_bf16_f32 v53, v42, v43
	v_cvt_pk_bf16_f32 v54, v44, v45
	v_cvt_pk_bf16_f32 v55, v46, v47
	global_store_dwordx4 v27, v[52:55], s[68:69]
	v_lshlrev_b32_e32 v32, 16, v116
	v_and_b32_e32 v33, 0xffff0000, v116
	v_lshlrev_b32_e32 v34, 16, v117
	v_and_b32_e32 v35, 0xffff0000, v117
	v_lshlrev_b32_e32 v36, 16, v118
	v_and_b32_e32 v37, 0xffff0000, v118
	v_lshlrev_b32_e32 v38, 16, v119
	v_and_b32_e32 v39, 0xffff0000, v119
	v_fmac_f32_e32 v32, v56, v40
	v_fmac_f32_e32 v33, v56, v41
	v_fmac_f32_e32 v34, v56, v42
	v_fmac_f32_e32 v35, v56, v43
	v_fmac_f32_e32 v36, v56, v44
	v_fmac_f32_e32 v37, v56, v45
	v_fmac_f32_e32 v38, v56, v46
	v_fmac_f32_e32 v39, v56, v47
	s_waitcnt vmcnt(16)
	v_cvt_pk_bf16_f32 v48, v32, v33
	v_cvt_pk_bf16_f32 v49, v34, v35
	v_cvt_pk_bf16_f32 v50, v36, v37
	v_cvt_pk_bf16_f32 v51, v38, v39
	global_store_dwordx4 v29, v[48:51], s[68:69]
	v_lshlrev_b32_e32 v40, 16, v120
	v_and_b32_e32 v41, 0xffff0000, v120
	v_lshlrev_b32_e32 v42, 16, v121
	v_and_b32_e32 v43, 0xffff0000, v121
	v_lshlrev_b32_e32 v44, 16, v122
	v_and_b32_e32 v45, 0xffff0000, v122
	v_lshlrev_b32_e32 v46, 16, v123
	v_and_b32_e32 v47, 0xffff0000, v123
	v_fmac_f32_e32 v40, v56, v32
	v_fmac_f32_e32 v41, v56, v33
	v_fmac_f32_e32 v42, v56, v34
	v_fmac_f32_e32 v43, v56, v35
	v_fmac_f32_e32 v44, v56, v36
	v_fmac_f32_e32 v45, v56, v37
	v_fmac_f32_e32 v46, v56, v38
	v_fmac_f32_e32 v47, v56, v39
	s_waitcnt vmcnt(15)
	v_cvt_pk_bf16_f32 v52, v40, v41
	v_cvt_pk_bf16_f32 v53, v42, v43
	v_cvt_pk_bf16_f32 v54, v44, v45
	v_cvt_pk_bf16_f32 v55, v46, v47
	global_store_dwordx4 v31, v[52:55], s[68:69]
	s_branch .LBB0_427

; #define ROW_LOOP(row, NROWS, BID, NB, WID) \
;   for (int it_ = 0, row = ((NB) == 256 ? ((((BID) & 7)) << 8) + (((BID) >> 3) << 3) + (WID) : (BID) * 8 + (WID)); row < (NROWS); \
;        ++it_, row = ((NB) == 256 ? ((((BID) & 7) + 8 * it_) << 8) + (((BID) >> 3) << 3) + (WID) : (BID) * 8 + (WID) + it_ * (NB) * 8))
; DI void phase_ret_comb() {
;     ...
;   ROW_LOOP(t, TG, bid, nb, wid) {
;     const size_t off0 = (size_t)t * 2048 + lane * 8;
;     f32x4 a[4], b[4]; u32x4 gg[4], yy[4];
; #pragma unroll
;     for (int h = 0; h < 4; ++h) { yy[h] = *(const u32x4*)(Yb + off0 + h * 512); gg[h] = *(const u32x4*)(Gs + off0 + h * 512); }
; #pragma unroll
;     for (int h = 0; h < 4; ++h) {
;       a[h] = f32x4{__uint_as_float(yy[h][0] << 16), __uint_as_float(yy[h][0] & 0xffff0000u), __uint_as_float(yy[h][1] << 16), __uint_as_float(yy[h][1] & 0xffff0000u)};
;       b[h] = f32x4{__uint_as_float(yy[h][2] << 16), __uint_as_float(yy[h][2] & 0xffff0000u), __uint_as_float(yy[h][3] << 16), __uint_as_float(yy[h][3] & 0xffff0000u)};
;     }
; #pragma unroll
;     for (int h = 0; h < 4; ++h) {
;       const float mu = wsum(a[h][0] + a[h][1] + a[h][2] + a[h][3] + b[h][0] + b[h][1] + b[h][2] + b[h][3]) * (1.f / 512.f);
.LBB0_573:
	v_ashrrev_i32_e32 v29, 6, v0
	v_add_u32_e32 v0, s1, v29
	s_movk_i32 s1, 0x4000
	v_cmp_gt_i32_e32 vcc, s1, v0
	s_and_saveexec_b64 s[8:9], vcc
	s_cbranch_execz .LBB0_578
	v_lshlrev_b32_e32 v1, 3, v1
	v_and_b32_e32 v28, 0x1f8, v1
	v_and_b32_e32 v1, 64, v183
	v_add_u32_e32 v1, 64, v1
	v_xor_b32_e32 v2, 32, v183
	v_cmp_lt_i32_e32 vcc, v2, v1
	s_waitcnt lgkmcnt(0)
	s_add_u32 s10, s16, 0x2362c100
	s_addc_u32 s11, s17, 0
	v_cndmask_b32_e32 v2, v183, v2, vcc
	v_lshlrev_b32_e32 v30, 2, v2
	v_xor_b32_e32 v2, 16, v183
	v_cmp_lt_i32_e32 vcc, v2, v1
	s_add_u32 s12, s16, 0x1f62c100
	s_addc_u32 s13, s17, 0
	v_cndmask_b32_e32 v2, v183, v2, vcc
	v_lshlrev_b32_e32 v31, 2, v2
	v_xor_b32_e32 v2, 8, v183
	v_cmp_lt_i32_e32 vcc, v2, v1
	s_add_u32 s68, s16, 0x2762c100
	s_addc_u32 s69, s17, 0
	v_cndmask_b32_e32 v2, v183, v2, vcc
	v_lshlrev_b32_e32 v32, 2, v2
	v_xor_b32_e32 v2, 4, v183
	v_cmp_lt_i32_e32 vcc, v2, v1
	s_lshl_b32 s2, s0, 8
	s_and_b32 s2, s2, 0x700
	v_cndmask_b32_e32 v2, v183, v2, vcc
	v_lshlrev_b32_e32 v33, 2, v2
	v_xor_b32_e32 v2, 2, v183
	v_cmp_lt_i32_e32 vcc, v2, v1
	s_and_b32 s16, s0, -8
	s_add_i32 s2, s2, s16
	v_cndmask_b32_e32 v2, v183, v2, vcc
	v_lshlrev_b32_e32 v34, 2, v2
	v_xor_b32_e32 v2, 1, v183
	v_cmp_lt_i32_e32 vcc, v2, v1
	s_mov_b32 s1, 0
	s_addk_i32 s2, 0x800
	v_cndmask_b32_e32 v1, v183, v2, vcc
	v_lshlrev_b32_e32 v35, 2, v1
	s_mov_b64 s[70:71], 0
	s_and_b64 vcc, exec, s[4:5]
	s_cbranch_vccz .LBB0_576
	v_readfirstlane_b32 s1, v0
	v_lshlrev_b32_e32 v6, 1, v28
	s_nop 3
	s_lshl_b32 s16, s1, 12
	v_add_u32_e32 v4, s16, v6
	global_load_dwordx4 v[60:63], v4, s[10:11]
	global_load_dwordx4 v[64:67], v4, s[10:11] offset:1024
	global_load_dwordx4 v[68:71], v4, s[10:11] offset:2048
	global_load_dwordx4 v[72:75], v4, s[10:11] offset:3072
	global_load_dwordx4 v[76:79], v4, s[12:13]
	global_load_dwordx4 v[80:83], v4, s[12:13] offset:1024
	global_load_dwordx4 v[84:87], v4, s[12:13] offset:2048
	global_load_dwordx4 v[88:91], v4, s[12:13] offset:3072
	s_waitcnt vmcnt(4)
	s_branch .Lfc_K_body
.Lfc_K_top:
	s_waitcnt vmcnt(8)
.Lfc_K_body:
	v_lshlrev_b32_e32 v92, 16, v60
	v_and_b32_e32 v93, 0xffff0000, v60
	v_lshlrev_b32_e32 v94, 16, v61
	v_and_b32_e32 v95, 0xffff0000, v61
	v_lshlrev_b32_e32 v96, 16, v62
	v_and_b32_e32 v97, 0xffff0000, v62
	v_lshlrev_b32_e32 v98, 16, v63
	v_and_b32_e32 v99, 0xffff0000, v63
	v_lshlrev_b32_e32 v100, 16, v64
	v_and_b32_e32 v101, 0xffff0000, v64
	v_lshlrev_b32_e32 v102, 16, v65
	v_and_b32_e32 v103, 0xffff0000, v65
	v_lshlrev_b32_e32 v104, 16, v66
	v_and_b32_e32 v105, 0xffff0000, v66
	v_lshlrev_b32_e32 v106, 16, v67
	v_and_b32_e32 v107, 0xffff0000, v67
	v_lshlrev_b32_e32 v108, 16, v68
	v_and_b32_e32 v109, 0xffff0000, v68
	v_lshlrev_b32_e32 v110, 16, v69
	v_and_b32_e32 v111, 0xffff0000, v69
	v_lshlrev_b32_e32 v112, 16, v70
	v_and_b32_e32 v113, 0xffff0000, v70
	v_lshlrev_b32_e32 v114, 16, v71
	v_and_b32_e32 v115, 0xffff0000, v71
	v_lshlrev_b32_e32 v116, 16, v72
	v_and_b32_e32 v117, 0xffff0000, v72
	v_lshlrev_b32_e32 v118, 16, v73
	v_and_b32_e32 v119, 0xffff0000, v73
	v_lshlrev_b32_e32 v120, 16, v74
	v_and_b32_e32 v121, 0xffff0000, v74
	v_lshlrev_b32_e32 v122, 16, v75
	v_and_b32_e32 v123, 0xffff0000, v75
	s_add_i32 s2, s1, 0x800
	s_cmp_lt_i32 s2, 0x4000
	s_cselect_b32 s16, s2, s1
	s_lshl_b32 s16, s16, 12
	v_add_u32_e32 v5, s16, v6
	global_load_dwordx4 v[60:63], v5, s[10:11]
	global_load_dwordx4 v[64:67], v5, s[10:11] offset:1024
	global_load_dwordx4 v[68:71], v5, s[10:11] offset:2048
	global_load_dwordx4 v[72:75], v5, s[10:11] offset:3072
	v_add_f32_e32 v40, v92, v93
	v_add_f32_e32 v41, v100, v101
	v_add_f32_e32 v42, v108, v109
	v_add_f32_e32 v43, v116, v117
	v_add_f32_e32 v40, v40, v94
	v_add_f32_e32 v41, v41, v102
	v_add_f32_e32 v42, v42, v110
	v_add_f32_e32 v43, v43, v118
	v_add_f32_e32 v40, v40, v95
	v_add_f32_e32 v41, v41, v103
	v_add_f32_e32 v42, v42, v111
	v_add_f32_e32 v43, v43, v119
	v_add_f32_e32 v40, v40, v96
	v_add_f32_e32 v41, v41, v104
	v_add_f32_e32 v42, v42, v112
	v_add_f32_e32 v43, v43, v120
	v_add_f32_e32 v40, v40, v97
	v_add_f32_e32 v41, v41, v105
	v_add_f32_e32 v42, v42, v113
	v_add_f32_e32 v43, v43, v121
	v_add_f32_e32 v40, v40, v98
	v_add_f32_e32 v41, v41, v106
	v_add_f32_e32 v42, v42, v114
	v_add_f32_e32 v43, v43, v122
	v_add_f32_e32 v40, v40, v99
	v_add_f32_e32 v41, v41, v107
	v_add_f32_e32 v42, v42, v115
	v_add_f32_e32 v43, v43, v123
	ds_bpermute_b32 v44, v30, v40
	ds_bpermute_b32 v45, v30, v41
	ds_bpermute_b32 v46, v30, v42
	ds_bpermute_b32 v47, v30, v43
	s_waitcnt lgkmcnt(0)
	v_add_f32_e32 v40, v40, v44
	v_add_f32_e32 v41, v41, v45
	v_add_f32_e32 v42, v42, v46
	v_add_f32_e32 v43, v43, v47
	ds_bpermute_b32 v44, v31, v40
	ds_bpermute_b32 v45, v31, v41
	ds_bpermute_b32 v46, v31, v42
	ds_bpermute_b32 v47, v31, v43
	s_waitcnt lgkmcnt(0)
	v_add_f32_e32 v40, v40, v44
	v_add_f32_e32 v41, v41, v45
	v_add_f32_e32 v42, v42, v46
	v_add_f32_e32 v43, v43, v47
	ds_bpermute_b32 v44, v32, v40
	ds_bpermute_b32 v45, v32, v41
	ds_bpermute_b32 v46, v32, v42
	ds_bpermute_b32 v47, v32, v43
	s_waitcnt lgkmcnt(0)
	v_add_f32_e32 v40, v40, v44
	v_add_f32_e32 v41, v41, v45
	v_add_f32_e32 v42, v42, v46
	v_add_f32_e32 v43, v43, v47
	ds_bpermute_b32 v44, v33, v40
	ds_bpermute_b32 v45, v33, v41
	ds_bpermute_b32 v46, v33, v42
	ds_bpermute_b32 v47, v33, v43
	s_waitcnt lgkmcnt(0)
	v_add_f32_e32 v40, v40, v44
	v_add_f32_e32 v41, v41, v45
	v_add_f32_e32 v42, v42, v46
	v_add_f32_e32 v43, v43, v47
	ds_bpermute_b32 v44, v34, v40
	ds_bpermute_b32 v45, v34, v41
	ds_bpermute_b32 v46, v34, v42
	ds_bpermute_b32 v47, v34, v43
	s_waitcnt lgkmcnt(0)
; DI void phase_ret_comb() {
;     ...
;     for (int h = 0; h < 4; ++h) {
;       const float mu = wsum(a[h][0] + a[h][1] + a[h][2] + a[h][3] + b[h][0] + b[h][1] + b[h][2] + b[h][3]) * (1.f / 512.f);
;       float d[8] = {a[h][0] - mu, a[h][1] - mu, a[h][2] - mu, a[h][3] - mu, b[h][0] - mu, b[h][1] - mu, b[h][2] - mu, b[h][3] - mu};
;       float vs = 0.f;
; #pragma unroll
;       for (int j = 0; j < 8; ++j) vs += d[j] * d[j];
;       const float rs = rsqrtf(wsum(vs) * (1.f / 512.f) + EPS);
	v_add_f32_e32 v40, v40, v44
	v_add_f32_e32 v41, v41, v45
	v_add_f32_e32 v42, v42, v46
	v_add_f32_e32 v43, v43, v47
	ds_bpermute_b32 v44, v35, v40
	ds_bpermute_b32 v45, v35, v41
	ds_bpermute_b32 v46, v35, v42
	ds_bpermute_b32 v47, v35, v43
	s_waitcnt lgkmcnt(0)
	v_add_f32_e32 v40, v40, v44
	v_add_f32_e32 v41, v41, v45
	v_add_f32_e32 v42, v42, v46
	v_add_f32_e32 v43, v43, v47
	v_fmac_f32_e32 v92, 0xbb000000, v40
	v_fmac_f32_e32 v100, 0xbb000000, v41
	v_fmac_f32_e32 v108, 0xbb000000, v42
	v_fmac_f32_e32 v116, 0xbb000000, v43
	v_fmac_f32_e32 v93, 0xbb000000, v40
	v_fmac_f32_e32 v101, 0xbb000000, v41
	v_fmac_f32_e32 v109, 0xbb000000, v42
	v_fmac_f32_e32 v117, 0xbb000000, v43
	v_fmac_f32_e32 v94, 0xbb000000, v40
	v_fmac_f32_e32 v102, 0xbb000000, v41
	v_fmac_f32_e32 v110, 0xbb000000, v42
	v_fmac_f32_e32 v118, 0xbb000000, v43
	v_fmac_f32_e32 v95, 0xbb000000, v40
	v_fmac_f32_e32 v103, 0xbb000000, v41
	v_fmac_f32_e32 v111, 0xbb000000, v42
	v_fmac_f32_e32 v119, 0xbb000000, v43
	v_fmac_f32_e32 v96, 0xbb000000, v40
	v_fmac_f32_e32 v104, 0xbb000000, v41
	v_fmac_f32_e32 v112, 0xbb000000, v42
	v_fmac_f32_e32 v120, 0xbb000000, v43
	v_fmac_f32_e32 v97, 0xbb000000, v40
	v_fmac_f32_e32 v105, 0xbb000000, v41
	v_fmac_f32_e32 v113, 0xbb000000, v42
	v_fmac_f32_e32 v121, 0xbb000000, v43
	v_fmac_f32_e32 v98, 0xbb000000, v40
	v_fmac_f32_e32 v106, 0xbb000000, v41
	v_fmac_f32_e32 v114, 0xbb000000, v42
	v_fmac_f32_e32 v122, 0xbb000000, v43
	v_fmac_f32_e32 v99, 0xbb000000, v40
	v_fmac_f32_e32 v107, 0xbb000000, v41
	v_fmac_f32_e32 v115, 0xbb000000, v42
	v_fmac_f32_e32 v123, 0xbb000000, v43
	v_mul_f32_e32 v40, v92, v92
	v_mul_f32_e32 v41, v100, v100
	v_mul_f32_e32 v42, v108, v108
	v_mul_f32_e32 v43, v116, v116
	v_fmac_f32_e32 v40, v93, v93
	v_fmac_f32_e32 v41, v101, v101
	v_fmac_f32_e32 v42, v109, v109
	v_fmac_f32_e32 v43, v117, v117
	v_fmac_f32_e32 v40, v94, v94
	v_fmac_f32_e32 v41, v102, v102
	v_fmac_f32_e32 v42, v110, v110
	v_fmac_f32_e32 v43, v118, v118
	v_fmac_f32_e32 v40, v95, v95
	v_fmac_f32_e32 v41, v103, v103
	v_fmac_f32_e32 v42, v111, v111
	v_fmac_f32_e32 v43, v119, v119
	v_fmac_f32_e32 v40, v96, v96
	v_fmac_f32_e32 v41, v104, v104
	v_fmac_f32_e32 v42, v112, v112
	v_fmac_f32_e32 v43, v120, v120
	v_fmac_f32_e32 v40, v97, v97
	v_fmac_f32_e32 v41, v105, v105
	v_fmac_f32_e32 v42, v113, v113
	v_fmac_f32_e32 v43, v121, v121
	v_fmac_f32_e32 v40, v98, v98
	v_fmac_f32_e32 v41, v106, v106
	v_fmac_f32_e32 v42, v114, v114
	v_fmac_f32_e32 v43, v122, v122
	v_fmac_f32_e32 v40, v99, v99
	v_fmac_f32_e32 v41, v107, v107
	v_fmac_f32_e32 v42, v115, v115
	v_fmac_f32_e32 v43, v123, v123
	ds_bpermute_b32 v44, v30, v40
	ds_bpermute_b32 v45, v30, v41
	ds_bpermute_b32 v46, v30, v42
	ds_bpermute_b32 v47, v30, v43
	s_waitcnt lgkmcnt(0)
	v_add_f32_e32 v40, v40, v44
	v_add_f32_e32 v41, v41, v45
	v_add_f32_e32 v42, v42, v46
	v_add_f32_e32 v43, v43, v47
	ds_bpermute_b32 v44, v31, v40
	ds_bpermute_b32 v45, v31, v41
	ds_bpermute_b32 v46, v31, v42
	ds_bpermute_b32 v47, v31, v43
	s_waitcnt lgkmcnt(0)
	v_add_f32_e32 v40, v40, v44
	v_add_f32_e32 v41, v41, v45
	v_add_f32_e32 v42, v42, v46
	v_add_f32_e32 v43, v43, v47
	ds_bpermute_b32 v44, v32, v40
	ds_bpermute_b32 v45, v32, v41
	ds_bpermute_b32 v46, v32, v42
	ds_bpermute_b32 v47, v32, v43
	s_waitcnt lgkmcnt(0)
	v_add_f32_e32 v40, v40, v44
	v_add_f32_e32 v41, v41, v45
	v_add_f32_e32 v42, v42, v46
	v_add_f32_e32 v43, v43, v47
	ds_bpermute_b32 v44, v33, v40
	ds_bpermute_b32 v45, v33, v41
	ds_bpermute_b32 v46, v33, v42
	ds_bpermute_b32 v47, v33, v43
	s_waitcnt lgkmcnt(0)
	v_add_f32_e32 v40, v40, v44
	v_add_f32_e32 v41, v41, v45
	v_add_f32_e32 v42, v42, v46
	v_add_f32_e32 v43, v43, v47
	ds_bpermute_b32 v44, v34, v40
	ds_bpermute_b32 v45, v34, v41
	ds_bpermute_b32 v46, v34, v42
	ds_bpermute_b32 v47, v34, v43
	s_waitcnt lgkmcnt(0)
	v_add_f32_e32 v40, v40, v44
	v_add_f32_e32 v41, v41, v45
	v_add_f32_e32 v42, v42, v46
	v_add_f32_e32 v43, v43, v47
	ds_bpermute_b32 v44, v35, v40
	ds_bpermute_b32 v45, v35, v41
	ds_bpermute_b32 v46, v35, v42
	ds_bpermute_b32 v47, v35, v43
	s_waitcnt lgkmcnt(0)
	v_add_f32_e32 v40, v40, v44
	v_add_f32_e32 v41, v41, v45
	v_add_f32_e32 v42, v42, v46
	v_add_f32_e32 v43, v43, v47
	v_fmamk_f32 v52, v40, 0x3b000000, v142
	v_cmp_gt_f32_e32 vcc, 0x800000, v52
	v_mul_f32_e32 v53, 0x4b800000, v52
	s_nop 1
	v_cndmask_b32_e32 v52, v52, v53, vcc
	v_rsq_f32_e32 v52, v52
	s_nop 0
	v_mul_f32_e32 v53, 0x45800000, v52
	v_cndmask_b32_e32 v48, v52, v53, vcc
	v_fmamk_f32 v52, v41, 0x3b000000, v142
	v_cmp_gt_f32_e32 vcc, 0x800000, v52
	v_mul_f32_e32 v53, 0x4b800000, v52
	s_nop 1
	v_cndmask_b32_e32 v52, v52, v53, vcc
	v_rsq_f32_e32 v52, v52
	s_nop 0
	v_mul_f32_e32 v53, 0x45800000, v52
	v_cndmask_b32_e32 v49, v52, v53, vcc
	v_fmamk_f32 v52, v42, 0x3b000000, v142
	v_cmp_gt_f32_e32 vcc, 0x800000, v52
	v_mul_f32_e32 v53, 0x4b800000, v52
	s_nop 1
	v_cndmask_b32_e32 v52, v52, v53, vcc
	v_rsq_f32_e32 v52, v52
	s_nop 0
	v_mul_f32_e32 v53, 0x45800000, v52
	v_cndmask_b32_e32 v50, v52, v53, vcc
	v_fmamk_f32 v52, v43, 0x3b000000, v142
	v_cmp_gt_f32_e32 vcc, 0x800000, v52
	v_mul_f32_e32 v53, 0x4b800000, v52
	s_nop 1
	v_cndmask_b32_e32 v52, v52, v53, vcc
	v_rsq_f32_e32 v52, v52
	s_nop 0
	v_mul_f32_e32 v53, 0x45800000, v52
	v_cndmask_b32_e32 v51, v52, v53, vcc
	s_waitcnt vmcnt(4)
; DI unsigned cvtpk(float lo, float hi) { unsigned r; asm volatile("v_cvt_pk_bf16_f32 %0, %1, %2" : "=v"(r) : "v"(lo), "v"(hi)); return r; }
; DI void phase_ret_comb() {
;     ...
;       float o[8];
; #pragma unroll
;       for (int j = 0; j < 4; ++j) { o[2 * j] = d[2 * j] * rs * __uint_as_float(gg[h][j] << 16); o[2 * j + 1] = d[2 * j + 1] * rs * __uint_as_float(gg[h][j] & 0xffff0000u); }
;       u32x4 wv = {cvtpk(o[0], o[1]), cvtpk(o[2], o[3]), cvtpk(o[4], o[5]), cvtpk(o[6], o[7])};
;       *(u32x4*)(Yn + off0 + h * 512) = wv;
;     }
	v_mul_f32_e32 v92, v92, v48
	v_mul_f32_e32 v93, v93, v48
	v_mul_f32_e32 v94, v94, v48
	v_mul_f32_e32 v95, v95, v48
	v_mul_f32_e32 v96, v96, v48
	v_mul_f32_e32 v97, v97, v48
	v_mul_f32_e32 v98, v98, v48
	v_mul_f32_e32 v99, v99, v48
	v_lshlrev_b32_e32 v52, 16, v76
	v_and_b32_e32 v53, 0xffff0000, v76
	v_mul_f32_e32 v92, v92, v52
	v_mul_f32_e32 v93, v93, v53
	v_cvt_pk_bf16_f32 v36, v92, v93
	v_lshlrev_b32_e32 v52, 16, v77
	v_and_b32_e32 v53, 0xffff0000, v77
	v_mul_f32_e32 v94, v94, v52
	v_mul_f32_e32 v95, v95, v53
	v_cvt_pk_bf16_f32 v37, v94, v95
	v_lshlrev_b32_e32 v52, 16, v78
	v_and_b32_e32 v53, 0xffff0000, v78
	v_mul_f32_e32 v96, v96, v52
	v_mul_f32_e32 v97, v97, v53
	v_cvt_pk_bf16_f32 v38, v96, v97
	v_lshlrev_b32_e32 v52, 16, v79
	v_and_b32_e32 v53, 0xffff0000, v79
	v_mul_f32_e32 v98, v98, v52
	v_mul_f32_e32 v99, v99, v53
	v_cvt_pk_bf16_f32 v39, v98, v99
	global_store_dwordx4 v4, v[36:39], s[68:69]
	v_mul_f32_e32 v100, v100, v49
	v_mul_f32_e32 v101, v101, v49
	v_mul_f32_e32 v102, v102, v49
	v_mul_f32_e32 v103, v103, v49
	v_mul_f32_e32 v104, v104, v49
	v_mul_f32_e32 v105, v105, v49
	v_mul_f32_e32 v106, v106, v49
	v_mul_f32_e32 v107, v107, v49
	v_lshlrev_b32_e32 v52, 16, v80
	v_and_b32_e32 v53, 0xffff0000, v80
	v_mul_f32_e32 v100, v100, v52
	v_mul_f32_e32 v101, v101, v53
	v_cvt_pk_bf16_f32 v24, v100, v101
	v_lshlrev_b32_e32 v52, 16, v81
	v_and_b32_e32 v53, 0xffff0000, v81
	v_mul_f32_e32 v102, v102, v52
	v_mul_f32_e32 v103, v103, v53
	v_cvt_pk_bf16_f32 v25, v102, v103
	v_lshlrev_b32_e32 v52, 16, v82
	v_and_b32_e32 v53, 0xffff0000, v82
	v_mul_f32_e32 v104, v104, v52
	v_mul_f32_e32 v105, v105, v53
	v_cvt_pk_bf16_f32 v26, v104, v105
	v_lshlrev_b32_e32 v52, 16, v83
	v_and_b32_e32 v53, 0xffff0000, v83
	v_mul_f32_e32 v106, v106, v52
	v_mul_f32_e32 v107, v107, v53
	v_cvt_pk_bf16_f32 v27, v106, v107
	global_store_dwordx4 v4, v[24:27], s[68:69] offset:1024
	v_mul_f32_e32 v108, v108, v50
	v_mul_f32_e32 v109, v109, v50
	v_mul_f32_e32 v110, v110, v50
	v_mul_f32_e32 v111, v111, v50
	v_mul_f32_e32 v112, v112, v50
	v_mul_f32_e32 v113, v113, v50
	v_mul_f32_e32 v114, v114, v50
	v_mul_f32_e32 v115, v115, v50
	v_lshlrev_b32_e32 v52, 16, v84
	v_and_b32_e32 v53, 0xffff0000, v84
	v_mul_f32_e32 v108, v108, v52
	v_mul_f32_e32 v109, v109, v53
	v_cvt_pk_bf16_f32 v36, v108, v109
	v_lshlrev_b32_e32 v52, 16, v85
	v_and_b32_e32 v53, 0xffff0000, v85
	v_mul_f32_e32 v110, v110, v52
	v_mul_f32_e32 v111, v111, v53
	v_cvt_pk_bf16_f32 v37, v110, v111
	v_lshlrev_b32_e32 v52, 16, v86
	v_and_b32_e32 v53, 0xffff0000, v86
	v_mul_f32_e32 v112, v112, v52
	v_mul_f32_e32 v113, v113, v53
	v_cvt_pk_bf16_f32 v38, v112, v113
	v_lshlrev_b32_e32 v52, 16, v87
	v_and_b32_e32 v53, 0xffff0000, v87
	v_mul_f32_e32 v114, v114, v52
	v_mul_f32_e32 v115, v115, v53
	v_cvt_pk_bf16_f32 v39, v114, v115
	global_store_dwordx4 v4, v[36:39], s[68:69] offset:2048
	v_mul_f32_e32 v116, v116, v51
	v_mul_f32_e32 v117, v117, v51
	v_mul_f32_e32 v118, v118, v51
	v_mul_f32_e32 v119, v119, v51
	v_mul_f32_e32 v120, v120, v51
	v_mul_f32_e32 v121, v121, v51
	v_mul_f32_e32 v122, v122, v51
	v_mul_f32_e32 v123, v123, v51
	v_lshlrev_b32_e32 v52, 16, v88
	v_and_b32_e32 v53, 0xffff0000, v88
	v_mul_f32_e32 v116, v116, v52
	v_mul_f32_e32 v117, v117, v53
	v_cvt_pk_bf16_f32 v24, v116, v117
	v_lshlrev_b32_e32 v52, 16, v89
	v_and_b32_e32 v53, 0xffff0000, v89
	v_mul_f32_e32 v118, v118, v52
	v_mul_f32_e32 v119, v119, v53
	v_cvt_pk_bf16_f32 v25, v118, v119
	v_lshlrev_b32_e32 v52, 16, v90
	v_and_b32_e32 v53, 0xffff0000, v90
	v_mul_f32_e32 v120, v120, v52
	v_mul_f32_e32 v121, v121, v53
	v_cvt_pk_bf16_f32 v26, v120, v121
	v_lshlrev_b32_e32 v52, 16, v91
	v_and_b32_e32 v53, 0xffff0000, v91
	v_mul_f32_e32 v122, v122, v52
	v_mul_f32_e32 v123, v123, v53
	v_cvt_pk_bf16_f32 v27, v122, v123
	global_store_dwordx4 v4, v[24:27], s[68:69] offset:3072
	global_load_dwordx4 v[76:79], v5, s[12:13]
	global_load_dwordx4 v[80:83], v5, s[12:13] offset:1024
	global_load_dwordx4 v[84:87], v5, s[12:13] offset:2048
	global_load_dwordx4 v[88:91], v5, s[12:13] offset:3072
	v_mov_b32_e32 v4, v5
	s_mov_b32 s1, s2
	s_cmp_lt_i32 s2, 0x4000
	s_cbranch_scc1 .Lfc_K_top
	s_branch .LBB0_578

; DI void st4(u16* p, float a, float b, float c, float d) { u32x2 w = {cvtpk(a, b), cvtpk(c, d)}; *(u32x2*)p = w; }
;   DI void operator()(int m, int n, f32x4 v) const { st4(dst + (size_t)m * ld + n, v[0], v[1], v[2], v[3]); }
;   DI void operator()(int m, int n, f32x4 v) const {
;     const f32x4 x = *(const f32x4*)(xin + (size_t)m * 1024 + n), g = *(const f32x4*)(gate + n);
;     st4(out + (size_t)m * 1024 + n, x[0] + g[0] * v[0], x[1] + g[1] * v[1], x[2] + g[2] * v[2], x[3] + g[3] * v[3]);
;   }
.LBB0_638:
	s_or_b64 exec, exec, s[10:11]
	s_ashr_i32 s10, s68, 4
	s_add_i32 s26, s10, s0
	s_lshl_b64 s[10:11], s[68:69], 18
	s_or_b64 s[10:11], s[10:11], s[96:97]
	s_mul_hi_i32 s27, s26, 0x6000
	s_mulk_i32 s26, 0x6000
	s_add_u32 s26, s16, s26
	s_addc_u32 s27, s17, s27
	s_lshl_b32 s33, s96, 2
	s_add_u32 s68, s26, s33
	s_addc_u32 s69, s27, 0
	s_lshl_b64 s[26:27], s[10:11], 2
	s_add_u32 s72, s12, s26
	s_addc_u32 s73, s13, s27
	s_lshl_b64 s[10:11], s[10:11], 1
	s_add_u32 s70, s24, s10
	v_cmp_gt_i32_e32 vcc, 3, v136
	s_movk_i32 s10, 0x2200
	v_mul_lo_u32 v128, v136, s10
	v_cndmask_b32_e32 v130, v143, v144, vcc
	v_lshlrev_b32_e32 v131, 4, v134
	v_add3_u32 v128, 16, v128, v130
	v_and_b32_e32 v130, 0x80, v131
	v_lshlrev_b32_e32 v132, 5, v135
	v_and_b32_e32 v135, 28, v137
	v_or3_b32 v154, v130, v132, v135
	v_lshlrev_b32_e32 v132, 2, v134
	v_mul_u32_u24_e32 v134, 0x440, v133
	v_add3_u32 v132, v128, v132, v134
	ds_write2_b32 v132, v104, v108 offset1:16
	ds_write2_b32 v132, v105, v109 offset0:68 offset1:84
	ds_write2_b32 v132, v106, v110 offset0:136 offset1:152
	ds_write2_b32 v132, v107, v111 offset0:204 offset1:220
	ds_write2_b32 v132, v120, v124 offset0:32 offset1:48
	ds_write2_b32 v132, v121, v125 offset0:100 offset1:116
	ds_write2_b32 v132, v122, v126 offset0:168 offset1:184
	ds_write2_b32 v132, v123, v127 offset0:236 offset1:252
	v_add_u32_e32 v122, 0x1000, v132
	v_or_b32_e32 v130, v160, v133
	ds_write2_b32 v122, v96, v100 offset0:64 offset1:80
	ds_write2_b32 v122, v97, v101 offset0:132 offset1:148
	ds_write2_b32 v122, v98, v102 offset0:200 offset1:216
	v_mul_u32_u24_e32 v96, 0x110, v133
	v_add3_u32 v123, v128, v131, v96
	v_ashrrev_i32_e32 v131, 31, v130
	v_add_u32_e32 v124, 0x1400, v132
	v_lshlrev_b64 v[120:121], 12, v[130:131]
	ds_write2_b32 v124, v99, v103 offset0:12 offset1:28
	ds_write2_b32 v122, v112, v116 offset0:96 offset1:112
	ds_write2_b32 v122, v113, v117 offset0:164 offset1:180
	ds_write2_b32 v122, v114, v118 offset0:232 offset1:248
	ds_write2_b32 v124, v115, v119 offset0:44 offset1:60
	v_lshl_add_u64 v[120:121], s[72:73], 0, v[120:121]
	v_lshlrev_b32_e32 v128, 2, v154
	s_waitcnt lgkmcnt(0)
	v_lshl_add_u64 v[120:121], v[120:121], 0, v[128:129]
	ds_read_b128 v[134:137], v123
	ds_read_b128 v[138:141], v123 offset:1088
	ds_read_b128 v[116:119], v123 offset:2176
	ds_read_b128 v[112:115], v123 offset:3264
	ds_read_b128 v[108:111], v123 offset:4352
	ds_read_b128 v[104:107], v123 offset:5440
	ds_read_b128 v[100:103], v123 offset:6528
	ds_read_b128 v[96:99], v123 offset:7616
	s_mov_b64 s[74:75], 0x4000
	global_load_dwordx4 v[188:191], v[120:121], off
	v_lshl_add_u64 v[224:225], v[120:121], 0, s[74:75]
	global_load_dwordx4 v[192:195], v[224:225], off
	v_lshl_add_u64 v[224:225], v[224:225], 0, s[74:75]
	global_load_dwordx4 v[196:199], v[224:225], off
	v_lshl_add_u64 v[224:225], v[224:225], 0, s[74:75]
	global_load_dwordx4 v[200:203], v[224:225], off
	v_lshl_add_u64 v[224:225], v[224:225], 0, s[74:75]
	global_load_dwordx4 v[204:207], v[224:225], off
	v_lshl_add_u64 v[224:225], v[224:225], 0, s[74:75]
	global_load_dwordx4 v[208:211], v[224:225], off
	v_lshl_add_u64 v[224:225], v[224:225], 0, s[74:75]
	global_load_dwordx4 v[212:215], v[224:225], off
	v_lshl_add_u64 v[224:225], v[224:225], 0, s[74:75]
	global_load_dwordx4 v[216:219], v[224:225], off
	global_load_dwordx4 v[220:223], v128, s[68:69]
	s_addc_u32 s71, s25, s11
	v_lshlrev_b64 v[120:121], 11, v[130:131]
	v_lshl_add_u64 v[126:127], s[70:71], 0, v[120:121]
	v_lshlrev_b32_e32 v120, 1, v154
	v_mov_b32_e32 v121, v129
	v_lshl_add_u64 v[126:127], v[126:127], 0, v[120:121]
	s_add_i32 s2, s2, s3
	s_ashr_i32 s10, s2, 31
	s_lshr_b32 s10, s10, 29
	s_add_i32 s26, s2, s10
	s_ashr_i32 s27, s26, 3
	s_and_b64 s[10:11], s[6:7], exec
	s_cselect_b32 s10, s2, s27
	s_and_b32 s11, s26, -8
	s_sub_i32 s11, s2, s11
	s_and_b64 s[26:27], s[6:7], exec
	s_cselect_b32 s1, s1, s11
	s_cmp_lt_i32 s10, 32
	s_cselect_b64 s[26:27], -1, 0
	s_cmpk_lt_i32 s2, 0x100
	s_waitcnt vmcnt(0) lgkmcnt(0)
	v_mov_b32_e32 v146, v188
	v_mov_b32_e32 v147, v189
	v_mov_b32_e32 v148, v190
	v_mov_b32_e32 v149, v191
	v_mov_b32_e32 v150, v220
	v_mov_b32_e32 v151, v221
	v_mov_b32_e32 v152, v222
	v_mov_b32_e32 v153, v223
	v_fma_f32 v125, v134, v150, v146
	v_fma_f32 v131, v135, v151, v147
	v_fma_f32 v133, v136, v152, v148
	v_fmac_f32_e32 v149, v137, v153
	v_cvt_pk_bf16_f32 v134, v125, v131
	v_cvt_pk_bf16_f32 v135, v133, v149
	global_store_dwordx2 v[126:127], v[134:135], off
	v_or_b32_e32 v126, 4, v130
	v_ashrrev_i32_e32 v127, 31, v126
	v_lshlrev_b64 v[134:135], 12, v[126:127]
	v_lshl_add_u64 v[134:135], s[72:73], 0, v[134:135]
	v_lshl_add_u64 v[134:135], v[134:135], 0, v[128:129]
	s_nop 0
	v_lshlrev_b64 v[126:127], 11, v[126:127]
	v_lshl_add_u64 v[126:127], s[70:71], 0, v[126:127]
	v_lshl_add_u64 v[126:127], v[126:127], 0, v[120:121]
	s_waitcnt vmcnt(7)
	v_mov_b32_e32 v134, v192
	v_mov_b32_e32 v135, v193
	v_mov_b32_e32 v136, v194
	v_mov_b32_e32 v137, v195
	v_mov_b32_e32 v146, v220
	v_mov_b32_e32 v147, v221
	v_mov_b32_e32 v148, v222
	v_mov_b32_e32 v149, v223
	v_fma_f32 v125, v138, v146, v134
	v_fma_f32 v131, v139, v147, v135
	v_fma_f32 v133, v140, v148, v136
	v_fmac_f32_e32 v137, v141, v149
	v_cvt_pk_bf16_f32 v134, v125, v131
	v_cvt_pk_bf16_f32 v135, v133, v137
	global_store_dwordx2 v[126:127], v[134:135], off
	v_or_b32_e32 v126, 8, v130
	v_ashrrev_i32_e32 v127, 31, v126
	v_lshlrev_b64 v[134:135], 12, v[126:127]
	v_lshl_add_u64 v[134:135], s[72:73], 0, v[134:135]
	v_lshl_add_u64 v[134:135], v[134:135], 0, v[128:129]
	s_nop 0
	v_lshlrev_b64 v[126:127], 11, v[126:127]
	v_lshl_add_u64 v[126:127], s[70:71], 0, v[126:127]
	v_lshl_add_u64 v[126:127], v[126:127], 0, v[120:121]
	s_waitcnt vmcnt(7)
; DI void st4(u16* p, float a, float b, float c, float d) { u32x2 w = {cvtpk(a, b), cvtpk(c, d)}; *(u32x2*)p = w; }
;   DI void operator()(int m, int n, f32x4 v) const { st4(dst + (size_t)m * ld + n, v[0], v[1], v[2], v[3]); }
;   DI void operator()(int m, int n, f32x4 v) const {
;     const f32x4 x = *(const f32x4*)(xin + (size_t)m * 1024 + n), g = *(const f32x4*)(gate + n);
;     st4(out + (size_t)m * 1024 + n, x[0] + g[0] * v[0], x[1] + g[1] * v[1], x[2] + g[2] * v[2], x[3] + g[3] * v[3]);
;   }
	v_mov_b32_e32 v134, v196
	v_mov_b32_e32 v135, v197
	v_mov_b32_e32 v136, v198
	v_mov_b32_e32 v137, v199
	v_mov_b32_e32 v138, v220
	v_mov_b32_e32 v139, v221
	v_mov_b32_e32 v140, v222
	v_mov_b32_e32 v141, v223
	v_fma_f32 v116, v116, v138, v134
	v_fma_f32 v117, v117, v139, v135
	v_fma_f32 v118, v118, v140, v136
	v_fmac_f32_e32 v137, v119, v141
	v_cvt_pk_bf16_f32 v116, v116, v117
	v_cvt_pk_bf16_f32 v117, v118, v137
	global_store_dwordx2 v[126:127], v[116:117], off
	v_or_b32_e32 v126, 12, v130
	v_ashrrev_i32_e32 v127, 31, v126
	v_lshlrev_b64 v[116:117], 12, v[126:127]
	v_lshl_add_u64 v[116:117], s[72:73], 0, v[116:117]
	v_lshl_add_u64 v[116:117], v[116:117], 0, v[128:129]
	s_nop 0
	v_lshlrev_b64 v[126:127], 11, v[126:127]
	v_lshl_add_u64 v[126:127], s[70:71], 0, v[126:127]
	v_lshl_add_u64 v[126:127], v[126:127], 0, v[120:121]
	s_waitcnt vmcnt(7)
	v_mov_b32_e32 v116, v200
	v_mov_b32_e32 v117, v201
	v_mov_b32_e32 v118, v202
	v_mov_b32_e32 v119, v203
	v_mov_b32_e32 v134, v220
	v_mov_b32_e32 v135, v221
	v_mov_b32_e32 v136, v222
	v_mov_b32_e32 v137, v223
	v_fma_f32 v112, v112, v134, v116
	v_fma_f32 v113, v113, v135, v117
	v_fma_f32 v114, v114, v136, v118
	v_fmac_f32_e32 v119, v115, v137
	v_cvt_pk_bf16_f32 v112, v112, v113
	v_cvt_pk_bf16_f32 v113, v114, v119
	global_store_dwordx2 v[126:127], v[112:113], off
	v_or_b32_e32 v126, 16, v130
	v_ashrrev_i32_e32 v127, 31, v126
	v_lshlrev_b64 v[112:113], 12, v[126:127]
	v_lshl_add_u64 v[112:113], s[72:73], 0, v[112:113]
	v_lshl_add_u64 v[112:113], v[112:113], 0, v[128:129]
	s_nop 0
	v_lshlrev_b64 v[126:127], 11, v[126:127]
	v_lshl_add_u64 v[126:127], s[70:71], 0, v[126:127]
	v_lshl_add_u64 v[126:127], v[126:127], 0, v[120:121]
	s_waitcnt vmcnt(7)
	v_mov_b32_e32 v112, v204
	v_mov_b32_e32 v113, v205
	v_mov_b32_e32 v114, v206
	v_mov_b32_e32 v115, v207
	v_mov_b32_e32 v116, v220
	v_mov_b32_e32 v117, v221
	v_mov_b32_e32 v118, v222
	v_mov_b32_e32 v119, v223
	v_fma_f32 v108, v108, v116, v112
	v_fma_f32 v109, v109, v117, v113
	v_or_b32_e32 v116, 20, v130
	v_fma_f32 v110, v110, v118, v114
	v_fmac_f32_e32 v115, v111, v119
	v_cvt_pk_bf16_f32 v108, v108, v109
	v_cvt_pk_bf16_f32 v109, v110, v115
	v_ashrrev_i32_e32 v117, 31, v116
	global_store_dwordx2 v[126:127], v[108:109], off
	v_lshlrev_b64 v[108:109], 12, v[116:117]
	v_lshl_add_u64 v[108:109], s[72:73], 0, v[108:109]
	v_lshl_add_u64 v[108:109], v[108:109], 0, v[128:129]
	s_nop 0
	v_lshlrev_b64 v[116:117], 11, v[116:117]
	v_lshl_add_u64 v[116:117], s[70:71], 0, v[116:117]
	v_lshl_add_u64 v[116:117], v[116:117], 0, v[120:121]
	s_waitcnt vmcnt(7)
	v_mov_b32_e32 v108, v208
	v_mov_b32_e32 v109, v209
	v_mov_b32_e32 v110, v210
	v_mov_b32_e32 v111, v211
	v_mov_b32_e32 v112, v220
	v_mov_b32_e32 v113, v221
	v_mov_b32_e32 v114, v222
	v_mov_b32_e32 v115, v223
	v_fma_f32 v104, v104, v112, v108
	v_fma_f32 v105, v105, v113, v109
	v_or_b32_e32 v112, 24, v130
	v_fma_f32 v106, v106, v114, v110
	v_fmac_f32_e32 v111, v107, v115
	v_cvt_pk_bf16_f32 v104, v104, v105
	v_cvt_pk_bf16_f32 v105, v106, v111
	v_ashrrev_i32_e32 v113, 31, v112
	global_store_dwordx2 v[116:117], v[104:105], off
	v_lshlrev_b64 v[104:105], 12, v[112:113]
	v_lshl_add_u64 v[104:105], s[72:73], 0, v[104:105]
	v_lshl_add_u64 v[104:105], v[104:105], 0, v[128:129]
	s_nop 0
	v_lshlrev_b64 v[112:113], 11, v[112:113]
	v_lshl_add_u64 v[112:113], s[70:71], 0, v[112:113]
	v_lshl_add_u64 v[112:113], v[112:113], 0, v[120:121]
	s_waitcnt vmcnt(7)
	v_mov_b32_e32 v104, v212
	v_mov_b32_e32 v105, v213
	v_mov_b32_e32 v106, v214
	v_mov_b32_e32 v107, v215
	v_mov_b32_e32 v108, v220
	v_mov_b32_e32 v109, v221
	v_mov_b32_e32 v110, v222
	v_mov_b32_e32 v111, v223
	v_fma_f32 v100, v100, v108, v104
	v_fma_f32 v101, v101, v109, v105
	v_or_b32_e32 v108, 28, v130
	v_fma_f32 v102, v102, v110, v106
	v_fmac_f32_e32 v107, v103, v111
	v_cvt_pk_bf16_f32 v100, v100, v101
	v_cvt_pk_bf16_f32 v101, v102, v107
	v_ashrrev_i32_e32 v109, 31, v108
	global_store_dwordx2 v[112:113], v[100:101], off
	v_lshlrev_b64 v[100:101], 12, v[108:109]
	v_lshl_add_u64 v[100:101], s[72:73], 0, v[100:101]
	v_lshl_add_u64 v[100:101], v[100:101], 0, v[128:129]
	s_nop 0
	v_lshlrev_b64 v[108:109], 11, v[108:109]
	v_lshl_add_u64 v[108:109], s[70:71], 0, v[108:109]
	v_lshl_add_u64 v[108:109], v[108:109], 0, v[120:121]
	s_waitcnt vmcnt(7)
	v_mov_b32_e32 v100, v216
	v_mov_b32_e32 v101, v217
	v_mov_b32_e32 v102, v218
	v_mov_b32_e32 v103, v219
	v_mov_b32_e32 v104, v220
	v_mov_b32_e32 v105, v221
	v_mov_b32_e32 v106, v222
	v_mov_b32_e32 v107, v223
	v_fma_f32 v96, v96, v104, v100
	v_fma_f32 v97, v97, v105, v101
	v_or_b32_e32 v104, 32, v130
	v_fma_f32 v98, v98, v106, v102
	v_fmac_f32_e32 v103, v99, v107
	v_cvt_pk_bf16_f32 v96, v96, v97
	v_cvt_pk_bf16_f32 v97, v98, v103
	v_ashrrev_i32_e32 v105, 31, v104
	global_store_dwordx2 v[108:109], v[96:97], off
	v_lshlrev_b64 v[96:97], 12, v[104:105]
	s_waitcnt lgkmcnt(0)
	ds_write2_b32 v132, v72, v76 offset1:16
	ds_write2_b32 v132, v73, v77 offset0:68 offset1:84
	ds_write2_b32 v132, v74, v78 offset0:136 offset1:152
	ds_write2_b32 v132, v75, v79 offset0:204 offset1:220
	ds_write2_b32 v132, v88, v92 offset0:32 offset1:48
	ds_write2_b32 v132, v89, v93 offset0:100 offset1:116
	ds_write2_b32 v132, v90, v94 offset0:168 offset1:184
	ds_write2_b32 v132, v91, v95 offset0:236 offset1:252
	ds_write2_b32 v122, v64, v68 offset0:64 offset1:80
	ds_write2_b32 v122, v65, v69 offset0:132 offset1:148
	ds_write2_b32 v122, v66, v70 offset0:200 offset1:216
	ds_write2_b32 v124, v67, v71 offset0:12 offset1:28
	ds_write2_b32 v122, v80, v84 offset0:96 offset1:112
	ds_write2_b32 v122, v81, v85 offset0:164 offset1:180
	ds_write2_b32 v122, v82, v86 offset0:232 offset1:248
	ds_write2_b32 v124, v83, v87 offset0:44 offset1:60
	v_lshl_add_u64 v[96:97], s[72:73], 0, v[96:97]
	s_waitcnt lgkmcnt(0)
; DI void st4(u16* p, float a, float b, float c, float d) { u32x2 w = {cvtpk(a, b), cvtpk(c, d)}; *(u32x2*)p = w; }
;   DI void operator()(int m, int n, f32x4 v) const { st4(dst + (size_t)m * ld + n, v[0], v[1], v[2], v[3]); }
;   DI void operator()(int m, int n, f32x4 v) const {
;     const f32x4 x = *(const f32x4*)(xin + (size_t)m * 1024 + n), g = *(const f32x4*)(gate + n);
;     st4(out + (size_t)m * 1024 + n, x[0] + g[0] * v[0], x[1] + g[1] * v[1], x[2] + g[2] * v[2], x[3] + g[3] * v[3]);
;   }
	v_lshl_add_u64 v[96:97], v[96:97], 0, v[128:129]
	ds_read_b128 v[92:95], v123
	ds_read_b128 v[88:91], v123 offset:1088
	ds_read_b128 v[84:87], v123 offset:2176
	ds_read_b128 v[80:83], v123 offset:3264
	ds_read_b128 v[76:79], v123 offset:4352
	ds_read_b128 v[72:75], v123 offset:5440
	ds_read_b128 v[68:71], v123 offset:6528
	ds_read_b128 v[64:67], v123 offset:7616
	s_mov_b64 s[74:75], 0x4000
	global_load_dwordx4 v[188:191], v[96:97], off
	v_lshl_add_u64 v[224:225], v[96:97], 0, s[74:75]
	global_load_dwordx4 v[192:195], v[224:225], off
	v_lshl_add_u64 v[224:225], v[224:225], 0, s[74:75]
	global_load_dwordx4 v[196:199], v[224:225], off
	v_lshl_add_u64 v[224:225], v[224:225], 0, s[74:75]
	global_load_dwordx4 v[200:203], v[224:225], off
	v_lshl_add_u64 v[224:225], v[224:225], 0, s[74:75]
	global_load_dwordx4 v[204:207], v[224:225], off
	v_lshl_add_u64 v[224:225], v[224:225], 0, s[74:75]
	global_load_dwordx4 v[208:211], v[224:225], off
	v_lshl_add_u64 v[224:225], v[224:225], 0, s[74:75]
	global_load_dwordx4 v[212:215], v[224:225], off
	v_lshl_add_u64 v[224:225], v[224:225], 0, s[74:75]
	global_load_dwordx4 v[216:219], v[224:225], off
	s_nop 0
	v_lshlrev_b64 v[104:105], 11, v[104:105]
	v_lshl_add_u64 v[104:105], s[70:71], 0, v[104:105]
	v_lshl_add_u64 v[104:105], v[104:105], 0, v[120:121]
	s_waitcnt vmcnt(7) lgkmcnt(7)
	v_mov_b32_e32 v96, v188
	v_mov_b32_e32 v97, v189
	v_mov_b32_e32 v98, v190
	v_mov_b32_e32 v99, v191
	v_mov_b32_e32 v100, v220
	v_mov_b32_e32 v101, v221
	v_mov_b32_e32 v102, v222
	v_mov_b32_e32 v103, v223
	v_fma_f32 v92, v92, v100, v96
	v_fma_f32 v93, v93, v101, v97
	v_or_b32_e32 v100, 36, v130
	v_fma_f32 v94, v94, v102, v98
	v_fmac_f32_e32 v99, v95, v103
	v_cvt_pk_bf16_f32 v92, v92, v93
	v_cvt_pk_bf16_f32 v93, v94, v99
	v_ashrrev_i32_e32 v101, 31, v100
	global_store_dwordx2 v[104:105], v[92:93], off
	v_lshlrev_b64 v[92:93], 12, v[100:101]
	v_lshl_add_u64 v[92:93], s[72:73], 0, v[92:93]
	v_lshl_add_u64 v[92:93], v[92:93], 0, v[128:129]
	s_nop 0
	v_lshlrev_b64 v[100:101], 11, v[100:101]
	v_lshl_add_u64 v[100:101], s[70:71], 0, v[100:101]
	v_lshl_add_u64 v[100:101], v[100:101], 0, v[120:121]
	s_waitcnt vmcnt(7) lgkmcnt(6)
	v_mov_b32_e32 v92, v192
	v_mov_b32_e32 v93, v193
	v_mov_b32_e32 v94, v194
	v_mov_b32_e32 v95, v195
	v_mov_b32_e32 v96, v220
	v_mov_b32_e32 v97, v221
	v_mov_b32_e32 v98, v222
	v_mov_b32_e32 v99, v223
	v_fma_f32 v88, v88, v96, v92
	v_fma_f32 v89, v89, v97, v93
	v_or_b32_e32 v96, 40, v130
	v_fma_f32 v90, v90, v98, v94
	v_fmac_f32_e32 v95, v91, v99
	v_cvt_pk_bf16_f32 v88, v88, v89
	v_cvt_pk_bf16_f32 v89, v90, v95
	v_ashrrev_i32_e32 v97, 31, v96
	global_store_dwordx2 v[100:101], v[88:89], off
	v_lshlrev_b64 v[88:89], 12, v[96:97]
	v_lshl_add_u64 v[88:89], s[72:73], 0, v[88:89]
	v_lshl_add_u64 v[88:89], v[88:89], 0, v[128:129]
	s_nop 0
	v_lshlrev_b64 v[96:97], 11, v[96:97]
	v_lshl_add_u64 v[96:97], s[70:71], 0, v[96:97]
	v_lshl_add_u64 v[96:97], v[96:97], 0, v[120:121]
	s_waitcnt vmcnt(7) lgkmcnt(5)
	v_mov_b32_e32 v88, v196
	v_mov_b32_e32 v89, v197
	v_mov_b32_e32 v90, v198
	v_mov_b32_e32 v91, v199
	v_mov_b32_e32 v92, v220
	v_mov_b32_e32 v93, v221
	v_mov_b32_e32 v94, v222
	v_mov_b32_e32 v95, v223
	v_fma_f32 v84, v84, v92, v88
	v_fma_f32 v85, v85, v93, v89
	v_or_b32_e32 v92, 44, v130
	v_fma_f32 v86, v86, v94, v90
	v_fmac_f32_e32 v91, v87, v95
	v_cvt_pk_bf16_f32 v84, v84, v85
	v_cvt_pk_bf16_f32 v85, v86, v91
	v_ashrrev_i32_e32 v93, 31, v92
	global_store_dwordx2 v[96:97], v[84:85], off
	v_lshlrev_b64 v[84:85], 12, v[92:93]
	v_lshl_add_u64 v[84:85], s[72:73], 0, v[84:85]
	v_lshl_add_u64 v[84:85], v[84:85], 0, v[128:129]
	s_nop 0
	v_lshlrev_b64 v[92:93], 11, v[92:93]
	v_lshl_add_u64 v[92:93], s[70:71], 0, v[92:93]
	v_lshl_add_u64 v[92:93], v[92:93], 0, v[120:121]
	s_waitcnt vmcnt(7) lgkmcnt(4)
	v_mov_b32_e32 v84, v200
	v_mov_b32_e32 v85, v201
	v_mov_b32_e32 v86, v202
	v_mov_b32_e32 v87, v203
	v_mov_b32_e32 v88, v220
	v_mov_b32_e32 v89, v221
	v_mov_b32_e32 v90, v222
	v_mov_b32_e32 v91, v223
	v_fma_f32 v80, v80, v88, v84
	v_fma_f32 v81, v81, v89, v85
	v_or_b32_e32 v88, 48, v130
	v_fma_f32 v82, v82, v90, v86
	v_fmac_f32_e32 v87, v83, v91
	v_cvt_pk_bf16_f32 v80, v80, v81
	v_cvt_pk_bf16_f32 v81, v82, v87
	v_ashrrev_i32_e32 v89, 31, v88
	global_store_dwordx2 v[92:93], v[80:81], off
	v_lshlrev_b64 v[80:81], 12, v[88:89]
	v_lshl_add_u64 v[80:81], s[72:73], 0, v[80:81]
	v_lshl_add_u64 v[80:81], v[80:81], 0, v[128:129]
	s_nop 0
	v_lshlrev_b64 v[88:89], 11, v[88:89]
	v_lshl_add_u64 v[88:89], s[70:71], 0, v[88:89]
	v_lshl_add_u64 v[88:89], v[88:89], 0, v[120:121]
	s_waitcnt vmcnt(7) lgkmcnt(3)
	v_mov_b32_e32 v80, v204
	v_mov_b32_e32 v81, v205
	v_mov_b32_e32 v82, v206
	v_mov_b32_e32 v83, v207
	v_mov_b32_e32 v84, v220
	v_mov_b32_e32 v85, v221
	v_mov_b32_e32 v86, v222
	v_mov_b32_e32 v87, v223
	v_fma_f32 v76, v76, v84, v80
	v_fma_f32 v77, v77, v85, v81
	v_or_b32_e32 v84, 52, v130
	v_fma_f32 v78, v78, v86, v82
	v_fmac_f32_e32 v83, v79, v87
	v_cvt_pk_bf16_f32 v76, v76, v77
	v_cvt_pk_bf16_f32 v77, v78, v83
	v_ashrrev_i32_e32 v85, 31, v84
	global_store_dwordx2 v[88:89], v[76:77], off
	v_lshlrev_b64 v[76:77], 12, v[84:85]
	v_lshl_add_u64 v[76:77], s[72:73], 0, v[76:77]
	v_lshl_add_u64 v[76:77], v[76:77], 0, v[128:129]
	s_nop 0
	v_lshlrev_b64 v[84:85], 11, v[84:85]
	v_lshl_add_u64 v[84:85], s[70:71], 0, v[84:85]
	v_lshl_add_u64 v[84:85], v[84:85], 0, v[120:121]
	s_waitcnt vmcnt(7) lgkmcnt(2)
; DI void st4(u16* p, float a, float b, float c, float d) { u32x2 w = {cvtpk(a, b), cvtpk(c, d)}; *(u32x2*)p = w; }
;   DI void operator()(int m, int n, f32x4 v) const { st4(dst + (size_t)m * ld + n, v[0], v[1], v[2], v[3]); }
;   DI void operator()(int m, int n, f32x4 v) const {
;     const f32x4 x = *(const f32x4*)(xin + (size_t)m * 1024 + n), g = *(const f32x4*)(gate + n);
;     st4(out + (size_t)m * 1024 + n, x[0] + g[0] * v[0], x[1] + g[1] * v[1], x[2] + g[2] * v[2], x[3] + g[3] * v[3]);
;   }
	v_mov_b32_e32 v76, v208
	v_mov_b32_e32 v77, v209
	v_mov_b32_e32 v78, v210
	v_mov_b32_e32 v79, v211
	v_mov_b32_e32 v80, v220
	v_mov_b32_e32 v81, v221
	v_mov_b32_e32 v82, v222
	v_mov_b32_e32 v83, v223
	v_fma_f32 v72, v72, v80, v76
	v_fma_f32 v73, v73, v81, v77
	v_or_b32_e32 v80, 56, v130
	v_fma_f32 v74, v74, v82, v78
	v_fmac_f32_e32 v79, v75, v83
	v_cvt_pk_bf16_f32 v72, v72, v73
	v_cvt_pk_bf16_f32 v73, v74, v79
	v_ashrrev_i32_e32 v81, 31, v80
	global_store_dwordx2 v[84:85], v[72:73], off
	v_lshlrev_b64 v[72:73], 12, v[80:81]
	v_lshl_add_u64 v[72:73], s[72:73], 0, v[72:73]
	v_lshl_add_u64 v[72:73], v[72:73], 0, v[128:129]
	s_nop 0
	v_lshlrev_b64 v[80:81], 11, v[80:81]
	v_lshl_add_u64 v[80:81], s[70:71], 0, v[80:81]
	v_lshl_add_u64 v[80:81], v[80:81], 0, v[120:121]
	s_waitcnt vmcnt(7) lgkmcnt(1)
	v_mov_b32_e32 v72, v212
	v_mov_b32_e32 v73, v213
	v_mov_b32_e32 v74, v214
	v_mov_b32_e32 v75, v215
	v_mov_b32_e32 v76, v220
	v_mov_b32_e32 v77, v221
	v_mov_b32_e32 v78, v222
	v_mov_b32_e32 v79, v223
	v_fma_f32 v68, v68, v76, v72
	v_fma_f32 v69, v69, v77, v73
	v_or_b32_e32 v76, 60, v130
	v_fma_f32 v70, v70, v78, v74
	v_fmac_f32_e32 v75, v71, v79
	v_cvt_pk_bf16_f32 v68, v68, v69
	v_cvt_pk_bf16_f32 v69, v70, v75
	v_ashrrev_i32_e32 v77, 31, v76
	global_store_dwordx2 v[80:81], v[68:69], off
	v_lshlrev_b64 v[68:69], 12, v[76:77]
	v_lshl_add_u64 v[68:69], s[72:73], 0, v[68:69]
	v_lshl_add_u64 v[68:69], v[68:69], 0, v[128:129]
	s_nop 0
	v_lshlrev_b64 v[76:77], 11, v[76:77]
	v_lshl_add_u64 v[76:77], s[70:71], 0, v[76:77]
	v_lshl_add_u64 v[76:77], v[76:77], 0, v[120:121]
	s_waitcnt vmcnt(7) lgkmcnt(0)
	v_mov_b32_e32 v68, v216
	v_mov_b32_e32 v69, v217
	v_mov_b32_e32 v70, v218
	v_mov_b32_e32 v71, v219
	v_mov_b32_e32 v72, v220
	v_mov_b32_e32 v73, v221
	v_mov_b32_e32 v74, v222
	v_mov_b32_e32 v75, v223
	v_fma_f32 v64, v64, v72, v68
	v_fma_f32 v65, v65, v73, v69
	v_add_u32_e32 v72, 0x80, v130
	v_fma_f32 v66, v66, v74, v70
	v_fmac_f32_e32 v71, v67, v75
	v_cvt_pk_bf16_f32 v64, v64, v65
	v_cvt_pk_bf16_f32 v65, v66, v71
	v_ashrrev_i32_e32 v73, 31, v72
	global_store_dwordx2 v[76:77], v[64:65], off
	v_lshlrev_b64 v[64:65], 12, v[72:73]
	s_waitcnt lgkmcnt(0)
	ds_write2_b32 v132, v40, v44 offset1:16
	ds_write2_b32 v132, v41, v45 offset0:68 offset1:84
	ds_write2_b32 v132, v42, v46 offset0:136 offset1:152
	ds_write2_b32 v132, v43, v47 offset0:204 offset1:220
	ds_write2_b32 v132, v56, v60 offset0:32 offset1:48
	ds_write2_b32 v132, v57, v61 offset0:100 offset1:116
	ds_write2_b32 v132, v58, v62 offset0:168 offset1:184
	ds_write2_b32 v132, v59, v63 offset0:236 offset1:252
	ds_write2_b32 v122, v32, v36 offset0:64 offset1:80
	ds_write2_b32 v122, v33, v37 offset0:132 offset1:148
	ds_write2_b32 v122, v34, v38 offset0:200 offset1:216
	ds_write2_b32 v124, v35, v39 offset0:12 offset1:28
	ds_write2_b32 v122, v48, v52 offset0:96 offset1:112
	ds_write2_b32 v122, v49, v53 offset0:164 offset1:180
	ds_write2_b32 v122, v50, v54 offset0:232 offset1:248
	ds_write2_b32 v124, v51, v55 offset0:44 offset1:60
	v_lshl_add_u64 v[64:65], s[72:73], 0, v[64:65]
	s_waitcnt lgkmcnt(0)
	v_lshl_add_u64 v[64:65], v[64:65], 0, v[128:129]
	ds_read_b128 v[60:63], v123
	ds_read_b128 v[56:59], v123 offset:1088
	ds_read_b128 v[52:55], v123 offset:2176
	ds_read_b128 v[48:51], v123 offset:3264
	ds_read_b128 v[44:47], v123 offset:4352
	ds_read_b128 v[40:43], v123 offset:5440
	ds_read_b128 v[36:39], v123 offset:6528
	ds_read_b128 v[32:35], v123 offset:7616
	s_mov_b64 s[74:75], 0x4000
	global_load_dwordx4 v[188:191], v[64:65], off
	v_lshl_add_u64 v[224:225], v[64:65], 0, s[74:75]
	global_load_dwordx4 v[192:195], v[224:225], off
	v_lshl_add_u64 v[224:225], v[224:225], 0, s[74:75]
	global_load_dwordx4 v[196:199], v[224:225], off
	v_lshl_add_u64 v[224:225], v[224:225], 0, s[74:75]
	global_load_dwordx4 v[200:203], v[224:225], off
	v_lshl_add_u64 v[224:225], v[224:225], 0, s[74:75]
	global_load_dwordx4 v[204:207], v[224:225], off
	v_lshl_add_u64 v[224:225], v[224:225], 0, s[74:75]
	global_load_dwordx4 v[208:211], v[224:225], off
	v_lshl_add_u64 v[224:225], v[224:225], 0, s[74:75]
	global_load_dwordx4 v[212:215], v[224:225], off
	v_lshl_add_u64 v[224:225], v[224:225], 0, s[74:75]
	global_load_dwordx4 v[216:219], v[224:225], off
	s_nop 0
	v_lshlrev_b64 v[72:73], 11, v[72:73]
	v_lshl_add_u64 v[72:73], s[70:71], 0, v[72:73]
	v_lshl_add_u64 v[72:73], v[72:73], 0, v[120:121]
	s_waitcnt vmcnt(7) lgkmcnt(7)
	v_mov_b32_e32 v64, v188
	v_mov_b32_e32 v65, v189
	v_mov_b32_e32 v66, v190
	v_mov_b32_e32 v67, v191
	v_mov_b32_e32 v68, v220
	v_mov_b32_e32 v69, v221
	v_mov_b32_e32 v70, v222
	v_mov_b32_e32 v71, v223
	v_fma_f32 v60, v60, v68, v64
	v_fma_f32 v61, v61, v69, v65
	v_add_u32_e32 v68, 0x84, v130
	v_fma_f32 v62, v62, v70, v66
	v_fmac_f32_e32 v67, v63, v71
	v_cvt_pk_bf16_f32 v60, v60, v61
	v_cvt_pk_bf16_f32 v61, v62, v67
	v_ashrrev_i32_e32 v69, 31, v68
	global_store_dwordx2 v[72:73], v[60:61], off
	v_lshlrev_b64 v[60:61], 12, v[68:69]
	v_lshl_add_u64 v[60:61], s[72:73], 0, v[60:61]
	v_lshl_add_u64 v[60:61], v[60:61], 0, v[128:129]
	s_nop 0
	v_lshlrev_b64 v[68:69], 11, v[68:69]
	v_lshl_add_u64 v[68:69], s[70:71], 0, v[68:69]
	v_lshl_add_u64 v[68:69], v[68:69], 0, v[120:121]
	s_waitcnt vmcnt(7) lgkmcnt(6)
	v_mov_b32_e32 v60, v192
	v_mov_b32_e32 v61, v193
	v_mov_b32_e32 v62, v194
	v_mov_b32_e32 v63, v195
	v_mov_b32_e32 v64, v220
	v_mov_b32_e32 v65, v221
	v_mov_b32_e32 v66, v222
	v_mov_b32_e32 v67, v223
	v_fma_f32 v56, v56, v64, v60
	v_fma_f32 v57, v57, v65, v61
	v_add_u32_e32 v64, 0x88, v130
	v_fma_f32 v58, v58, v66, v62
	v_fmac_f32_e32 v63, v59, v67
	v_cvt_pk_bf16_f32 v56, v56, v57
	v_cvt_pk_bf16_f32 v57, v58, v63
	v_ashrrev_i32_e32 v65, 31, v64
	global_store_dwordx2 v[68:69], v[56:57], off
	v_lshlrev_b64 v[56:57], 12, v[64:65]
	v_lshl_add_u64 v[56:57], s[72:73], 0, v[56:57]
	v_lshl_add_u64 v[56:57], v[56:57], 0, v[128:129]
	s_nop 0
	v_lshlrev_b64 v[64:65], 11, v[64:65]
	v_lshl_add_u64 v[64:65], s[70:71], 0, v[64:65]
	v_lshl_add_u64 v[64:65], v[64:65], 0, v[120:121]
	s_waitcnt vmcnt(7) lgkmcnt(5)
; DI void st4(u16* p, float a, float b, float c, float d) { u32x2 w = {cvtpk(a, b), cvtpk(c, d)}; *(u32x2*)p = w; }
;   DI void operator()(int m, int n, f32x4 v) const { st4(dst + (size_t)m * ld + n, v[0], v[1], v[2], v[3]); }
;   DI void operator()(int m, int n, f32x4 v) const {
;     const f32x4 x = *(const f32x4*)(xin + (size_t)m * 1024 + n), g = *(const f32x4*)(gate + n);
;     st4(out + (size_t)m * 1024 + n, x[0] + g[0] * v[0], x[1] + g[1] * v[1], x[2] + g[2] * v[2], x[3] + g[3] * v[3]);
;   }
	v_mov_b32_e32 v56, v196
	v_mov_b32_e32 v57, v197
	v_mov_b32_e32 v58, v198
	v_mov_b32_e32 v59, v199
	v_mov_b32_e32 v60, v220
	v_mov_b32_e32 v61, v221
	v_mov_b32_e32 v62, v222
	v_mov_b32_e32 v63, v223
	v_fma_f32 v52, v52, v60, v56
	v_fma_f32 v53, v53, v61, v57
	v_add_u32_e32 v60, 0x8c, v130
	v_fma_f32 v54, v54, v62, v58
	v_fmac_f32_e32 v59, v55, v63
	v_cvt_pk_bf16_f32 v52, v52, v53
	v_cvt_pk_bf16_f32 v53, v54, v59
	v_ashrrev_i32_e32 v61, 31, v60
	global_store_dwordx2 v[64:65], v[52:53], off
	v_lshlrev_b64 v[52:53], 12, v[60:61]
	v_lshl_add_u64 v[52:53], s[72:73], 0, v[52:53]
	v_lshl_add_u64 v[52:53], v[52:53], 0, v[128:129]
	s_nop 0
	v_lshlrev_b64 v[60:61], 11, v[60:61]
	v_lshl_add_u64 v[60:61], s[70:71], 0, v[60:61]
	v_lshl_add_u64 v[60:61], v[60:61], 0, v[120:121]
	s_waitcnt vmcnt(7) lgkmcnt(4)
	v_mov_b32_e32 v52, v200
	v_mov_b32_e32 v53, v201
	v_mov_b32_e32 v54, v202
	v_mov_b32_e32 v55, v203
	v_mov_b32_e32 v56, v220
	v_mov_b32_e32 v57, v221
	v_mov_b32_e32 v58, v222
	v_mov_b32_e32 v59, v223
	v_fma_f32 v48, v48, v56, v52
	v_fma_f32 v49, v49, v57, v53
	v_add_u32_e32 v56, 0x90, v130
	v_fma_f32 v50, v50, v58, v54
	v_fmac_f32_e32 v55, v51, v59
	v_cvt_pk_bf16_f32 v48, v48, v49
	v_cvt_pk_bf16_f32 v49, v50, v55
	v_ashrrev_i32_e32 v57, 31, v56
	global_store_dwordx2 v[60:61], v[48:49], off
	v_lshlrev_b64 v[48:49], 12, v[56:57]
	v_lshl_add_u64 v[48:49], s[72:73], 0, v[48:49]
	v_lshl_add_u64 v[48:49], v[48:49], 0, v[128:129]
	s_nop 0
	v_lshlrev_b64 v[56:57], 11, v[56:57]
	v_lshl_add_u64 v[56:57], s[70:71], 0, v[56:57]
	v_lshl_add_u64 v[56:57], v[56:57], 0, v[120:121]
	s_waitcnt vmcnt(7) lgkmcnt(3)
	v_mov_b32_e32 v48, v204
	v_mov_b32_e32 v49, v205
	v_mov_b32_e32 v50, v206
	v_mov_b32_e32 v51, v207
	v_mov_b32_e32 v52, v220
	v_mov_b32_e32 v53, v221
	v_mov_b32_e32 v54, v222
	v_mov_b32_e32 v55, v223
	v_fma_f32 v44, v44, v52, v48
	v_fma_f32 v45, v45, v53, v49
	v_add_u32_e32 v52, 0x94, v130
	v_fma_f32 v46, v46, v54, v50
	v_fmac_f32_e32 v51, v47, v55
	v_cvt_pk_bf16_f32 v44, v44, v45
	v_cvt_pk_bf16_f32 v45, v46, v51
	v_ashrrev_i32_e32 v53, 31, v52
	global_store_dwordx2 v[56:57], v[44:45], off
	v_lshlrev_b64 v[44:45], 12, v[52:53]
	v_lshl_add_u64 v[44:45], s[72:73], 0, v[44:45]
	v_lshl_add_u64 v[44:45], v[44:45], 0, v[128:129]
	s_nop 0
	v_lshlrev_b64 v[52:53], 11, v[52:53]
	v_lshl_add_u64 v[52:53], s[70:71], 0, v[52:53]
	v_lshl_add_u64 v[52:53], v[52:53], 0, v[120:121]
	s_waitcnt vmcnt(7) lgkmcnt(2)
	v_mov_b32_e32 v44, v208
	v_mov_b32_e32 v45, v209
	v_mov_b32_e32 v46, v210
	v_mov_b32_e32 v47, v211
	v_mov_b32_e32 v48, v220
	v_mov_b32_e32 v49, v221
	v_mov_b32_e32 v50, v222
	v_mov_b32_e32 v51, v223
	v_fma_f32 v40, v40, v48, v44
	v_fma_f32 v41, v41, v49, v45
	v_add_u32_e32 v48, 0x98, v130
	v_fma_f32 v42, v42, v50, v46
	v_fmac_f32_e32 v47, v43, v51
	v_cvt_pk_bf16_f32 v40, v40, v41
	v_cvt_pk_bf16_f32 v41, v42, v47
	v_ashrrev_i32_e32 v49, 31, v48
	global_store_dwordx2 v[52:53], v[40:41], off
	v_lshlrev_b64 v[40:41], 12, v[48:49]
	v_lshl_add_u64 v[40:41], s[72:73], 0, v[40:41]
	v_lshl_add_u64 v[40:41], v[40:41], 0, v[128:129]
	s_nop 0
	v_lshlrev_b64 v[48:49], 11, v[48:49]
	v_lshl_add_u64 v[48:49], s[70:71], 0, v[48:49]
	v_lshl_add_u64 v[48:49], v[48:49], 0, v[120:121]
	s_waitcnt vmcnt(7) lgkmcnt(1)
	v_mov_b32_e32 v40, v212
	v_mov_b32_e32 v41, v213
	v_mov_b32_e32 v42, v214
	v_mov_b32_e32 v43, v215
	v_mov_b32_e32 v44, v220
	v_mov_b32_e32 v45, v221
	v_mov_b32_e32 v46, v222
	v_mov_b32_e32 v47, v223
	v_fma_f32 v36, v36, v44, v40
	v_fma_f32 v37, v37, v45, v41
	v_add_u32_e32 v44, 0x9c, v130
	v_fma_f32 v38, v38, v46, v42
	v_fmac_f32_e32 v43, v39, v47
	v_cvt_pk_bf16_f32 v36, v36, v37
	v_cvt_pk_bf16_f32 v37, v38, v43
	v_ashrrev_i32_e32 v45, 31, v44
	global_store_dwordx2 v[48:49], v[36:37], off
	v_lshlrev_b64 v[36:37], 12, v[44:45]
	v_lshl_add_u64 v[36:37], s[72:73], 0, v[36:37]
	v_lshl_add_u64 v[36:37], v[36:37], 0, v[128:129]
	s_nop 0
	v_lshlrev_b64 v[44:45], 11, v[44:45]
	v_lshl_add_u64 v[44:45], s[70:71], 0, v[44:45]
	v_lshl_add_u64 v[44:45], v[44:45], 0, v[120:121]
	s_waitcnt vmcnt(7) lgkmcnt(0)
	v_mov_b32_e32 v36, v216
	v_mov_b32_e32 v37, v217
	v_mov_b32_e32 v38, v218
	v_mov_b32_e32 v39, v219
	v_mov_b32_e32 v40, v220
	v_mov_b32_e32 v41, v221
	v_mov_b32_e32 v42, v222
	v_mov_b32_e32 v43, v223
	v_fma_f32 v32, v32, v40, v36
	v_fma_f32 v33, v33, v41, v37
	v_add_u32_e32 v40, 0xa0, v130
	v_fma_f32 v34, v34, v42, v38
	v_fmac_f32_e32 v39, v35, v43
	v_cvt_pk_bf16_f32 v32, v32, v33
	v_cvt_pk_bf16_f32 v33, v34, v39
	v_ashrrev_i32_e32 v41, 31, v40
	global_store_dwordx2 v[44:45], v[32:33], off
	v_lshlrev_b64 v[32:33], 12, v[40:41]
	s_waitcnt lgkmcnt(0)
	ds_write2_b32 v132, v8, v12 offset1:16
	ds_write2_b32 v132, v9, v13 offset0:68 offset1:84
	ds_write2_b32 v132, v10, v14 offset0:136 offset1:152
	ds_write2_b32 v132, v11, v15 offset0:204 offset1:220
	ds_write2_b32 v132, v24, v28 offset0:32 offset1:48
	ds_write2_b32 v132, v25, v29 offset0:100 offset1:116
	ds_write2_b32 v132, v26, v30 offset0:168 offset1:184
	ds_write2_b32 v132, v27, v31 offset0:236 offset1:252
	ds_write2_b32 v122, v0, v4 offset0:64 offset1:80
	ds_write2_b32 v122, v1, v5 offset0:132 offset1:148
	ds_write2_b32 v122, v2, v6 offset0:200 offset1:216
	ds_write2_b32 v124, v3, v7 offset0:12 offset1:28
	ds_write2_b32 v122, v16, v20 offset0:96 offset1:112
	ds_write2_b32 v122, v17, v21 offset0:164 offset1:180
	ds_write2_b32 v122, v18, v22 offset0:232 offset1:248
	ds_write2_b32 v124, v19, v23 offset0:44 offset1:60
	v_lshl_add_u64 v[32:33], s[72:73], 0, v[32:33]
	s_waitcnt lgkmcnt(0)
; DI void st4(u16* p, float a, float b, float c, float d) { u32x2 w = {cvtpk(a, b), cvtpk(c, d)}; *(u32x2*)p = w; }
;   DI void operator()(int m, int n, f32x4 v) const { st4(dst + (size_t)m * ld + n, v[0], v[1], v[2], v[3]); }
;   DI void operator()(int m, int n, f32x4 v) const {
;     const f32x4 x = *(const f32x4*)(xin + (size_t)m * 1024 + n), g = *(const f32x4*)(gate + n);
;     st4(out + (size_t)m * 1024 + n, x[0] + g[0] * v[0], x[1] + g[1] * v[1], x[2] + g[2] * v[2], x[3] + g[3] * v[3]);
;   }
	v_lshl_add_u64 v[32:33], v[32:33], 0, v[128:129]
	ds_read_b128 v[28:31], v123
	ds_read_b128 v[24:27], v123 offset:1088
	ds_read_b128 v[20:23], v123 offset:2176
	ds_read_b128 v[16:19], v123 offset:3264
	ds_read_b128 v[12:15], v123 offset:4352
	ds_read_b128 v[8:11], v123 offset:5440
	ds_read_b128 v[4:7], v123 offset:6528
	ds_read_b128 v[0:3], v123 offset:7616
	s_mov_b64 s[74:75], 0x4000
	global_load_dwordx4 v[188:191], v[32:33], off
	v_lshl_add_u64 v[224:225], v[32:33], 0, s[74:75]
	global_load_dwordx4 v[192:195], v[224:225], off
	v_lshl_add_u64 v[224:225], v[224:225], 0, s[74:75]
	global_load_dwordx4 v[196:199], v[224:225], off
	v_lshl_add_u64 v[224:225], v[224:225], 0, s[74:75]
	global_load_dwordx4 v[200:203], v[224:225], off
	v_lshl_add_u64 v[224:225], v[224:225], 0, s[74:75]
	global_load_dwordx4 v[204:207], v[224:225], off
	v_lshl_add_u64 v[224:225], v[224:225], 0, s[74:75]
	global_load_dwordx4 v[208:211], v[224:225], off
	v_lshl_add_u64 v[224:225], v[224:225], 0, s[74:75]
	global_load_dwordx4 v[212:215], v[224:225], off
	v_lshl_add_u64 v[224:225], v[224:225], 0, s[74:75]
	global_load_dwordx4 v[216:219], v[224:225], off
	s_nop 0
	v_lshlrev_b64 v[40:41], 11, v[40:41]
	v_lshl_add_u64 v[40:41], s[70:71], 0, v[40:41]
	v_lshl_add_u64 v[40:41], v[40:41], 0, v[120:121]
	s_waitcnt vmcnt(7) lgkmcnt(7)
	v_mov_b32_e32 v32, v188
	v_mov_b32_e32 v33, v189
	v_mov_b32_e32 v34, v190
	v_mov_b32_e32 v35, v191
	v_mov_b32_e32 v36, v220
	v_mov_b32_e32 v37, v221
	v_mov_b32_e32 v38, v222
	v_mov_b32_e32 v39, v223
	v_fma_f32 v28, v28, v36, v32
	v_fma_f32 v29, v29, v37, v33
	v_add_u32_e32 v36, 0xa4, v130
	v_fma_f32 v30, v30, v38, v34
	v_fmac_f32_e32 v35, v31, v39
	v_cvt_pk_bf16_f32 v28, v28, v29
	v_cvt_pk_bf16_f32 v29, v30, v35
	v_ashrrev_i32_e32 v37, 31, v36
	global_store_dwordx2 v[40:41], v[28:29], off
	v_lshlrev_b64 v[28:29], 12, v[36:37]
	v_lshl_add_u64 v[28:29], s[72:73], 0, v[28:29]
	v_lshl_add_u64 v[28:29], v[28:29], 0, v[128:129]
	s_nop 0
	v_lshlrev_b64 v[36:37], 11, v[36:37]
	v_lshl_add_u64 v[36:37], s[70:71], 0, v[36:37]
	v_lshl_add_u64 v[36:37], v[36:37], 0, v[120:121]
	s_waitcnt vmcnt(7) lgkmcnt(6)
	v_mov_b32_e32 v28, v192
	v_mov_b32_e32 v29, v193
	v_mov_b32_e32 v30, v194
	v_mov_b32_e32 v31, v195
	v_mov_b32_e32 v32, v220
	v_mov_b32_e32 v33, v221
	v_mov_b32_e32 v34, v222
	v_mov_b32_e32 v35, v223
	v_fma_f32 v24, v24, v32, v28
	v_fma_f32 v25, v25, v33, v29
	v_add_u32_e32 v32, 0xa8, v130
	v_fma_f32 v26, v26, v34, v30
	v_fmac_f32_e32 v31, v27, v35
	v_cvt_pk_bf16_f32 v24, v24, v25
	v_cvt_pk_bf16_f32 v25, v26, v31
	v_ashrrev_i32_e32 v33, 31, v32
	global_store_dwordx2 v[36:37], v[24:25], off
	v_lshlrev_b64 v[24:25], 12, v[32:33]
	v_lshl_add_u64 v[24:25], s[72:73], 0, v[24:25]
	v_lshl_add_u64 v[24:25], v[24:25], 0, v[128:129]
	s_nop 0
	v_lshlrev_b64 v[32:33], 11, v[32:33]
	v_lshl_add_u64 v[32:33], s[70:71], 0, v[32:33]
	v_lshl_add_u64 v[32:33], v[32:33], 0, v[120:121]
	s_waitcnt vmcnt(7) lgkmcnt(5)
	v_mov_b32_e32 v24, v196
	v_mov_b32_e32 v25, v197
	v_mov_b32_e32 v26, v198
	v_mov_b32_e32 v27, v199
	v_mov_b32_e32 v28, v220
	v_mov_b32_e32 v29, v221
	v_mov_b32_e32 v30, v222
	v_mov_b32_e32 v31, v223
	v_fma_f32 v20, v20, v28, v24
	v_fma_f32 v21, v21, v29, v25
	v_add_u32_e32 v28, 0xac, v130
	v_fma_f32 v22, v22, v30, v26
	v_fmac_f32_e32 v27, v23, v31
	v_cvt_pk_bf16_f32 v20, v20, v21
	v_cvt_pk_bf16_f32 v21, v22, v27
	v_ashrrev_i32_e32 v29, 31, v28
	global_store_dwordx2 v[32:33], v[20:21], off
	v_lshlrev_b64 v[20:21], 12, v[28:29]
	v_lshl_add_u64 v[20:21], s[72:73], 0, v[20:21]
	v_lshl_add_u64 v[20:21], v[20:21], 0, v[128:129]
	s_nop 0
	v_lshlrev_b64 v[28:29], 11, v[28:29]
	v_lshl_add_u64 v[28:29], s[70:71], 0, v[28:29]
	v_lshl_add_u64 v[28:29], v[28:29], 0, v[120:121]
	s_waitcnt vmcnt(7) lgkmcnt(4)
; DI void st4(u16* p, float a, float b, float c, float d) { u32x2 w = {cvtpk(a, b), cvtpk(c, d)}; *(u32x2*)p = w; }
;   DI void operator()(int m, int n, f32x4 v) const { st4(dst + (size_t)m * ld + n, v[0], v[1], v[2], v[3]); }
;   DI void operator()(int m, int n, f32x4 v) const {
;     const f32x4 x = *(const f32x4*)(xin + (size_t)m * 1024 + n), g = *(const f32x4*)(gate + n);
;     st4(out + (size_t)m * 1024 + n, x[0] + g[0] * v[0], x[1] + g[1] * v[1], x[2] + g[2] * v[2], x[3] + g[3] * v[3]);
;   }
	v_mov_b32_e32 v20, v200
	v_mov_b32_e32 v21, v201
	v_mov_b32_e32 v22, v202
	v_mov_b32_e32 v23, v203
	v_mov_b32_e32 v24, v220
	v_mov_b32_e32 v25, v221
	v_mov_b32_e32 v26, v222
	v_mov_b32_e32 v27, v223
	v_fma_f32 v16, v16, v24, v20
	v_fma_f32 v17, v17, v25, v21
	v_add_u32_e32 v24, 0xb0, v130
	v_fma_f32 v18, v18, v26, v22
	v_fmac_f32_e32 v23, v19, v27
	v_cvt_pk_bf16_f32 v16, v16, v17
	v_cvt_pk_bf16_f32 v17, v18, v23
	v_ashrrev_i32_e32 v25, 31, v24
	global_store_dwordx2 v[28:29], v[16:17], off
	v_lshlrev_b64 v[16:17], 12, v[24:25]
	v_lshl_add_u64 v[16:17], s[72:73], 0, v[16:17]
	v_lshl_add_u64 v[16:17], v[16:17], 0, v[128:129]
	s_nop 0
	v_lshlrev_b64 v[24:25], 11, v[24:25]
	v_lshl_add_u64 v[24:25], s[70:71], 0, v[24:25]
	v_lshl_add_u64 v[24:25], v[24:25], 0, v[120:121]
	s_waitcnt vmcnt(7) lgkmcnt(3)
	v_mov_b32_e32 v16, v204
	v_mov_b32_e32 v17, v205
	v_mov_b32_e32 v18, v206
	v_mov_b32_e32 v19, v207
	v_mov_b32_e32 v20, v220
	v_mov_b32_e32 v21, v221
	v_mov_b32_e32 v22, v222
	v_mov_b32_e32 v23, v223
	v_fma_f32 v12, v12, v20, v16
	v_fma_f32 v13, v13, v21, v17
	v_add_u32_e32 v20, 0xb4, v130
	v_fma_f32 v14, v14, v22, v18
	v_fmac_f32_e32 v19, v15, v23
	v_cvt_pk_bf16_f32 v12, v12, v13
	v_cvt_pk_bf16_f32 v13, v14, v19
	v_ashrrev_i32_e32 v21, 31, v20
	global_store_dwordx2 v[24:25], v[12:13], off
	v_lshlrev_b64 v[12:13], 12, v[20:21]
	v_lshl_add_u64 v[12:13], s[72:73], 0, v[12:13]
	v_lshl_add_u64 v[12:13], v[12:13], 0, v[128:129]
	s_nop 0
	v_lshlrev_b64 v[20:21], 11, v[20:21]
	v_lshl_add_u64 v[20:21], s[70:71], 0, v[20:21]
	v_lshl_add_u64 v[20:21], v[20:21], 0, v[120:121]
	s_waitcnt vmcnt(7) lgkmcnt(2)
	v_mov_b32_e32 v12, v208
	v_mov_b32_e32 v13, v209
	v_mov_b32_e32 v14, v210
	v_mov_b32_e32 v15, v211
	v_mov_b32_e32 v16, v220
	v_mov_b32_e32 v17, v221
	v_mov_b32_e32 v18, v222
	v_mov_b32_e32 v19, v223
	v_fma_f32 v8, v8, v16, v12
	v_fma_f32 v9, v9, v17, v13
	v_add_u32_e32 v16, 0xb8, v130
	v_fma_f32 v10, v10, v18, v14
	v_fmac_f32_e32 v15, v11, v19
	v_cvt_pk_bf16_f32 v8, v8, v9
	v_cvt_pk_bf16_f32 v9, v10, v15
	v_ashrrev_i32_e32 v17, 31, v16
	global_store_dwordx2 v[20:21], v[8:9], off
	v_lshlrev_b64 v[8:9], 12, v[16:17]
	v_lshl_add_u64 v[8:9], s[72:73], 0, v[8:9]
	v_lshl_add_u64 v[8:9], v[8:9], 0, v[128:129]
	s_nop 0
	v_lshlrev_b64 v[16:17], 11, v[16:17]
	v_lshl_add_u64 v[16:17], s[70:71], 0, v[16:17]
	v_lshl_add_u64 v[16:17], v[16:17], 0, v[120:121]
	s_waitcnt vmcnt(7) lgkmcnt(1)
	v_mov_b32_e32 v8, v212
	v_mov_b32_e32 v9, v213
	v_mov_b32_e32 v10, v214
	v_mov_b32_e32 v11, v215
	v_mov_b32_e32 v12, v220
	v_mov_b32_e32 v13, v221
	v_mov_b32_e32 v14, v222
	v_mov_b32_e32 v15, v223
	v_fma_f32 v4, v4, v12, v8
	v_fma_f32 v5, v5, v13, v9
	v_add_u32_e32 v12, 0xbc, v130
	v_fma_f32 v6, v6, v14, v10
	v_fmac_f32_e32 v11, v7, v15
	v_cvt_pk_bf16_f32 v4, v4, v5
	v_cvt_pk_bf16_f32 v5, v6, v11
	v_ashrrev_i32_e32 v13, 31, v12
	global_store_dwordx2 v[16:17], v[4:5], off
	v_lshlrev_b64 v[4:5], 12, v[12:13]
	v_lshl_add_u64 v[4:5], s[72:73], 0, v[4:5]
	v_lshl_add_u64 v[4:5], v[4:5], 0, v[128:129]
	s_nop 0
	v_lshlrev_b64 v[12:13], 11, v[12:13]
	v_lshl_add_u64 v[12:13], s[70:71], 0, v[12:13]
	v_lshl_add_u64 v[12:13], v[12:13], 0, v[120:121]
	s_cselect_b64 s[68:69], -1, 0
	s_waitcnt vmcnt(7) lgkmcnt(0)
	v_mov_b32_e32 v4, v216
	v_mov_b32_e32 v5, v217
	v_mov_b32_e32 v6, v218
	v_mov_b32_e32 v7, v219
	v_mov_b32_e32 v8, v220
	v_mov_b32_e32 v9, v221
	v_mov_b32_e32 v10, v222
	v_mov_b32_e32 v11, v223
	v_fma_f32 v0, v0, v8, v4
	v_fma_f32 v1, v1, v9, v5
	v_fma_f32 v2, v2, v10, v6
	v_fmac_f32_e32 v7, v3, v11
	v_cvt_pk_bf16_f32 v0, v0, v1
	v_cvt_pk_bf16_f32 v1, v2, v7
	global_store_dwordx2 v[12:13], v[0:1], off
	v_cndmask_b32_e64 v0, 0, 1, s[26:27]
	v_cndmask_b32_e64 v1, 0, 1, s[68:69]
	v_cndmask_b32_e64 v0, v1, v0, s[6:7]
	s_waitcnt lgkmcnt(0)
	v_and_b32_e32 v0, 1, v0
	v_cmp_eq_u32_e32 vcc, 1, v0
	s_barrier
	s_cbranch_vccz .LBB0_645

; DI void st4(u16* p, float a, float b, float c, float d) { u32x2 w = {cvtpk(a, b), cvtpk(c, d)}; *(u32x2*)p = w; }
;   DI void operator()(int m, int n, f32x4 v) const { st4(dst + (size_t)m * ld + n, v[0], v[1], v[2], v[3]); }
; DI void ld4bf(const u16* p, float* o) { const u32x2 w = *(const u32x2*)p; o[0] = __uint_as_float(w[0] << 16); o[1] = __uint_as_float(w[0] & 0xffff0000u); o[2] = __uint_as_float(w[1] << 16); o[3] = __uint_as_float(w[1] & 0xffff0000u); }
;   DI void operator()(int m, int n, f32x4 v) const {
;     float x[4]; ld4bf(xb + (size_t)m * 1024 + n, x);
;     const f32x4 g = *(const f32x4*)(gate + n);
;     st4(xb + (size_t)m * 1024 + n, x[0] + g[0] * v[0], x[1] + g[1] * v[1], x[2] + g[2] * v[2], x[3] + g[3] * v[3]);
;   }
.LBB0_902:
	s_or_b64 exec, exec, s[10:11]
	s_ashr_i32 s10, s12, 4
	s_add_i32 s10, s10, s0
	s_mul_hi_i32 s11, s10, 0x6000
	s_mulk_i32 s10, 0x6000
	s_add_u32 s10, s16, s10
	s_addc_u32 s11, s17, s11
	s_lshl_b32 s26, s33, 2
	s_add_u32 s10, s10, s26
	s_addc_u32 s11, s11, 0
	s_lshl_b64 s[12:13], s[12:13], 19
	s_add_u32 s12, s18, s12
	s_addc_u32 s13, s19, s13
	s_lshl_b32 s26, s33, 1
	s_add_u32 s12, s12, s26
	v_cmp_gt_i32_e32 vcc, 3, v136
	s_movk_i32 s26, 0x2200
	v_mul_lo_u32 v128, v136, s26
	v_cndmask_b32_e32 v130, v143, v144, vcc
	v_lshlrev_b32_e32 v131, 4, v134
	v_add3_u32 v128, 16, v128, v130
	v_and_b32_e32 v130, 0x80, v131
	v_lshlrev_b32_e32 v132, 5, v135
	v_and_b32_e32 v135, 28, v137
	v_or3_b32 v146, v130, v132, v135
	v_lshlrev_b32_e32 v132, 2, v134
	v_mul_u32_u24_e32 v134, 0x440, v133
	v_add3_u32 v132, v128, v132, v134
	ds_write2_b32 v132, v104, v108 offset1:16
	ds_write2_b32 v132, v105, v109 offset0:68 offset1:84
	ds_write2_b32 v132, v106, v110 offset0:136 offset1:152
	ds_write2_b32 v132, v107, v111 offset0:204 offset1:220
	ds_write2_b32 v132, v120, v124 offset0:32 offset1:48
	ds_write2_b32 v132, v121, v125 offset0:100 offset1:116
	ds_write2_b32 v132, v122, v126 offset0:168 offset1:184
	ds_write2_b32 v132, v123, v127 offset0:236 offset1:252
	v_add_u32_e32 v123, 0x1000, v132
	v_or_b32_e32 v130, v160, v133
	ds_write2_b32 v123, v96, v100 offset0:64 offset1:80
	ds_write2_b32 v123, v97, v101 offset0:132 offset1:148
	ds_write2_b32 v123, v98, v102 offset0:200 offset1:216
	v_mul_u32_u24_e32 v96, 0x110, v133
	v_add3_u32 v124, v128, v131, v96
	v_ashrrev_i32_e32 v131, 31, v130
	s_addc_u32 s13, s13, 0
	v_add_u32_e32 v125, 0x1400, v132
	v_lshlrev_b64 v[120:121], 11, v[130:131]
	ds_write2_b32 v125, v99, v103 offset0:12 offset1:28
	ds_write2_b32 v123, v112, v116 offset0:96 offset1:112
	ds_write2_b32 v123, v113, v117 offset0:164 offset1:180
	ds_write2_b32 v123, v114, v118 offset0:232 offset1:248
	ds_write2_b32 v125, v115, v119 offset0:44 offset1:60
	v_lshl_add_u64 v[120:121], s[12:13], 0, v[120:121]
	v_lshlrev_b32_e32 v128, 1, v146
	s_waitcnt lgkmcnt(0)
	v_lshl_add_u64 v[120:121], v[120:121], 0, v[128:129]
	ds_read_b128 v[134:137], v124
	ds_read_b128 v[138:141], v124 offset:1088
	ds_read_b128 v[116:119], v124 offset:2176
	ds_read_b128 v[112:115], v124 offset:3264
	ds_read_b128 v[108:111], v124 offset:4352
	ds_read_b128 v[104:107], v124 offset:5440
	ds_read_b128 v[100:103], v124 offset:6528
	ds_read_b128 v[96:99], v124 offset:7616
	s_mov_b64 s[26:27], 0x2000
	global_load_dwordx2 v[190:191], v[120:121], off
	v_lshl_add_u64 v[206:207], v[120:121], 0, s[26:27]
	global_load_dwordx2 v[192:193], v[206:207], off
	v_lshl_add_u64 v[206:207], v[206:207], 0, s[26:27]
	global_load_dwordx2 v[194:195], v[206:207], off
	v_lshl_add_u64 v[206:207], v[206:207], 0, s[26:27]
	global_load_dwordx2 v[196:197], v[206:207], off
	v_lshl_add_u64 v[206:207], v[206:207], 0, s[26:27]
	global_load_dwordx2 v[198:199], v[206:207], off
	v_lshl_add_u64 v[206:207], v[206:207], 0, s[26:27]
	global_load_dwordx2 v[200:201], v[206:207], off
	v_lshl_add_u64 v[206:207], v[206:207], 0, s[26:27]
	global_load_dwordx2 v[202:203], v[206:207], off
	v_lshl_add_u64 v[206:207], v[206:207], 0, s[26:27]
	global_load_dwordx2 v[204:205], v[206:207], off
	v_lshlrev_b32_e32 v122, 2, v146
	global_load_dwordx4 v[208:211], v122, s[10:11]
	s_add_i32 s2, s2, s3
	s_waitcnt vmcnt(0)
	v_mov_b32_e32 v126, v190
	v_mov_b32_e32 v127, v191
	v_mov_b32_e32 v146, v208
	v_mov_b32_e32 v147, v209
	v_mov_b32_e32 v148, v210
	v_mov_b32_e32 v149, v211
	v_lshlrev_b32_e32 v131, 16, v126
	v_and_b32_e32 v126, 0xffff0000, v126
	v_lshlrev_b32_e32 v133, 16, v127
	v_and_b32_e32 v127, 0xffff0000, v127
	s_waitcnt lgkmcnt(7)
	v_fmac_f32_e32 v126, v135, v147
	v_fmac_f32_e32 v131, v134, v146
	v_fmac_f32_e32 v127, v137, v149
	v_cvt_pk_bf16_f32 v126, v131, v126
	v_fmac_f32_e32 v133, v136, v148
	v_cvt_pk_bf16_f32 v127, v133, v127
	global_store_dwordx2 v[120:121], v[126:127], off
	v_or_b32_e32 v126, 4, v130
	v_ashrrev_i32_e32 v127, 31, v126
	v_lshlrev_b64 v[126:127], 11, v[126:127]
	v_lshl_add_u64 v[126:127], s[12:13], 0, v[126:127]
	v_lshl_add_u64 v[126:127], v[126:127], 0, v[128:129]
	s_waitcnt vmcnt(7)
	v_mov_b32_e32 v134, v192
	v_mov_b32_e32 v135, v193
	v_lshlrev_b32_e32 v131, 16, v134
	v_and_b32_e32 v133, 0xffff0000, v134
	v_lshlrev_b32_e32 v146, 16, v135
	v_and_b32_e32 v147, 0xffff0000, v135
	s_waitcnt vmcnt(7) lgkmcnt(6)
	v_mov_b32_e32 v134, v208
	v_mov_b32_e32 v135, v209
	v_mov_b32_e32 v136, v210
	v_mov_b32_e32 v137, v211
	v_fmac_f32_e32 v131, v138, v134
	v_fmac_f32_e32 v133, v139, v135
	v_fmac_f32_e32 v146, v140, v136
	v_fmac_f32_e32 v147, v141, v137
	v_cvt_pk_bf16_f32 v134, v131, v133
	v_cvt_pk_bf16_f32 v135, v146, v147
	global_store_dwordx2 v[126:127], v[134:135], off
	v_or_b32_e32 v126, 8, v130
	v_ashrrev_i32_e32 v127, 31, v126
	v_lshlrev_b64 v[126:127], 11, v[126:127]
	v_lshl_add_u64 v[126:127], s[12:13], 0, v[126:127]
	v_lshl_add_u64 v[126:127], v[126:127], 0, v[128:129]
	s_waitcnt vmcnt(7)
	v_mov_b32_e32 v134, v194
	v_mov_b32_e32 v135, v195
	v_lshlrev_b32_e32 v131, 16, v134
	v_and_b32_e32 v133, 0xffff0000, v134
	v_lshlrev_b32_e32 v138, 16, v135
	v_and_b32_e32 v139, 0xffff0000, v135
	s_waitcnt vmcnt(7) lgkmcnt(5)
	v_mov_b32_e32 v134, v208
	v_mov_b32_e32 v135, v209
	v_mov_b32_e32 v136, v210
	v_mov_b32_e32 v137, v211
	v_fmac_f32_e32 v131, v116, v134
	v_fmac_f32_e32 v133, v117, v135
	v_cvt_pk_bf16_f32 v116, v131, v133
	v_fmac_f32_e32 v138, v118, v136
	v_fmac_f32_e32 v139, v119, v137
	v_cvt_pk_bf16_f32 v117, v138, v139
	global_store_dwordx2 v[126:127], v[116:117], off
	v_or_b32_e32 v116, 12, v130
	v_ashrrev_i32_e32 v117, 31, v116
	v_lshlrev_b64 v[116:117], 11, v[116:117]
	v_lshl_add_u64 v[116:117], s[12:13], 0, v[116:117]
	v_lshl_add_u64 v[126:127], v[116:117], 0, v[128:129]
	s_waitcnt vmcnt(7)
; DI void st4(u16* p, float a, float b, float c, float d) { u32x2 w = {cvtpk(a, b), cvtpk(c, d)}; *(u32x2*)p = w; }
;   DI void operator()(int m, int n, f32x4 v) const { st4(dst + (size_t)m * ld + n, v[0], v[1], v[2], v[3]); }
; DI void ld4bf(const u16* p, float* o) { const u32x2 w = *(const u32x2*)p; o[0] = __uint_as_float(w[0] << 16); o[1] = __uint_as_float(w[0] & 0xffff0000u); o[2] = __uint_as_float(w[1] << 16); o[3] = __uint_as_float(w[1] & 0xffff0000u); }
;   DI void operator()(int m, int n, f32x4 v) const {
;     float x[4]; ld4bf(xb + (size_t)m * 1024 + n, x);
;     const f32x4 g = *(const f32x4*)(gate + n);
;     st4(xb + (size_t)m * 1024 + n, x[0] + g[0] * v[0], x[1] + g[1] * v[1], x[2] + g[2] * v[2], x[3] + g[3] * v[3]);
;   }
	v_mov_b32_e32 v116, v196
	v_mov_b32_e32 v117, v197
	v_lshlrev_b32_e32 v131, 16, v116
	v_and_b32_e32 v133, 0xffff0000, v116
	v_lshlrev_b32_e32 v134, 16, v117
	v_and_b32_e32 v135, 0xffff0000, v117
	s_waitcnt vmcnt(7) lgkmcnt(4)
	v_mov_b32_e32 v116, v208
	v_mov_b32_e32 v117, v209
	v_mov_b32_e32 v118, v210
	v_mov_b32_e32 v119, v211
	v_fmac_f32_e32 v131, v112, v116
	v_fmac_f32_e32 v133, v113, v117
	v_cvt_pk_bf16_f32 v112, v131, v133
	v_fmac_f32_e32 v134, v114, v118
	v_fmac_f32_e32 v135, v115, v119
	v_cvt_pk_bf16_f32 v113, v134, v135
	global_store_dwordx2 v[126:127], v[112:113], off
	v_or_b32_e32 v112, 16, v130
	v_ashrrev_i32_e32 v113, 31, v112
	v_lshlrev_b64 v[112:113], 11, v[112:113]
	v_lshl_add_u64 v[112:113], s[12:13], 0, v[112:113]
	v_lshl_add_u64 v[116:117], v[112:113], 0, v[128:129]
	s_waitcnt vmcnt(7)
	v_mov_b32_e32 v112, v198
	v_mov_b32_e32 v113, v199
	v_lshlrev_b32_e32 v118, 16, v112
	v_and_b32_e32 v119, 0xffff0000, v112
	v_lshlrev_b32_e32 v126, 16, v113
	v_and_b32_e32 v127, 0xffff0000, v113
	s_waitcnt vmcnt(7) lgkmcnt(3)
	v_mov_b32_e32 v112, v208
	v_mov_b32_e32 v113, v209
	v_mov_b32_e32 v114, v210
	v_mov_b32_e32 v115, v211
	v_fmac_f32_e32 v118, v108, v112
	v_fmac_f32_e32 v119, v109, v113
	v_cvt_pk_bf16_f32 v108, v118, v119
	v_fmac_f32_e32 v126, v110, v114
	v_fmac_f32_e32 v127, v111, v115
	v_cvt_pk_bf16_f32 v109, v126, v127
	global_store_dwordx2 v[116:117], v[108:109], off
	v_or_b32_e32 v108, 20, v130
	v_ashrrev_i32_e32 v109, 31, v108
	v_lshlrev_b64 v[108:109], 11, v[108:109]
	v_lshl_add_u64 v[108:109], s[12:13], 0, v[108:109]
	v_lshl_add_u64 v[112:113], v[108:109], 0, v[128:129]
	s_waitcnt vmcnt(7)
	v_mov_b32_e32 v108, v200
	v_mov_b32_e32 v109, v201
	v_lshlrev_b32_e32 v114, 16, v108
	v_and_b32_e32 v115, 0xffff0000, v108
	v_lshlrev_b32_e32 v116, 16, v109
	v_and_b32_e32 v117, 0xffff0000, v109
	s_waitcnt vmcnt(7) lgkmcnt(2)
	v_mov_b32_e32 v108, v208
	v_mov_b32_e32 v109, v209
	v_mov_b32_e32 v110, v210
	v_mov_b32_e32 v111, v211
	v_fmac_f32_e32 v114, v104, v108
	v_fmac_f32_e32 v115, v105, v109
	v_cvt_pk_bf16_f32 v104, v114, v115
	v_fmac_f32_e32 v116, v106, v110
	v_fmac_f32_e32 v117, v107, v111
	v_cvt_pk_bf16_f32 v105, v116, v117
	global_store_dwordx2 v[112:113], v[104:105], off
	v_or_b32_e32 v104, 24, v130
	v_ashrrev_i32_e32 v105, 31, v104
	v_lshlrev_b64 v[104:105], 11, v[104:105]
	v_lshl_add_u64 v[104:105], s[12:13], 0, v[104:105]
	v_lshl_add_u64 v[108:109], v[104:105], 0, v[128:129]
	s_waitcnt vmcnt(7)
	v_mov_b32_e32 v104, v202
	v_mov_b32_e32 v105, v203
	v_lshlrev_b32_e32 v110, 16, v104
	v_and_b32_e32 v111, 0xffff0000, v104
	v_lshlrev_b32_e32 v112, 16, v105
	v_and_b32_e32 v113, 0xffff0000, v105
	s_waitcnt vmcnt(7) lgkmcnt(1)
	v_mov_b32_e32 v104, v208
	v_mov_b32_e32 v105, v209
	v_mov_b32_e32 v106, v210
	v_mov_b32_e32 v107, v211
	v_fmac_f32_e32 v110, v100, v104
	v_fmac_f32_e32 v111, v101, v105
	v_cvt_pk_bf16_f32 v100, v110, v111
	v_fmac_f32_e32 v112, v102, v106
	v_fmac_f32_e32 v113, v103, v107
	v_cvt_pk_bf16_f32 v101, v112, v113
	global_store_dwordx2 v[108:109], v[100:101], off
	v_or_b32_e32 v100, 28, v130
	v_ashrrev_i32_e32 v101, 31, v100
	v_lshlrev_b64 v[100:101], 11, v[100:101]
	v_lshl_add_u64 v[100:101], s[12:13], 0, v[100:101]
	v_lshl_add_u64 v[104:105], v[100:101], 0, v[128:129]
	s_waitcnt vmcnt(7)
	v_mov_b32_e32 v100, v204
	v_mov_b32_e32 v101, v205
	v_lshlrev_b32_e32 v106, 16, v100
	v_and_b32_e32 v107, 0xffff0000, v100
	v_lshlrev_b32_e32 v108, 16, v101
	v_and_b32_e32 v109, 0xffff0000, v101
	s_waitcnt vmcnt(7) lgkmcnt(0)
	v_mov_b32_e32 v100, v208
	v_mov_b32_e32 v101, v209
	v_mov_b32_e32 v102, v210
	v_mov_b32_e32 v103, v211
	v_fmac_f32_e32 v106, v96, v100
	v_fmac_f32_e32 v107, v97, v101
	v_cvt_pk_bf16_f32 v96, v106, v107
	v_fmac_f32_e32 v108, v98, v102
	v_fmac_f32_e32 v109, v99, v103
	v_cvt_pk_bf16_f32 v97, v108, v109
	global_store_dwordx2 v[104:105], v[96:97], off
	v_or_b32_e32 v96, 32, v130
	v_ashrrev_i32_e32 v97, 31, v96
	v_lshlrev_b64 v[96:97], 11, v[96:97]
	s_waitcnt lgkmcnt(0)
	ds_write2_b32 v132, v72, v76 offset1:16
	ds_write2_b32 v132, v73, v77 offset0:68 offset1:84
	ds_write2_b32 v132, v74, v78 offset0:136 offset1:152
	ds_write2_b32 v132, v75, v79 offset0:204 offset1:220
	ds_write2_b32 v132, v88, v92 offset0:32 offset1:48
	ds_write2_b32 v132, v89, v93 offset0:100 offset1:116
	ds_write2_b32 v132, v90, v94 offset0:168 offset1:184
	ds_write2_b32 v132, v91, v95 offset0:236 offset1:252
	ds_write2_b32 v123, v64, v68 offset0:64 offset1:80
	ds_write2_b32 v123, v65, v69 offset0:132 offset1:148
	ds_write2_b32 v123, v66, v70 offset0:200 offset1:216
	ds_write2_b32 v125, v67, v71 offset0:12 offset1:28
	ds_write2_b32 v123, v80, v84 offset0:96 offset1:112
	ds_write2_b32 v123, v81, v85 offset0:164 offset1:180
	ds_write2_b32 v123, v82, v86 offset0:232 offset1:248
	ds_write2_b32 v125, v83, v87 offset0:44 offset1:60
	v_lshl_add_u64 v[96:97], s[12:13], 0, v[96:97]
	s_waitcnt lgkmcnt(0)
	v_lshl_add_u64 v[100:101], v[96:97], 0, v[128:129]
	ds_read_b128 v[92:95], v124
	ds_read_b128 v[88:91], v124 offset:1088
	ds_read_b128 v[84:87], v124 offset:2176
	ds_read_b128 v[80:83], v124 offset:3264
	ds_read_b128 v[76:79], v124 offset:4352
	ds_read_b128 v[72:75], v124 offset:5440
	ds_read_b128 v[68:71], v124 offset:6528
	ds_read_b128 v[64:67], v124 offset:7616
	s_mov_b64 s[26:27], 0x2000
	global_load_dwordx2 v[190:191], v[100:101], off
	v_lshl_add_u64 v[206:207], v[100:101], 0, s[26:27]
	global_load_dwordx2 v[192:193], v[206:207], off
	v_lshl_add_u64 v[206:207], v[206:207], 0, s[26:27]
	global_load_dwordx2 v[194:195], v[206:207], off
	v_lshl_add_u64 v[206:207], v[206:207], 0, s[26:27]
	global_load_dwordx2 v[196:197], v[206:207], off
	v_lshl_add_u64 v[206:207], v[206:207], 0, s[26:27]
	global_load_dwordx2 v[198:199], v[206:207], off
	v_lshl_add_u64 v[206:207], v[206:207], 0, s[26:27]
	global_load_dwordx2 v[200:201], v[206:207], off
	v_lshl_add_u64 v[206:207], v[206:207], 0, s[26:27]
	global_load_dwordx2 v[202:203], v[206:207], off
	v_lshl_add_u64 v[206:207], v[206:207], 0, s[26:27]
	global_load_dwordx2 v[204:205], v[206:207], off
	s_waitcnt vmcnt(7)
; DI void st4(u16* p, float a, float b, float c, float d) { u32x2 w = {cvtpk(a, b), cvtpk(c, d)}; *(u32x2*)p = w; }
;   DI void operator()(int m, int n, f32x4 v) const { st4(dst + (size_t)m * ld + n, v[0], v[1], v[2], v[3]); }
; DI void ld4bf(const u16* p, float* o) { const u32x2 w = *(const u32x2*)p; o[0] = __uint_as_float(w[0] << 16); o[1] = __uint_as_float(w[0] & 0xffff0000u); o[2] = __uint_as_float(w[1] << 16); o[3] = __uint_as_float(w[1] & 0xffff0000u); }
;   DI void operator()(int m, int n, f32x4 v) const {
;     float x[4]; ld4bf(xb + (size_t)m * 1024 + n, x);
;     const f32x4 g = *(const f32x4*)(gate + n);
;     st4(xb + (size_t)m * 1024 + n, x[0] + g[0] * v[0], x[1] + g[1] * v[1], x[2] + g[2] * v[2], x[3] + g[3] * v[3]);
;   }
	v_mov_b32_e32 v96, v190
	v_mov_b32_e32 v97, v191
	v_lshlrev_b32_e32 v102, 16, v96
	v_and_b32_e32 v103, 0xffff0000, v96
	v_lshlrev_b32_e32 v104, 16, v97
	v_and_b32_e32 v105, 0xffff0000, v97
	s_waitcnt vmcnt(7) lgkmcnt(7)
	v_mov_b32_e32 v96, v208
	v_mov_b32_e32 v97, v209
	v_mov_b32_e32 v98, v210
	v_mov_b32_e32 v99, v211
	v_fmac_f32_e32 v102, v92, v96
	v_fmac_f32_e32 v103, v93, v97
	v_cvt_pk_bf16_f32 v92, v102, v103
	v_fmac_f32_e32 v104, v94, v98
	v_fmac_f32_e32 v105, v95, v99
	v_cvt_pk_bf16_f32 v93, v104, v105
	global_store_dwordx2 v[100:101], v[92:93], off
	v_or_b32_e32 v92, 36, v130
	v_ashrrev_i32_e32 v93, 31, v92
	v_lshlrev_b64 v[92:93], 11, v[92:93]
	v_lshl_add_u64 v[92:93], s[12:13], 0, v[92:93]
	v_lshl_add_u64 v[96:97], v[92:93], 0, v[128:129]
	s_waitcnt vmcnt(7)
	v_mov_b32_e32 v92, v192
	v_mov_b32_e32 v93, v193
	v_lshlrev_b32_e32 v98, 16, v92
	v_and_b32_e32 v99, 0xffff0000, v92
	v_lshlrev_b32_e32 v100, 16, v93
	v_and_b32_e32 v101, 0xffff0000, v93
	s_waitcnt vmcnt(7) lgkmcnt(6)
	v_mov_b32_e32 v92, v208
	v_mov_b32_e32 v93, v209
	v_mov_b32_e32 v94, v210
	v_mov_b32_e32 v95, v211
	v_fmac_f32_e32 v98, v88, v92
	v_fmac_f32_e32 v99, v89, v93
	v_cvt_pk_bf16_f32 v88, v98, v99
	v_fmac_f32_e32 v100, v90, v94
	v_fmac_f32_e32 v101, v91, v95
	v_cvt_pk_bf16_f32 v89, v100, v101
	global_store_dwordx2 v[96:97], v[88:89], off
	v_or_b32_e32 v88, 40, v130
	v_ashrrev_i32_e32 v89, 31, v88
	v_lshlrev_b64 v[88:89], 11, v[88:89]
	v_lshl_add_u64 v[88:89], s[12:13], 0, v[88:89]
	v_lshl_add_u64 v[92:93], v[88:89], 0, v[128:129]
	s_waitcnt vmcnt(7)
	v_mov_b32_e32 v88, v194
	v_mov_b32_e32 v89, v195
	v_lshlrev_b32_e32 v94, 16, v88
	v_and_b32_e32 v95, 0xffff0000, v88
	v_lshlrev_b32_e32 v96, 16, v89
	v_and_b32_e32 v97, 0xffff0000, v89
	s_waitcnt vmcnt(7) lgkmcnt(5)
	v_mov_b32_e32 v88, v208
	v_mov_b32_e32 v89, v209
	v_mov_b32_e32 v90, v210
	v_mov_b32_e32 v91, v211
	v_fmac_f32_e32 v94, v84, v88
	v_fmac_f32_e32 v95, v85, v89
	v_cvt_pk_bf16_f32 v84, v94, v95
	v_fmac_f32_e32 v96, v86, v90
	v_fmac_f32_e32 v97, v87, v91
	v_cvt_pk_bf16_f32 v85, v96, v97
	global_store_dwordx2 v[92:93], v[84:85], off
	v_or_b32_e32 v84, 44, v130
	v_ashrrev_i32_e32 v85, 31, v84
	v_lshlrev_b64 v[84:85], 11, v[84:85]
	v_lshl_add_u64 v[84:85], s[12:13], 0, v[84:85]
	v_lshl_add_u64 v[88:89], v[84:85], 0, v[128:129]
	s_waitcnt vmcnt(7)
	v_mov_b32_e32 v84, v196
	v_mov_b32_e32 v85, v197
	v_lshlrev_b32_e32 v90, 16, v84
	v_and_b32_e32 v91, 0xffff0000, v84
	v_lshlrev_b32_e32 v92, 16, v85
	v_and_b32_e32 v93, 0xffff0000, v85
	s_waitcnt vmcnt(7) lgkmcnt(4)
	v_mov_b32_e32 v84, v208
	v_mov_b32_e32 v85, v209
	v_mov_b32_e32 v86, v210
	v_mov_b32_e32 v87, v211
	v_fmac_f32_e32 v90, v80, v84
	v_fmac_f32_e32 v91, v81, v85
	v_cvt_pk_bf16_f32 v80, v90, v91
	v_fmac_f32_e32 v92, v82, v86
	v_fmac_f32_e32 v93, v83, v87
	v_cvt_pk_bf16_f32 v81, v92, v93
	global_store_dwordx2 v[88:89], v[80:81], off
	v_or_b32_e32 v80, 48, v130
	v_ashrrev_i32_e32 v81, 31, v80
	v_lshlrev_b64 v[80:81], 11, v[80:81]
	v_lshl_add_u64 v[80:81], s[12:13], 0, v[80:81]
	v_lshl_add_u64 v[84:85], v[80:81], 0, v[128:129]
	s_waitcnt vmcnt(7)
	v_mov_b32_e32 v80, v198
	v_mov_b32_e32 v81, v199
	v_lshlrev_b32_e32 v86, 16, v80
	v_and_b32_e32 v87, 0xffff0000, v80
	v_lshlrev_b32_e32 v88, 16, v81
	v_and_b32_e32 v89, 0xffff0000, v81
	s_waitcnt vmcnt(7) lgkmcnt(3)
	v_mov_b32_e32 v80, v208
	v_mov_b32_e32 v81, v209
	v_mov_b32_e32 v82, v210
	v_mov_b32_e32 v83, v211
	v_fmac_f32_e32 v86, v76, v80
	v_fmac_f32_e32 v87, v77, v81
	v_cvt_pk_bf16_f32 v76, v86, v87
	v_fmac_f32_e32 v88, v78, v82
	v_fmac_f32_e32 v89, v79, v83
	v_cvt_pk_bf16_f32 v77, v88, v89
	global_store_dwordx2 v[84:85], v[76:77], off
	v_or_b32_e32 v76, 52, v130
	v_ashrrev_i32_e32 v77, 31, v76
	v_lshlrev_b64 v[76:77], 11, v[76:77]
	v_lshl_add_u64 v[76:77], s[12:13], 0, v[76:77]
	v_lshl_add_u64 v[80:81], v[76:77], 0, v[128:129]
	s_waitcnt vmcnt(7)
	v_mov_b32_e32 v76, v200
	v_mov_b32_e32 v77, v201
	v_lshlrev_b32_e32 v82, 16, v76
	v_and_b32_e32 v83, 0xffff0000, v76
	v_lshlrev_b32_e32 v84, 16, v77
	v_and_b32_e32 v85, 0xffff0000, v77
	s_waitcnt vmcnt(7) lgkmcnt(2)
	v_mov_b32_e32 v76, v208
	v_mov_b32_e32 v77, v209
	v_mov_b32_e32 v78, v210
	v_mov_b32_e32 v79, v211
	v_fmac_f32_e32 v82, v72, v76
	v_fmac_f32_e32 v83, v73, v77
	v_cvt_pk_bf16_f32 v72, v82, v83
	v_fmac_f32_e32 v84, v74, v78
	v_fmac_f32_e32 v85, v75, v79
	v_cvt_pk_bf16_f32 v73, v84, v85
	global_store_dwordx2 v[80:81], v[72:73], off
	v_or_b32_e32 v72, 56, v130
	v_ashrrev_i32_e32 v73, 31, v72
	v_lshlrev_b64 v[72:73], 11, v[72:73]
	v_lshl_add_u64 v[72:73], s[12:13], 0, v[72:73]
	v_lshl_add_u64 v[76:77], v[72:73], 0, v[128:129]
	s_waitcnt vmcnt(7)
	v_mov_b32_e32 v72, v202
	v_mov_b32_e32 v73, v203
	v_lshlrev_b32_e32 v78, 16, v72
	v_and_b32_e32 v79, 0xffff0000, v72
	v_lshlrev_b32_e32 v80, 16, v73
	v_and_b32_e32 v81, 0xffff0000, v73
	s_waitcnt vmcnt(7) lgkmcnt(1)
	v_mov_b32_e32 v72, v208
	v_mov_b32_e32 v73, v209
	v_mov_b32_e32 v74, v210
	v_mov_b32_e32 v75, v211
	v_fmac_f32_e32 v78, v68, v72
	v_fmac_f32_e32 v79, v69, v73
	v_cvt_pk_bf16_f32 v68, v78, v79
	v_fmac_f32_e32 v80, v70, v74
	v_fmac_f32_e32 v81, v71, v75
	v_cvt_pk_bf16_f32 v69, v80, v81
	global_store_dwordx2 v[76:77], v[68:69], off
	v_or_b32_e32 v68, 60, v130
	v_ashrrev_i32_e32 v69, 31, v68
	v_lshlrev_b64 v[68:69], 11, v[68:69]
	v_lshl_add_u64 v[68:69], s[12:13], 0, v[68:69]
	v_lshl_add_u64 v[72:73], v[68:69], 0, v[128:129]
	s_mov_b32 s12, 0x40000
	s_waitcnt vmcnt(7)
	v_mov_b32_e32 v68, v204
	v_mov_b32_e32 v69, v205
	v_lshlrev_b32_e32 v74, 16, v68
	v_and_b32_e32 v75, 0xffff0000, v68
	v_lshlrev_b32_e32 v76, 16, v69
	v_and_b32_e32 v77, 0xffff0000, v69
	s_waitcnt vmcnt(7) lgkmcnt(0)
; DI void st4(u16* p, float a, float b, float c, float d) { u32x2 w = {cvtpk(a, b), cvtpk(c, d)}; *(u32x2*)p = w; }
;   DI void operator()(int m, int n, f32x4 v) const { st4(dst + (size_t)m * ld + n, v[0], v[1], v[2], v[3]); }
; DI void ld4bf(const u16* p, float* o) { const u32x2 w = *(const u32x2*)p; o[0] = __uint_as_float(w[0] << 16); o[1] = __uint_as_float(w[0] & 0xffff0000u); o[2] = __uint_as_float(w[1] << 16); o[3] = __uint_as_float(w[1] & 0xffff0000u); }
;   DI void operator()(int m, int n, f32x4 v) const {
;     float x[4]; ld4bf(xb + (size_t)m * 1024 + n, x);
;     const f32x4 g = *(const f32x4*)(gate + n);
;     st4(xb + (size_t)m * 1024 + n, x[0] + g[0] * v[0], x[1] + g[1] * v[1], x[2] + g[2] * v[2], x[3] + g[3] * v[3]);
;   }
	v_mov_b32_e32 v68, v208
	v_mov_b32_e32 v69, v209
	v_mov_b32_e32 v70, v210
	v_mov_b32_e32 v71, v211
	v_fmac_f32_e32 v74, v64, v68
	v_fmac_f32_e32 v75, v65, v69
	v_fmac_f32_e32 v76, v66, v70
	v_fmac_f32_e32 v77, v67, v71
	v_cvt_pk_bf16_f32 v64, v74, v75
	v_cvt_pk_bf16_f32 v65, v76, v77
	global_store_dwordx2 v[72:73], v[64:65], off
	s_waitcnt lgkmcnt(0)
	ds_write2_b32 v132, v40, v44 offset1:16
	ds_write2_b32 v132, v41, v45 offset0:68 offset1:84
	ds_write2_b32 v132, v42, v46 offset0:136 offset1:152
	ds_write2_b32 v132, v43, v47 offset0:204 offset1:220
	ds_write2_b32 v132, v56, v60 offset0:32 offset1:48
	ds_write2_b32 v132, v57, v61 offset0:100 offset1:116
	ds_write2_b32 v132, v58, v62 offset0:168 offset1:184
	ds_write2_b32 v132, v59, v63 offset0:236 offset1:252
	ds_write2_b32 v123, v32, v36 offset0:64 offset1:80
	ds_write2_b32 v123, v33, v37 offset0:132 offset1:148
	ds_write2_b32 v123, v34, v38 offset0:200 offset1:216
	ds_write2_b32 v125, v35, v39 offset0:12 offset1:28
	ds_write2_b32 v123, v48, v52 offset0:96 offset1:112
	ds_write2_b32 v123, v49, v53 offset0:164 offset1:180
	ds_write2_b32 v123, v50, v54 offset0:232 offset1:248
	ds_write2_b32 v125, v51, v55 offset0:44 offset1:60
	v_add_co_u32_e32 v68, vcc, s12, v120
	s_waitcnt lgkmcnt(0)
	ds_read_b128 v[60:63], v124
	ds_read_b128 v[56:59], v124 offset:1088
	ds_read_b128 v[52:55], v124 offset:2176
	ds_read_b128 v[48:51], v124 offset:3264
	ds_read_b128 v[44:47], v124 offset:4352
	ds_read_b128 v[40:43], v124 offset:5440
	ds_read_b128 v[36:39], v124 offset:6528
	ds_read_b128 v[32:35], v124 offset:7616
	v_addc_co_u32_e32 v69, vcc, 0, v121, vcc
	s_mov_b64 s[26:27], 0x2000
	global_load_dwordx2 v[190:191], v[68:69], off
	v_lshl_add_u64 v[206:207], v[68:69], 0, s[26:27]
	global_load_dwordx2 v[192:193], v[206:207], off
	v_lshl_add_u64 v[206:207], v[206:207], 0, s[26:27]
	global_load_dwordx2 v[194:195], v[206:207], off
	v_lshl_add_u64 v[206:207], v[206:207], 0, s[26:27]
	global_load_dwordx2 v[196:197], v[206:207], off
	v_lshl_add_u64 v[206:207], v[206:207], 0, s[26:27]
	global_load_dwordx2 v[198:199], v[206:207], off
	v_lshl_add_u64 v[206:207], v[206:207], 0, s[26:27]
	global_load_dwordx2 v[200:201], v[206:207], off
	v_lshl_add_u64 v[206:207], v[206:207], 0, s[26:27]
	global_load_dwordx2 v[202:203], v[206:207], off
	v_lshl_add_u64 v[206:207], v[206:207], 0, s[26:27]
	global_load_dwordx2 v[204:205], v[206:207], off
	s_mov_b32 s12, 0x42000
	s_waitcnt vmcnt(7)
	v_mov_b32_e32 v64, v190
	v_mov_b32_e32 v65, v191
	v_lshlrev_b32_e32 v70, 16, v64
	v_and_b32_e32 v71, 0xffff0000, v64
	v_lshlrev_b32_e32 v72, 16, v65
	v_and_b32_e32 v73, 0xffff0000, v65
	s_waitcnt vmcnt(7) lgkmcnt(7)
	v_mov_b32_e32 v64, v208
	v_mov_b32_e32 v65, v209
	v_mov_b32_e32 v66, v210
	v_mov_b32_e32 v67, v211
	v_fmac_f32_e32 v70, v60, v64
	v_add_co_u32_e32 v64, vcc, s12, v120
	v_fmac_f32_e32 v71, v61, v65
	v_fmac_f32_e32 v72, v62, v66
	v_fmac_f32_e32 v73, v63, v67
	v_cvt_pk_bf16_f32 v60, v70, v71
	v_cvt_pk_bf16_f32 v61, v72, v73
	v_addc_co_u32_e32 v65, vcc, 0, v121, vcc
	global_store_dwordx2 v[68:69], v[60:61], off
	s_mov_b32 s12, 0x44000
	s_waitcnt vmcnt(7)
	v_mov_b32_e32 v60, v192
	v_mov_b32_e32 v61, v193
	v_lshlrev_b32_e32 v66, 16, v60
	v_and_b32_e32 v67, 0xffff0000, v60
	v_lshlrev_b32_e32 v68, 16, v61
	v_and_b32_e32 v69, 0xffff0000, v61
	s_waitcnt vmcnt(7) lgkmcnt(6)
	v_mov_b32_e32 v60, v208
	v_mov_b32_e32 v61, v209
	v_mov_b32_e32 v62, v210
	v_mov_b32_e32 v63, v211
	v_fmac_f32_e32 v66, v56, v60
	v_add_co_u32_e32 v60, vcc, s12, v120
	v_fmac_f32_e32 v67, v57, v61
	v_fmac_f32_e32 v68, v58, v62
	v_fmac_f32_e32 v69, v59, v63
	v_cvt_pk_bf16_f32 v56, v66, v67
	v_cvt_pk_bf16_f32 v57, v68, v69
	v_addc_co_u32_e32 v61, vcc, 0, v121, vcc
	global_store_dwordx2 v[64:65], v[56:57], off
	s_mov_b32 s12, 0x46000
	s_waitcnt vmcnt(7)
	v_mov_b32_e32 v56, v194
	v_mov_b32_e32 v57, v195
	v_lshlrev_b32_e32 v62, 16, v56
	v_and_b32_e32 v63, 0xffff0000, v56
	v_lshlrev_b32_e32 v64, 16, v57
	v_and_b32_e32 v65, 0xffff0000, v57
	s_waitcnt vmcnt(7) lgkmcnt(5)
	v_mov_b32_e32 v56, v208
	v_mov_b32_e32 v57, v209
	v_mov_b32_e32 v58, v210
	v_mov_b32_e32 v59, v211
	v_fmac_f32_e32 v62, v52, v56
	v_add_co_u32_e32 v56, vcc, s12, v120
	v_fmac_f32_e32 v63, v53, v57
	v_fmac_f32_e32 v64, v54, v58
	v_fmac_f32_e32 v65, v55, v59
	v_cvt_pk_bf16_f32 v52, v62, v63
	v_cvt_pk_bf16_f32 v53, v64, v65
	v_addc_co_u32_e32 v57, vcc, 0, v121, vcc
	global_store_dwordx2 v[60:61], v[52:53], off
	s_mov_b32 s12, 0x48000
	s_waitcnt vmcnt(7)
	v_mov_b32_e32 v52, v196
	v_mov_b32_e32 v53, v197
	v_lshlrev_b32_e32 v58, 16, v52
	v_and_b32_e32 v59, 0xffff0000, v52
	v_lshlrev_b32_e32 v60, 16, v53
	v_and_b32_e32 v61, 0xffff0000, v53
	s_waitcnt vmcnt(7) lgkmcnt(4)
	v_mov_b32_e32 v52, v208
	v_mov_b32_e32 v53, v209
	v_mov_b32_e32 v54, v210
	v_mov_b32_e32 v55, v211
	v_fmac_f32_e32 v58, v48, v52
	v_add_co_u32_e32 v52, vcc, s12, v120
	v_fmac_f32_e32 v59, v49, v53
	v_fmac_f32_e32 v60, v50, v54
	v_fmac_f32_e32 v61, v51, v55
	v_cvt_pk_bf16_f32 v48, v58, v59
	v_cvt_pk_bf16_f32 v49, v60, v61
	v_addc_co_u32_e32 v53, vcc, 0, v121, vcc
	global_store_dwordx2 v[56:57], v[48:49], off
	s_mov_b32 s12, 0x4a000
	s_waitcnt vmcnt(7)
	v_mov_b32_e32 v48, v198
	v_mov_b32_e32 v49, v199
	v_lshlrev_b32_e32 v54, 16, v48
	v_and_b32_e32 v55, 0xffff0000, v48
	v_lshlrev_b32_e32 v56, 16, v49
	v_and_b32_e32 v57, 0xffff0000, v49
	s_waitcnt vmcnt(7) lgkmcnt(3)
	v_mov_b32_e32 v48, v208
	v_mov_b32_e32 v49, v209
	v_mov_b32_e32 v50, v210
	v_mov_b32_e32 v51, v211
	v_fmac_f32_e32 v54, v44, v48
	v_add_co_u32_e32 v48, vcc, s12, v120
	v_fmac_f32_e32 v55, v45, v49
	v_fmac_f32_e32 v56, v46, v50
	v_fmac_f32_e32 v57, v47, v51
	v_cvt_pk_bf16_f32 v44, v54, v55
	v_cvt_pk_bf16_f32 v45, v56, v57
	v_addc_co_u32_e32 v49, vcc, 0, v121, vcc
	global_store_dwordx2 v[52:53], v[44:45], off
	s_mov_b32 s12, 0x4c000
	s_waitcnt vmcnt(7)
; DI void st4(u16* p, float a, float b, float c, float d) { u32x2 w = {cvtpk(a, b), cvtpk(c, d)}; *(u32x2*)p = w; }
;   DI void operator()(int m, int n, f32x4 v) const { st4(dst + (size_t)m * ld + n, v[0], v[1], v[2], v[3]); }
; DI void ld4bf(const u16* p, float* o) { const u32x2 w = *(const u32x2*)p; o[0] = __uint_as_float(w[0] << 16); o[1] = __uint_as_float(w[0] & 0xffff0000u); o[2] = __uint_as_float(w[1] << 16); o[3] = __uint_as_float(w[1] & 0xffff0000u); }
;   DI void operator()(int m, int n, f32x4 v) const {
;     float x[4]; ld4bf(xb + (size_t)m * 1024 + n, x);
;     const f32x4 g = *(const f32x4*)(gate + n);
;     st4(xb + (size_t)m * 1024 + n, x[0] + g[0] * v[0], x[1] + g[1] * v[1], x[2] + g[2] * v[2], x[3] + g[3] * v[3]);
;   }
	v_mov_b32_e32 v44, v200
	v_mov_b32_e32 v45, v201
	v_lshlrev_b32_e32 v50, 16, v44
	v_and_b32_e32 v51, 0xffff0000, v44
	v_lshlrev_b32_e32 v52, 16, v45
	v_and_b32_e32 v53, 0xffff0000, v45
	s_waitcnt vmcnt(7) lgkmcnt(2)
	v_mov_b32_e32 v44, v208
	v_mov_b32_e32 v45, v209
	v_mov_b32_e32 v46, v210
	v_mov_b32_e32 v47, v211
	v_fmac_f32_e32 v50, v40, v44
	v_add_co_u32_e32 v44, vcc, s12, v120
	v_fmac_f32_e32 v51, v41, v45
	v_fmac_f32_e32 v52, v42, v46
	v_fmac_f32_e32 v53, v43, v47
	v_cvt_pk_bf16_f32 v40, v50, v51
	v_cvt_pk_bf16_f32 v41, v52, v53
	v_addc_co_u32_e32 v45, vcc, 0, v121, vcc
	global_store_dwordx2 v[48:49], v[40:41], off
	s_mov_b32 s12, 0x4e000
	s_waitcnt vmcnt(7)
	v_mov_b32_e32 v40, v202
	v_mov_b32_e32 v41, v203
	v_lshlrev_b32_e32 v46, 16, v40
	v_and_b32_e32 v47, 0xffff0000, v40
	v_lshlrev_b32_e32 v48, 16, v41
	v_and_b32_e32 v49, 0xffff0000, v41
	s_waitcnt vmcnt(7) lgkmcnt(1)
	v_mov_b32_e32 v40, v208
	v_mov_b32_e32 v41, v209
	v_mov_b32_e32 v42, v210
	v_mov_b32_e32 v43, v211
	v_fmac_f32_e32 v46, v36, v40
	v_add_co_u32_e32 v40, vcc, s12, v120
	v_fmac_f32_e32 v47, v37, v41
	v_fmac_f32_e32 v48, v38, v42
	v_fmac_f32_e32 v49, v39, v43
	v_cvt_pk_bf16_f32 v36, v46, v47
	v_cvt_pk_bf16_f32 v37, v48, v49
	v_addc_co_u32_e32 v41, vcc, 0, v121, vcc
	global_store_dwordx2 v[44:45], v[36:37], off
	s_mov_b32 s12, 0x50000
	s_waitcnt vmcnt(7)
	v_mov_b32_e32 v36, v204
	v_mov_b32_e32 v37, v205
	v_lshlrev_b32_e32 v42, 16, v36
	v_and_b32_e32 v43, 0xffff0000, v36
	v_lshlrev_b32_e32 v44, 16, v37
	v_and_b32_e32 v45, 0xffff0000, v37
	s_waitcnt vmcnt(7) lgkmcnt(0)
	v_mov_b32_e32 v36, v208
	v_mov_b32_e32 v37, v209
	v_mov_b32_e32 v38, v210
	v_mov_b32_e32 v39, v211
	v_fmac_f32_e32 v42, v32, v36
	v_fmac_f32_e32 v43, v33, v37
	v_fmac_f32_e32 v44, v34, v38
	v_fmac_f32_e32 v45, v35, v39
	v_cvt_pk_bf16_f32 v32, v42, v43
	v_cvt_pk_bf16_f32 v33, v44, v45
	global_store_dwordx2 v[40:41], v[32:33], off
	s_waitcnt lgkmcnt(0)
	ds_write2_b32 v132, v8, v12 offset1:16
	ds_write2_b32 v132, v9, v13 offset0:68 offset1:84
	ds_write2_b32 v132, v10, v14 offset0:136 offset1:152
	ds_write2_b32 v132, v11, v15 offset0:204 offset1:220
	ds_write2_b32 v132, v24, v28 offset0:32 offset1:48
	ds_write2_b32 v132, v25, v29 offset0:100 offset1:116
	ds_write2_b32 v132, v26, v30 offset0:168 offset1:184
	ds_write2_b32 v132, v27, v31 offset0:236 offset1:252
	ds_write2_b32 v123, v0, v4 offset0:64 offset1:80
	ds_write2_b32 v123, v1, v5 offset0:132 offset1:148
	ds_write2_b32 v123, v2, v6 offset0:200 offset1:216
	ds_write2_b32 v125, v3, v7 offset0:12 offset1:28
	ds_write2_b32 v123, v16, v20 offset0:96 offset1:112
	ds_write2_b32 v123, v17, v21 offset0:164 offset1:180
	ds_write2_b32 v123, v18, v22 offset0:232 offset1:248
	ds_write2_b32 v125, v19, v23 offset0:44 offset1:60
	v_add_co_u32_e32 v36, vcc, s12, v120
	s_waitcnt lgkmcnt(0)
	ds_read_b128 v[28:31], v124
	ds_read_b128 v[24:27], v124 offset:1088
	ds_read_b128 v[20:23], v124 offset:2176
	ds_read_b128 v[16:19], v124 offset:3264
	ds_read_b128 v[12:15], v124 offset:4352
	ds_read_b128 v[8:11], v124 offset:5440
	ds_read_b128 v[4:7], v124 offset:6528
	ds_read_b128 v[0:3], v124 offset:7616
	v_addc_co_u32_e32 v37, vcc, 0, v121, vcc
	s_mov_b64 s[26:27], 0x2000
	global_load_dwordx2 v[190:191], v[36:37], off
	v_lshl_add_u64 v[206:207], v[36:37], 0, s[26:27]
	global_load_dwordx2 v[192:193], v[206:207], off
	v_lshl_add_u64 v[206:207], v[206:207], 0, s[26:27]
	global_load_dwordx2 v[194:195], v[206:207], off
	v_lshl_add_u64 v[206:207], v[206:207], 0, s[26:27]
	global_load_dwordx2 v[196:197], v[206:207], off
	v_lshl_add_u64 v[206:207], v[206:207], 0, s[26:27]
	global_load_dwordx2 v[198:199], v[206:207], off
	v_lshl_add_u64 v[206:207], v[206:207], 0, s[26:27]
	global_load_dwordx2 v[200:201], v[206:207], off
	v_lshl_add_u64 v[206:207], v[206:207], 0, s[26:27]
	global_load_dwordx2 v[202:203], v[206:207], off
	v_lshl_add_u64 v[206:207], v[206:207], 0, s[26:27]
	global_load_dwordx2 v[204:205], v[206:207], off
	s_mov_b32 s12, 0x52000
	s_waitcnt vmcnt(7)
	v_mov_b32_e32 v32, v190
	v_mov_b32_e32 v33, v191
	v_lshlrev_b32_e32 v38, 16, v32
	v_and_b32_e32 v39, 0xffff0000, v32
	v_lshlrev_b32_e32 v40, 16, v33
	v_and_b32_e32 v41, 0xffff0000, v33
	s_waitcnt vmcnt(7) lgkmcnt(7)
	v_mov_b32_e32 v32, v208
	v_mov_b32_e32 v33, v209
	v_mov_b32_e32 v34, v210
	v_mov_b32_e32 v35, v211
	v_fmac_f32_e32 v38, v28, v32
	v_add_co_u32_e32 v32, vcc, s12, v120
	v_fmac_f32_e32 v39, v29, v33
	v_fmac_f32_e32 v40, v30, v34
	v_fmac_f32_e32 v41, v31, v35
	v_cvt_pk_bf16_f32 v28, v38, v39
	v_cvt_pk_bf16_f32 v29, v40, v41
	v_addc_co_u32_e32 v33, vcc, 0, v121, vcc
	global_store_dwordx2 v[36:37], v[28:29], off
	s_mov_b32 s12, 0x54000
	s_waitcnt vmcnt(7)
	v_mov_b32_e32 v28, v192
	v_mov_b32_e32 v29, v193
	v_lshlrev_b32_e32 v34, 16, v28
	v_and_b32_e32 v35, 0xffff0000, v28
	v_lshlrev_b32_e32 v36, 16, v29
	v_and_b32_e32 v37, 0xffff0000, v29
	s_waitcnt vmcnt(7) lgkmcnt(6)
; DI void st4(u16* p, float a, float b, float c, float d) { u32x2 w = {cvtpk(a, b), cvtpk(c, d)}; *(u32x2*)p = w; }
;   DI void operator()(int m, int n, f32x4 v) const { st4(dst + (size_t)m * ld + n, v[0], v[1], v[2], v[3]); }
; DI void ld4bf(const u16* p, float* o) { const u32x2 w = *(const u32x2*)p; o[0] = __uint_as_float(w[0] << 16); o[1] = __uint_as_float(w[0] & 0xffff0000u); o[2] = __uint_as_float(w[1] << 16); o[3] = __uint_as_float(w[1] & 0xffff0000u); }
; #define TILE_LOOP(q, x, NPX) for (int lin_ = (nb == 256 ? (bid >> 3) : bid), q = (nb == 256 ? lin_ : lin_ / 8), x = (nb == 256 ? (bid & 7) : lin_ % 8); \
;     (nb == 256 ? q < (NPX) : lin_ < 8 * (NPX)); lin_ += (nb == 256 ? 32 : nb), q = (nb == 256 ? lin_ : lin_ / 8), x = (nb == 256 ? x : lin_ % 8))
;   DI void operator()(int m, int n, f32x4 v) const {
;     float x[4]; ld4bf(xb + (size_t)m * 1024 + n, x);
;     const f32x4 g = *(const f32x4*)(gate + n);
;     st4(xb + (size_t)m * 1024 + n, x[0] + g[0] * v[0], x[1] + g[1] * v[1], x[2] + g[2] * v[2], x[3] + g[3] * v[3]);
;   }
; DI void phase_resid_gemm(int layer, int g, int kind, char* smem) {
;     ...
;   TILE_LOOP(q, x, npx) {
;     const int mt = (q >> 2) * 8 + x, nt = q & 3, s = seq0 + (mt >> 4);
;     const size_t to = (size_t)mt * 256 * 1024 + nt * 256;
;     const float* gate = modl + (size_t)s * 6144 + goff + nt * 256;
;     if (kind == 0) { EpiResidF e{xin + to, xb + to, gate}; gemm_tile<false>(A + (size_t)mt * 256 * K, K, B + (size_t)(nt * 256) * K, K, K, (u16*)smem, e); }
;     else { EpiResidB e{xb + to, gate}; gemm_tile<false>(A + (size_t)mt * 256 * K, K, B + (size_t)(nt * 256) * K, K, K, (u16*)smem, e); }
	v_mov_b32_e32 v28, v208
	v_mov_b32_e32 v29, v209
	v_mov_b32_e32 v30, v210
	v_mov_b32_e32 v31, v211
	v_fmac_f32_e32 v34, v24, v28
	v_add_co_u32_e32 v28, vcc, s12, v120
	v_fmac_f32_e32 v35, v25, v29
	v_fmac_f32_e32 v36, v26, v30
	v_fmac_f32_e32 v37, v27, v31
	v_cvt_pk_bf16_f32 v24, v34, v35
	v_cvt_pk_bf16_f32 v25, v36, v37
	v_addc_co_u32_e32 v29, vcc, 0, v121, vcc
	global_store_dwordx2 v[32:33], v[24:25], off
	s_mov_b32 s12, 0x56000
	s_waitcnt vmcnt(7)
	v_mov_b32_e32 v24, v194
	v_mov_b32_e32 v25, v195
	v_lshlrev_b32_e32 v30, 16, v24
	v_and_b32_e32 v31, 0xffff0000, v24
	v_lshlrev_b32_e32 v32, 16, v25
	v_and_b32_e32 v33, 0xffff0000, v25
	s_waitcnt vmcnt(7) lgkmcnt(5)
	v_mov_b32_e32 v24, v208
	v_mov_b32_e32 v25, v209
	v_mov_b32_e32 v26, v210
	v_mov_b32_e32 v27, v211
	v_fmac_f32_e32 v30, v20, v24
	v_add_co_u32_e32 v24, vcc, s12, v120
	v_fmac_f32_e32 v31, v21, v25
	v_fmac_f32_e32 v32, v22, v26
	v_fmac_f32_e32 v33, v23, v27
	v_cvt_pk_bf16_f32 v20, v30, v31
	v_cvt_pk_bf16_f32 v21, v32, v33
	v_addc_co_u32_e32 v25, vcc, 0, v121, vcc
	global_store_dwordx2 v[28:29], v[20:21], off
	s_mov_b32 s12, 0x58000
	s_waitcnt vmcnt(7)
	v_mov_b32_e32 v20, v196
	v_mov_b32_e32 v21, v197
	v_lshlrev_b32_e32 v26, 16, v20
	v_and_b32_e32 v27, 0xffff0000, v20
	v_lshlrev_b32_e32 v28, 16, v21
	v_and_b32_e32 v29, 0xffff0000, v21
	s_waitcnt vmcnt(7) lgkmcnt(4)
	v_mov_b32_e32 v20, v208
	v_mov_b32_e32 v21, v209
	v_mov_b32_e32 v22, v210
	v_mov_b32_e32 v23, v211
	v_fmac_f32_e32 v26, v16, v20
	v_add_co_u32_e32 v20, vcc, s12, v120
	v_fmac_f32_e32 v27, v17, v21
	v_fmac_f32_e32 v28, v18, v22
	v_fmac_f32_e32 v29, v19, v23
	v_cvt_pk_bf16_f32 v16, v26, v27
	v_cvt_pk_bf16_f32 v17, v28, v29
	v_addc_co_u32_e32 v21, vcc, 0, v121, vcc
	global_store_dwordx2 v[24:25], v[16:17], off
	s_mov_b32 s12, 0x5a000
	s_waitcnt vmcnt(7)
	v_mov_b32_e32 v16, v198
	v_mov_b32_e32 v17, v199
	v_lshlrev_b32_e32 v22, 16, v16
	v_and_b32_e32 v23, 0xffff0000, v16
	v_lshlrev_b32_e32 v24, 16, v17
	v_and_b32_e32 v25, 0xffff0000, v17
	s_waitcnt vmcnt(7) lgkmcnt(3)
	v_mov_b32_e32 v16, v208
	v_mov_b32_e32 v17, v209
	v_mov_b32_e32 v18, v210
	v_mov_b32_e32 v19, v211
	v_fmac_f32_e32 v22, v12, v16
	v_add_co_u32_e32 v16, vcc, s12, v120
	v_fmac_f32_e32 v23, v13, v17
	v_fmac_f32_e32 v24, v14, v18
	v_fmac_f32_e32 v25, v15, v19
	v_cvt_pk_bf16_f32 v12, v22, v23
	v_cvt_pk_bf16_f32 v13, v24, v25
	v_addc_co_u32_e32 v17, vcc, 0, v121, vcc
	global_store_dwordx2 v[20:21], v[12:13], off
	s_mov_b32 s12, 0x5c000
	s_waitcnt vmcnt(7)
	v_mov_b32_e32 v12, v200
	v_mov_b32_e32 v13, v201
	v_lshlrev_b32_e32 v18, 16, v12
	v_and_b32_e32 v19, 0xffff0000, v12
	v_lshlrev_b32_e32 v20, 16, v13
	v_and_b32_e32 v21, 0xffff0000, v13
	s_waitcnt vmcnt(7) lgkmcnt(2)
	v_mov_b32_e32 v12, v208
	v_mov_b32_e32 v13, v209
	v_mov_b32_e32 v14, v210
	v_mov_b32_e32 v15, v211
	v_fmac_f32_e32 v18, v8, v12
	v_add_co_u32_e32 v12, vcc, s12, v120
	v_fmac_f32_e32 v19, v9, v13
	v_fmac_f32_e32 v20, v10, v14
	v_fmac_f32_e32 v21, v11, v15
	v_cvt_pk_bf16_f32 v8, v18, v19
	v_cvt_pk_bf16_f32 v9, v20, v21
	v_addc_co_u32_e32 v13, vcc, 0, v121, vcc
	global_store_dwordx2 v[16:17], v[8:9], off
	s_mov_b32 s12, 0x5e000
	s_waitcnt vmcnt(7)
	v_mov_b32_e32 v8, v202
	v_mov_b32_e32 v9, v203
	v_lshlrev_b32_e32 v14, 16, v8
	v_and_b32_e32 v15, 0xffff0000, v8
	v_lshlrev_b32_e32 v16, 16, v9
	v_and_b32_e32 v17, 0xffff0000, v9
	s_waitcnt vmcnt(7) lgkmcnt(1)
	v_mov_b32_e32 v8, v208
	v_mov_b32_e32 v9, v209
	v_mov_b32_e32 v10, v210
	v_mov_b32_e32 v11, v211
	v_fmac_f32_e32 v14, v4, v8
	v_add_co_u32_e32 v8, vcc, s12, v120
	v_fmac_f32_e32 v15, v5, v9
	v_fmac_f32_e32 v16, v6, v10
	v_fmac_f32_e32 v17, v7, v11
	v_cvt_pk_bf16_f32 v4, v14, v15
	v_cvt_pk_bf16_f32 v5, v16, v17
	v_addc_co_u32_e32 v9, vcc, 0, v121, vcc
	global_store_dwordx2 v[12:13], v[4:5], off
	s_waitcnt vmcnt(7)
	v_mov_b32_e32 v4, v204
	v_mov_b32_e32 v5, v205
	v_lshlrev_b32_e32 v10, 16, v4
	v_and_b32_e32 v11, 0xffff0000, v4
	v_lshlrev_b32_e32 v12, 16, v5
	v_and_b32_e32 v13, 0xffff0000, v5
	s_ashr_i32 s10, s2, 31
	s_lshr_b32 s10, s10, 29
	s_add_i32 s12, s2, s10
	s_ashr_i32 s13, s12, 3
	s_and_b64 s[10:11], s[6:7], exec
	s_cselect_b32 s10, s2, s13
	s_and_b32 s11, s12, -8
	s_sub_i32 s11, s2, s11
	s_and_b64 s[12:13], s[6:7], exec
	s_cselect_b32 s1, s1, s11
	s_cmp_lt_i32 s10, 32
	s_cselect_b64 s[12:13], -1, 0
	s_cmpk_lt_i32 s2, 0x100
	s_cselect_b64 s[26:27], -1, 0
	s_waitcnt vmcnt(7) lgkmcnt(0)
	v_mov_b32_e32 v4, v208
	v_mov_b32_e32 v5, v209
	v_mov_b32_e32 v6, v210
	v_mov_b32_e32 v7, v211
	v_fmac_f32_e32 v10, v0, v4
	v_fmac_f32_e32 v11, v1, v5
	v_fmac_f32_e32 v12, v2, v6
	v_fmac_f32_e32 v13, v3, v7
	v_cvt_pk_bf16_f32 v0, v10, v11
	v_cvt_pk_bf16_f32 v1, v12, v13
	global_store_dwordx2 v[8:9], v[0:1], off
	v_cndmask_b32_e64 v0, 0, 1, s[12:13]
	v_cndmask_b32_e64 v1, 0, 1, s[26:27]
	v_cndmask_b32_e64 v0, v1, v0, s[6:7]
	s_waitcnt lgkmcnt(0)
	v_and_b32_e32 v0, 1, v0
	v_cmp_eq_u32_e32 vcc, 1, v0
	s_barrier
	s_cbranch_vccz .LBB0_909

; DI void st4(u16* p, float a, float b, float c, float d) { u32x2 w = {cvtpk(a, b), cvtpk(c, d)}; *(u32x2*)p = w; }
;   DI void operator()(int m, int n, f32x4 v) const { st4(dst + (size_t)m * ld + n, v[0], v[1], v[2], v[3]); }
; DI void ld4bf(const u16* p, float* o) { const u32x2 w = *(const u32x2*)p; o[0] = __uint_as_float(w[0] << 16); o[1] = __uint_as_float(w[0] & 0xffff0000u); o[2] = __uint_as_float(w[1] << 16); o[3] = __uint_as_float(w[1] & 0xffff0000u); }
;   DI void operator()(int m, int n, f32x4 v) const {
;     float x[4]; ld4bf(xb + (size_t)m * 1024 + n, x);
;     const f32x4 g = *(const f32x4*)(gate + n);
;     st4(xb + (size_t)m * 1024 + n, x[0] + g[0] * v[0], x[1] + g[1] * v[1], x[2] + g[2] * v[2], x[3] + g[3] * v[3]);
;   }
.LBB0_1228:
	s_or_b64 exec, exec, s[18:19]
	s_ashr_i32 s10, s10, 4
	s_add_i32 s10, s10, s25
	s_mul_hi_i32 s11, s10, 0x6000
	s_mulk_i32 s10, 0x6000
	v_cmp_gt_i32_e32 vcc, 3, v134
	s_add_u32 s10, s23, s10
	v_mul_lo_u32 v128, v134, s1
	v_cndmask_b32_e32 v129, v189, v190, vcc
	v_lshlrev_b32_e32 v134, 4, v132
	s_addc_u32 s11, s24, s11
	s_lshl_b32 s18, s60, 2
	v_add3_u32 v129, 16, v128, v129
	v_and_b32_e32 v128, 0x80, v134
	v_lshlrev_b32_e32 v130, 5, v133
	v_and_b32_e32 v133, 28, v135
	s_add_u32 s10, s10, s18
	v_or3_b32 v140, v128, v130, v133
	v_lshlrev_b32_e32 v130, 2, v132
	v_mul_u32_u24_e32 v132, 0x440, v131
	s_addc_u32 s11, s11, 0
	v_add3_u32 v130, v129, v130, v132
	s_add_u32 s12, s26, s12
	ds_write2_b32 v130, v104, v108 offset1:16
	ds_write2_b32 v130, v105, v109 offset0:68 offset1:84
	ds_write2_b32 v130, v106, v110 offset0:136 offset1:152
	ds_write2_b32 v130, v107, v111 offset0:204 offset1:220
	ds_write2_b32 v130, v120, v124 offset0:32 offset1:48
	ds_write2_b32 v130, v121, v125 offset0:100 offset1:116
	ds_write2_b32 v130, v122, v126 offset0:168 offset1:184
	ds_write2_b32 v130, v123, v127 offset0:236 offset1:252
	v_add_u32_e32 v123, 0x1000, v130
	s_addc_u32 s13, s27, s13
	s_lshl_b32 s18, s60, 1
	v_or_b32_e32 v128, v136, v131
	ds_write2_b32 v123, v96, v100 offset0:64 offset1:80
	ds_write2_b32 v123, v97, v101 offset0:132 offset1:148
	ds_write2_b32 v123, v98, v102 offset0:200 offset1:216
	v_mul_u32_u24_e32 v96, 0x110, v131
	s_add_u32 s12, s12, s18
	v_add3_u32 v124, v129, v134, v96
	v_ashrrev_i32_e32 v129, 31, v128
	s_addc_u32 s13, s13, 0
	v_add_u32_e32 v125, 0x1400, v130
	v_lshlrev_b64 v[120:121], 11, v[128:129]
	ds_write2_b32 v125, v99, v103 offset0:12 offset1:28
	ds_write2_b32 v123, v112, v116 offset0:96 offset1:112
	ds_write2_b32 v123, v113, v117 offset0:164 offset1:180
	ds_write2_b32 v123, v114, v118 offset0:232 offset1:248
	ds_write2_b32 v125, v115, v119 offset0:44 offset1:60
	v_lshl_add_u64 v[120:121], s[12:13], 0, v[120:121]
	v_lshlrev_b32_e32 v176, 1, v140
	s_waitcnt lgkmcnt(0)
	v_lshl_add_u64 v[120:121], v[120:121], 0, v[176:177]
	ds_read_b128 v[132:135], v124
	ds_read_b128 v[136:139], v124 offset:1088
	ds_read_b128 v[116:119], v124 offset:2176
	ds_read_b128 v[112:115], v124 offset:3264
	ds_read_b128 v[108:111], v124 offset:4352
	ds_read_b128 v[104:107], v124 offset:5440
	ds_read_b128 v[100:103], v124 offset:6528
	ds_read_b128 v[96:99], v124 offset:7616
	s_mov_b64 s[70:71], 0x2000
	global_load_dwordx2 v[192:193], v[120:121], off
	v_lshl_add_u64 v[208:209], v[120:121], 0, s[70:71]
	global_load_dwordx2 v[194:195], v[208:209], off
	v_lshl_add_u64 v[208:209], v[208:209], 0, s[70:71]
	global_load_dwordx2 v[196:197], v[208:209], off
	v_lshl_add_u64 v[208:209], v[208:209], 0, s[70:71]
	global_load_dwordx2 v[198:199], v[208:209], off
	v_lshl_add_u64 v[208:209], v[208:209], 0, s[70:71]
	global_load_dwordx2 v[200:201], v[208:209], off
	v_lshl_add_u64 v[208:209], v[208:209], 0, s[70:71]
	global_load_dwordx2 v[202:203], v[208:209], off
	v_lshl_add_u64 v[208:209], v[208:209], 0, s[70:71]
	global_load_dwordx2 v[204:205], v[208:209], off
	v_lshl_add_u64 v[208:209], v[208:209], 0, s[70:71]
	global_load_dwordx2 v[206:207], v[208:209], off
	v_lshlrev_b32_e32 v122, 2, v140
	global_load_dwordx4 v[212:215], v122, s[10:11]
	s_add_i32 s22, s22, s3
	s_waitcnt vmcnt(0)
	v_mov_b32_e32 v126, v192
	v_mov_b32_e32 v127, v193
	v_mov_b32_e32 v140, v212
	v_mov_b32_e32 v141, v213
	v_mov_b32_e32 v142, v214
	v_mov_b32_e32 v143, v215
	v_lshlrev_b32_e32 v129, 16, v126
	v_and_b32_e32 v126, 0xffff0000, v126
	v_lshlrev_b32_e32 v131, 16, v127
	v_and_b32_e32 v127, 0xffff0000, v127
	s_waitcnt lgkmcnt(7)
	v_fmac_f32_e32 v126, v133, v141
	v_fmac_f32_e32 v129, v132, v140
	v_fmac_f32_e32 v127, v135, v143
	v_cvt_pk_bf16_f32 v126, v129, v126
	v_fmac_f32_e32 v131, v134, v142
	v_cvt_pk_bf16_f32 v127, v131, v127
	global_store_dwordx2 v[120:121], v[126:127], off
	v_or_b32_e32 v126, 4, v128
	v_ashrrev_i32_e32 v127, 31, v126
	v_lshlrev_b64 v[126:127], 11, v[126:127]
	v_lshl_add_u64 v[126:127], s[12:13], 0, v[126:127]
	v_lshl_add_u64 v[126:127], v[126:127], 0, v[176:177]
	s_waitcnt vmcnt(7)
	v_mov_b32_e32 v132, v194
	v_mov_b32_e32 v133, v195
	v_lshlrev_b32_e32 v129, 16, v132
	v_and_b32_e32 v131, 0xffff0000, v132
	v_lshlrev_b32_e32 v140, 16, v133
	v_and_b32_e32 v141, 0xffff0000, v133
	s_waitcnt vmcnt(7) lgkmcnt(6)
	v_mov_b32_e32 v132, v212
	v_mov_b32_e32 v133, v213
	v_mov_b32_e32 v134, v214
	v_mov_b32_e32 v135, v215
	v_fmac_f32_e32 v129, v136, v132
	v_fmac_f32_e32 v131, v137, v133
	v_fmac_f32_e32 v140, v138, v134
	v_fmac_f32_e32 v141, v139, v135
	v_cvt_pk_bf16_f32 v132, v129, v131
	v_cvt_pk_bf16_f32 v133, v140, v141
	global_store_dwordx2 v[126:127], v[132:133], off
	v_or_b32_e32 v126, 8, v128
	v_ashrrev_i32_e32 v127, 31, v126
	v_lshlrev_b64 v[126:127], 11, v[126:127]
	v_lshl_add_u64 v[126:127], s[12:13], 0, v[126:127]
	v_lshl_add_u64 v[126:127], v[126:127], 0, v[176:177]
	s_waitcnt vmcnt(7)
	v_mov_b32_e32 v132, v196
	v_mov_b32_e32 v133, v197
	v_lshlrev_b32_e32 v129, 16, v132
	v_and_b32_e32 v131, 0xffff0000, v132
	v_lshlrev_b32_e32 v136, 16, v133
	v_and_b32_e32 v137, 0xffff0000, v133
	s_waitcnt vmcnt(7) lgkmcnt(5)
	v_mov_b32_e32 v132, v212
	v_mov_b32_e32 v133, v213
	v_mov_b32_e32 v134, v214
	v_mov_b32_e32 v135, v215
	v_fmac_f32_e32 v129, v116, v132
	v_fmac_f32_e32 v131, v117, v133
	v_cvt_pk_bf16_f32 v116, v129, v131
	v_fmac_f32_e32 v136, v118, v134
	v_fmac_f32_e32 v137, v119, v135
	v_cvt_pk_bf16_f32 v117, v136, v137
	global_store_dwordx2 v[126:127], v[116:117], off
	v_or_b32_e32 v116, 12, v128
	v_ashrrev_i32_e32 v117, 31, v116
	v_lshlrev_b64 v[116:117], 11, v[116:117]
	v_lshl_add_u64 v[116:117], s[12:13], 0, v[116:117]
	v_lshl_add_u64 v[126:127], v[116:117], 0, v[176:177]
	s_waitcnt vmcnt(7)
; DI void st4(u16* p, float a, float b, float c, float d) { u32x2 w = {cvtpk(a, b), cvtpk(c, d)}; *(u32x2*)p = w; }
;   DI void operator()(int m, int n, f32x4 v) const { st4(dst + (size_t)m * ld + n, v[0], v[1], v[2], v[3]); }
; DI void ld4bf(const u16* p, float* o) { const u32x2 w = *(const u32x2*)p; o[0] = __uint_as_float(w[0] << 16); o[1] = __uint_as_float(w[0] & 0xffff0000u); o[2] = __uint_as_float(w[1] << 16); o[3] = __uint_as_float(w[1] & 0xffff0000u); }
;   DI void operator()(int m, int n, f32x4 v) const {
;     float x[4]; ld4bf(xb + (size_t)m * 1024 + n, x);
;     const f32x4 g = *(const f32x4*)(gate + n);
;     st4(xb + (size_t)m * 1024 + n, x[0] + g[0] * v[0], x[1] + g[1] * v[1], x[2] + g[2] * v[2], x[3] + g[3] * v[3]);
;   }
	v_mov_b32_e32 v116, v198
	v_mov_b32_e32 v117, v199
	v_lshlrev_b32_e32 v129, 16, v116
	v_and_b32_e32 v131, 0xffff0000, v116
	v_lshlrev_b32_e32 v132, 16, v117
	v_and_b32_e32 v133, 0xffff0000, v117
	s_waitcnt vmcnt(7) lgkmcnt(4)
	v_mov_b32_e32 v116, v212
	v_mov_b32_e32 v117, v213
	v_mov_b32_e32 v118, v214
	v_mov_b32_e32 v119, v215
	v_fmac_f32_e32 v129, v112, v116
	v_fmac_f32_e32 v131, v113, v117
	v_cvt_pk_bf16_f32 v112, v129, v131
	v_fmac_f32_e32 v132, v114, v118
	v_fmac_f32_e32 v133, v115, v119
	v_cvt_pk_bf16_f32 v113, v132, v133
	global_store_dwordx2 v[126:127], v[112:113], off
	v_or_b32_e32 v112, 16, v128
	v_ashrrev_i32_e32 v113, 31, v112
	v_lshlrev_b64 v[112:113], 11, v[112:113]
	v_lshl_add_u64 v[112:113], s[12:13], 0, v[112:113]
	v_lshl_add_u64 v[116:117], v[112:113], 0, v[176:177]
	s_waitcnt vmcnt(7)
	v_mov_b32_e32 v112, v200
	v_mov_b32_e32 v113, v201
	v_lshlrev_b32_e32 v118, 16, v112
	v_and_b32_e32 v119, 0xffff0000, v112
	v_lshlrev_b32_e32 v126, 16, v113
	v_and_b32_e32 v127, 0xffff0000, v113
	s_waitcnt vmcnt(7) lgkmcnt(3)
	v_mov_b32_e32 v112, v212
	v_mov_b32_e32 v113, v213
	v_mov_b32_e32 v114, v214
	v_mov_b32_e32 v115, v215
	v_fmac_f32_e32 v118, v108, v112
	v_fmac_f32_e32 v119, v109, v113
	v_cvt_pk_bf16_f32 v108, v118, v119
	v_fmac_f32_e32 v126, v110, v114
	v_fmac_f32_e32 v127, v111, v115
	v_cvt_pk_bf16_f32 v109, v126, v127
	global_store_dwordx2 v[116:117], v[108:109], off
	v_or_b32_e32 v108, 20, v128
	v_ashrrev_i32_e32 v109, 31, v108
	v_lshlrev_b64 v[108:109], 11, v[108:109]
	v_lshl_add_u64 v[108:109], s[12:13], 0, v[108:109]
	v_lshl_add_u64 v[112:113], v[108:109], 0, v[176:177]
	s_waitcnt vmcnt(7)
	v_mov_b32_e32 v108, v202
	v_mov_b32_e32 v109, v203
	v_lshlrev_b32_e32 v114, 16, v108
	v_and_b32_e32 v115, 0xffff0000, v108
	v_lshlrev_b32_e32 v116, 16, v109
	v_and_b32_e32 v117, 0xffff0000, v109
	s_waitcnt vmcnt(7) lgkmcnt(2)
	v_mov_b32_e32 v108, v212
	v_mov_b32_e32 v109, v213
	v_mov_b32_e32 v110, v214
	v_mov_b32_e32 v111, v215
	v_fmac_f32_e32 v114, v104, v108
	v_fmac_f32_e32 v115, v105, v109
	v_cvt_pk_bf16_f32 v104, v114, v115
	v_fmac_f32_e32 v116, v106, v110
	v_fmac_f32_e32 v117, v107, v111
	v_cvt_pk_bf16_f32 v105, v116, v117
	global_store_dwordx2 v[112:113], v[104:105], off
	v_or_b32_e32 v104, 24, v128
	v_ashrrev_i32_e32 v105, 31, v104
	v_lshlrev_b64 v[104:105], 11, v[104:105]
	v_lshl_add_u64 v[104:105], s[12:13], 0, v[104:105]
	v_lshl_add_u64 v[108:109], v[104:105], 0, v[176:177]
	s_waitcnt vmcnt(7)
	v_mov_b32_e32 v104, v204
	v_mov_b32_e32 v105, v205
	v_lshlrev_b32_e32 v110, 16, v104
	v_and_b32_e32 v111, 0xffff0000, v104
	v_lshlrev_b32_e32 v112, 16, v105
	v_and_b32_e32 v113, 0xffff0000, v105
	s_waitcnt vmcnt(7) lgkmcnt(1)
	v_mov_b32_e32 v104, v212
	v_mov_b32_e32 v105, v213
	v_mov_b32_e32 v106, v214
	v_mov_b32_e32 v107, v215
	v_fmac_f32_e32 v110, v100, v104
	v_fmac_f32_e32 v111, v101, v105
	v_cvt_pk_bf16_f32 v100, v110, v111
	v_fmac_f32_e32 v112, v102, v106
	v_fmac_f32_e32 v113, v103, v107
	v_cvt_pk_bf16_f32 v101, v112, v113
	global_store_dwordx2 v[108:109], v[100:101], off
	v_or_b32_e32 v100, 28, v128
	v_ashrrev_i32_e32 v101, 31, v100
	v_lshlrev_b64 v[100:101], 11, v[100:101]
	v_lshl_add_u64 v[100:101], s[12:13], 0, v[100:101]
	v_lshl_add_u64 v[104:105], v[100:101], 0, v[176:177]
	s_waitcnt vmcnt(7)
	v_mov_b32_e32 v100, v206
	v_mov_b32_e32 v101, v207
	v_lshlrev_b32_e32 v106, 16, v100
	v_and_b32_e32 v107, 0xffff0000, v100
	v_lshlrev_b32_e32 v108, 16, v101
	v_and_b32_e32 v109, 0xffff0000, v101
	s_waitcnt vmcnt(7) lgkmcnt(0)
	v_mov_b32_e32 v100, v212
	v_mov_b32_e32 v101, v213
	v_mov_b32_e32 v102, v214
	v_mov_b32_e32 v103, v215
	v_fmac_f32_e32 v106, v96, v100
	v_fmac_f32_e32 v107, v97, v101
	v_cvt_pk_bf16_f32 v96, v106, v107
	v_fmac_f32_e32 v108, v98, v102
	v_fmac_f32_e32 v109, v99, v103
	v_cvt_pk_bf16_f32 v97, v108, v109
	global_store_dwordx2 v[104:105], v[96:97], off
	v_or_b32_e32 v96, 32, v128
	v_ashrrev_i32_e32 v97, 31, v96
	v_lshlrev_b64 v[96:97], 11, v[96:97]
	s_waitcnt lgkmcnt(0)
	ds_write2_b32 v130, v72, v76 offset1:16
	ds_write2_b32 v130, v73, v77 offset0:68 offset1:84
	ds_write2_b32 v130, v74, v78 offset0:136 offset1:152
	ds_write2_b32 v130, v75, v79 offset0:204 offset1:220
	ds_write2_b32 v130, v88, v92 offset0:32 offset1:48
	ds_write2_b32 v130, v89, v93 offset0:100 offset1:116
	ds_write2_b32 v130, v90, v94 offset0:168 offset1:184
	ds_write2_b32 v130, v91, v95 offset0:236 offset1:252
	ds_write2_b32 v123, v64, v68 offset0:64 offset1:80
	ds_write2_b32 v123, v65, v69 offset0:132 offset1:148
	ds_write2_b32 v123, v66, v70 offset0:200 offset1:216
	ds_write2_b32 v125, v67, v71 offset0:12 offset1:28
	ds_write2_b32 v123, v80, v84 offset0:96 offset1:112
	ds_write2_b32 v123, v81, v85 offset0:164 offset1:180
	ds_write2_b32 v123, v82, v86 offset0:232 offset1:248
	ds_write2_b32 v125, v83, v87 offset0:44 offset1:60
	v_lshl_add_u64 v[96:97], s[12:13], 0, v[96:97]
	s_waitcnt lgkmcnt(0)
	v_lshl_add_u64 v[100:101], v[96:97], 0, v[176:177]
	ds_read_b128 v[92:95], v124
	ds_read_b128 v[88:91], v124 offset:1088
	ds_read_b128 v[84:87], v124 offset:2176
	ds_read_b128 v[80:83], v124 offset:3264
	ds_read_b128 v[76:79], v124 offset:4352
	ds_read_b128 v[72:75], v124 offset:5440
	ds_read_b128 v[68:71], v124 offset:6528
	ds_read_b128 v[64:67], v124 offset:7616
	s_mov_b64 s[70:71], 0x2000
	global_load_dwordx2 v[192:193], v[100:101], off
	v_lshl_add_u64 v[208:209], v[100:101], 0, s[70:71]
	global_load_dwordx2 v[194:195], v[208:209], off
	v_lshl_add_u64 v[208:209], v[208:209], 0, s[70:71]
	global_load_dwordx2 v[196:197], v[208:209], off
	v_lshl_add_u64 v[208:209], v[208:209], 0, s[70:71]
	global_load_dwordx2 v[198:199], v[208:209], off
	v_lshl_add_u64 v[208:209], v[208:209], 0, s[70:71]
	global_load_dwordx2 v[200:201], v[208:209], off
	v_lshl_add_u64 v[208:209], v[208:209], 0, s[70:71]
	global_load_dwordx2 v[202:203], v[208:209], off
	v_lshl_add_u64 v[208:209], v[208:209], 0, s[70:71]
	global_load_dwordx2 v[204:205], v[208:209], off
	v_lshl_add_u64 v[208:209], v[208:209], 0, s[70:71]
	global_load_dwordx2 v[206:207], v[208:209], off
	s_waitcnt vmcnt(7)
; DI void st4(u16* p, float a, float b, float c, float d) { u32x2 w = {cvtpk(a, b), cvtpk(c, d)}; *(u32x2*)p = w; }
;   DI void operator()(int m, int n, f32x4 v) const { st4(dst + (size_t)m * ld + n, v[0], v[1], v[2], v[3]); }
; DI void ld4bf(const u16* p, float* o) { const u32x2 w = *(const u32x2*)p; o[0] = __uint_as_float(w[0] << 16); o[1] = __uint_as_float(w[0] & 0xffff0000u); o[2] = __uint_as_float(w[1] << 16); o[3] = __uint_as_float(w[1] & 0xffff0000u); }
;   DI void operator()(int m, int n, f32x4 v) const {
;     float x[4]; ld4bf(xb + (size_t)m * 1024 + n, x);
;     const f32x4 g = *(const f32x4*)(gate + n);
;     st4(xb + (size_t)m * 1024 + n, x[0] + g[0] * v[0], x[1] + g[1] * v[1], x[2] + g[2] * v[2], x[3] + g[3] * v[3]);
;   }
	v_mov_b32_e32 v96, v192
	v_mov_b32_e32 v97, v193
	v_lshlrev_b32_e32 v102, 16, v96
	v_and_b32_e32 v103, 0xffff0000, v96
	v_lshlrev_b32_e32 v104, 16, v97
	v_and_b32_e32 v105, 0xffff0000, v97
	s_waitcnt vmcnt(7) lgkmcnt(7)
	v_mov_b32_e32 v96, v212
	v_mov_b32_e32 v97, v213
	v_mov_b32_e32 v98, v214
	v_mov_b32_e32 v99, v215
	v_fmac_f32_e32 v102, v92, v96
	v_fmac_f32_e32 v103, v93, v97
	v_cvt_pk_bf16_f32 v92, v102, v103
	v_fmac_f32_e32 v104, v94, v98
	v_fmac_f32_e32 v105, v95, v99
	v_cvt_pk_bf16_f32 v93, v104, v105
	global_store_dwordx2 v[100:101], v[92:93], off
	v_or_b32_e32 v92, 36, v128
	v_ashrrev_i32_e32 v93, 31, v92
	v_lshlrev_b64 v[92:93], 11, v[92:93]
	v_lshl_add_u64 v[92:93], s[12:13], 0, v[92:93]
	v_lshl_add_u64 v[96:97], v[92:93], 0, v[176:177]
	s_waitcnt vmcnt(7)
	v_mov_b32_e32 v92, v194
	v_mov_b32_e32 v93, v195
	v_lshlrev_b32_e32 v98, 16, v92
	v_and_b32_e32 v99, 0xffff0000, v92
	v_lshlrev_b32_e32 v100, 16, v93
	v_and_b32_e32 v101, 0xffff0000, v93
	s_waitcnt vmcnt(7) lgkmcnt(6)
	v_mov_b32_e32 v92, v212
	v_mov_b32_e32 v93, v213
	v_mov_b32_e32 v94, v214
	v_mov_b32_e32 v95, v215
	v_fmac_f32_e32 v98, v88, v92
	v_fmac_f32_e32 v99, v89, v93
	v_cvt_pk_bf16_f32 v88, v98, v99
	v_fmac_f32_e32 v100, v90, v94
	v_fmac_f32_e32 v101, v91, v95
	v_cvt_pk_bf16_f32 v89, v100, v101
	global_store_dwordx2 v[96:97], v[88:89], off
	v_or_b32_e32 v88, 40, v128
	v_ashrrev_i32_e32 v89, 31, v88
	v_lshlrev_b64 v[88:89], 11, v[88:89]
	v_lshl_add_u64 v[88:89], s[12:13], 0, v[88:89]
	v_lshl_add_u64 v[92:93], v[88:89], 0, v[176:177]
	s_waitcnt vmcnt(7)
	v_mov_b32_e32 v88, v196
	v_mov_b32_e32 v89, v197
	v_lshlrev_b32_e32 v94, 16, v88
	v_and_b32_e32 v95, 0xffff0000, v88
	v_lshlrev_b32_e32 v96, 16, v89
	v_and_b32_e32 v97, 0xffff0000, v89
	s_waitcnt vmcnt(7) lgkmcnt(5)
	v_mov_b32_e32 v88, v212
	v_mov_b32_e32 v89, v213
	v_mov_b32_e32 v90, v214
	v_mov_b32_e32 v91, v215
	v_fmac_f32_e32 v94, v84, v88
	v_fmac_f32_e32 v95, v85, v89
	v_cvt_pk_bf16_f32 v84, v94, v95
	v_fmac_f32_e32 v96, v86, v90
	v_fmac_f32_e32 v97, v87, v91
	v_cvt_pk_bf16_f32 v85, v96, v97
	global_store_dwordx2 v[92:93], v[84:85], off
	v_or_b32_e32 v84, 44, v128
	v_ashrrev_i32_e32 v85, 31, v84
	v_lshlrev_b64 v[84:85], 11, v[84:85]
	v_lshl_add_u64 v[84:85], s[12:13], 0, v[84:85]
	v_lshl_add_u64 v[88:89], v[84:85], 0, v[176:177]
	s_waitcnt vmcnt(7)
	v_mov_b32_e32 v84, v198
	v_mov_b32_e32 v85, v199
	v_lshlrev_b32_e32 v90, 16, v84
	v_and_b32_e32 v91, 0xffff0000, v84
	v_lshlrev_b32_e32 v92, 16, v85
	v_and_b32_e32 v93, 0xffff0000, v85
	s_waitcnt vmcnt(7) lgkmcnt(4)
	v_mov_b32_e32 v84, v212
	v_mov_b32_e32 v85, v213
	v_mov_b32_e32 v86, v214
	v_mov_b32_e32 v87, v215
	v_fmac_f32_e32 v90, v80, v84
	v_fmac_f32_e32 v91, v81, v85
	v_cvt_pk_bf16_f32 v80, v90, v91
	v_fmac_f32_e32 v92, v82, v86
	v_fmac_f32_e32 v93, v83, v87
	v_cvt_pk_bf16_f32 v81, v92, v93
	global_store_dwordx2 v[88:89], v[80:81], off
	v_or_b32_e32 v80, 48, v128
	v_ashrrev_i32_e32 v81, 31, v80
	v_lshlrev_b64 v[80:81], 11, v[80:81]
	v_lshl_add_u64 v[80:81], s[12:13], 0, v[80:81]
	v_lshl_add_u64 v[84:85], v[80:81], 0, v[176:177]
	s_waitcnt vmcnt(7)
	v_mov_b32_e32 v80, v200
	v_mov_b32_e32 v81, v201
	v_lshlrev_b32_e32 v86, 16, v80
	v_and_b32_e32 v87, 0xffff0000, v80
	v_lshlrev_b32_e32 v88, 16, v81
	v_and_b32_e32 v89, 0xffff0000, v81
	s_waitcnt vmcnt(7) lgkmcnt(3)
	v_mov_b32_e32 v80, v212
	v_mov_b32_e32 v81, v213
	v_mov_b32_e32 v82, v214
	v_mov_b32_e32 v83, v215
	v_fmac_f32_e32 v86, v76, v80
	v_fmac_f32_e32 v87, v77, v81
	v_cvt_pk_bf16_f32 v76, v86, v87
	v_fmac_f32_e32 v88, v78, v82
	v_fmac_f32_e32 v89, v79, v83
	v_cvt_pk_bf16_f32 v77, v88, v89
	global_store_dwordx2 v[84:85], v[76:77], off
	v_or_b32_e32 v76, 52, v128
	v_ashrrev_i32_e32 v77, 31, v76
	v_lshlrev_b64 v[76:77], 11, v[76:77]
	v_lshl_add_u64 v[76:77], s[12:13], 0, v[76:77]
	v_lshl_add_u64 v[80:81], v[76:77], 0, v[176:177]
	s_waitcnt vmcnt(7)
	v_mov_b32_e32 v76, v202
	v_mov_b32_e32 v77, v203
	v_lshlrev_b32_e32 v82, 16, v76
	v_and_b32_e32 v83, 0xffff0000, v76
	v_lshlrev_b32_e32 v84, 16, v77
	v_and_b32_e32 v85, 0xffff0000, v77
	s_waitcnt vmcnt(7) lgkmcnt(2)
	v_mov_b32_e32 v76, v212
	v_mov_b32_e32 v77, v213
	v_mov_b32_e32 v78, v214
	v_mov_b32_e32 v79, v215
	v_fmac_f32_e32 v82, v72, v76
	v_fmac_f32_e32 v83, v73, v77
	v_cvt_pk_bf16_f32 v72, v82, v83
	v_fmac_f32_e32 v84, v74, v78
	v_fmac_f32_e32 v85, v75, v79
	v_cvt_pk_bf16_f32 v73, v84, v85
	global_store_dwordx2 v[80:81], v[72:73], off
	v_or_b32_e32 v72, 56, v128
	v_ashrrev_i32_e32 v73, 31, v72
	v_lshlrev_b64 v[72:73], 11, v[72:73]
	v_lshl_add_u64 v[72:73], s[12:13], 0, v[72:73]
	v_lshl_add_u64 v[76:77], v[72:73], 0, v[176:177]
	s_waitcnt vmcnt(7)
	v_mov_b32_e32 v72, v204
	v_mov_b32_e32 v73, v205
	v_lshlrev_b32_e32 v78, 16, v72
	v_and_b32_e32 v79, 0xffff0000, v72
	v_lshlrev_b32_e32 v80, 16, v73
	v_and_b32_e32 v81, 0xffff0000, v73
	s_waitcnt vmcnt(7) lgkmcnt(1)
	v_mov_b32_e32 v72, v212
	v_mov_b32_e32 v73, v213
	v_mov_b32_e32 v74, v214
	v_mov_b32_e32 v75, v215
	v_fmac_f32_e32 v78, v68, v72
	v_fmac_f32_e32 v79, v69, v73
	v_cvt_pk_bf16_f32 v68, v78, v79
	v_fmac_f32_e32 v80, v70, v74
	v_fmac_f32_e32 v81, v71, v75
	v_cvt_pk_bf16_f32 v69, v80, v81
	global_store_dwordx2 v[76:77], v[68:69], off
	v_or_b32_e32 v68, 60, v128
	v_ashrrev_i32_e32 v69, 31, v68
	v_lshlrev_b64 v[68:69], 11, v[68:69]
	v_lshl_add_u64 v[68:69], s[12:13], 0, v[68:69]
	v_lshl_add_u64 v[72:73], v[68:69], 0, v[176:177]
	s_mov_b32 s12, 0x50000
	s_waitcnt vmcnt(7)
	v_mov_b32_e32 v68, v206
	v_mov_b32_e32 v69, v207
	v_lshlrev_b32_e32 v74, 16, v68
	v_and_b32_e32 v75, 0xffff0000, v68
	v_lshlrev_b32_e32 v76, 16, v69
	v_and_b32_e32 v77, 0xffff0000, v69
	s_waitcnt vmcnt(7) lgkmcnt(0)
; DI void st4(u16* p, float a, float b, float c, float d) { u32x2 w = {cvtpk(a, b), cvtpk(c, d)}; *(u32x2*)p = w; }
;   DI void operator()(int m, int n, f32x4 v) const { st4(dst + (size_t)m * ld + n, v[0], v[1], v[2], v[3]); }
; DI void ld4bf(const u16* p, float* o) { const u32x2 w = *(const u32x2*)p; o[0] = __uint_as_float(w[0] << 16); o[1] = __uint_as_float(w[0] & 0xffff0000u); o[2] = __uint_as_float(w[1] << 16); o[3] = __uint_as_float(w[1] & 0xffff0000u); }
;   DI void operator()(int m, int n, f32x4 v) const {
;     float x[4]; ld4bf(xb + (size_t)m * 1024 + n, x);
;     const f32x4 g = *(const f32x4*)(gate + n);
;     st4(xb + (size_t)m * 1024 + n, x[0] + g[0] * v[0], x[1] + g[1] * v[1], x[2] + g[2] * v[2], x[3] + g[3] * v[3]);
;   }
	v_mov_b32_e32 v68, v212
	v_mov_b32_e32 v69, v213
	v_mov_b32_e32 v70, v214
	v_mov_b32_e32 v71, v215
	v_fmac_f32_e32 v74, v64, v68
	v_fmac_f32_e32 v75, v65, v69
	v_fmac_f32_e32 v76, v66, v70
	v_fmac_f32_e32 v77, v67, v71
	v_cvt_pk_bf16_f32 v64, v74, v75
	v_cvt_pk_bf16_f32 v65, v76, v77
	global_store_dwordx2 v[72:73], v[64:65], off
	s_waitcnt lgkmcnt(0)
	ds_write2_b32 v130, v40, v44 offset1:16
	ds_write2_b32 v130, v41, v45 offset0:68 offset1:84
	ds_write2_b32 v130, v42, v46 offset0:136 offset1:152
	ds_write2_b32 v130, v43, v47 offset0:204 offset1:220
	ds_write2_b32 v130, v56, v60 offset0:32 offset1:48
	ds_write2_b32 v130, v57, v61 offset0:100 offset1:116
	ds_write2_b32 v130, v58, v62 offset0:168 offset1:184
	ds_write2_b32 v130, v59, v63 offset0:236 offset1:252
	ds_write2_b32 v123, v32, v36 offset0:64 offset1:80
	ds_write2_b32 v123, v33, v37 offset0:132 offset1:148
	ds_write2_b32 v123, v34, v38 offset0:200 offset1:216
	ds_write2_b32 v125, v35, v39 offset0:12 offset1:28
	ds_write2_b32 v123, v48, v52 offset0:96 offset1:112
	ds_write2_b32 v123, v49, v53 offset0:164 offset1:180
	ds_write2_b32 v123, v50, v54 offset0:232 offset1:248
	ds_write2_b32 v125, v51, v55 offset0:44 offset1:60
	v_add_co_u32_e32 v68, vcc, s90, v120
	s_waitcnt lgkmcnt(0)
	ds_read_b128 v[60:63], v124
	ds_read_b128 v[56:59], v124 offset:1088
	ds_read_b128 v[52:55], v124 offset:2176
	ds_read_b128 v[48:51], v124 offset:3264
	ds_read_b128 v[44:47], v124 offset:4352
	ds_read_b128 v[40:43], v124 offset:5440
	ds_read_b128 v[36:39], v124 offset:6528
	ds_read_b128 v[32:35], v124 offset:7616
	v_addc_co_u32_e32 v69, vcc, 0, v121, vcc
	s_mov_b64 s[70:71], 0x2000
	global_load_dwordx2 v[192:193], v[68:69], off
	v_lshl_add_u64 v[208:209], v[68:69], 0, s[70:71]
	global_load_dwordx2 v[194:195], v[208:209], off
	v_lshl_add_u64 v[208:209], v[208:209], 0, s[70:71]
	global_load_dwordx2 v[196:197], v[208:209], off
	v_lshl_add_u64 v[208:209], v[208:209], 0, s[70:71]
	global_load_dwordx2 v[198:199], v[208:209], off
	v_lshl_add_u64 v[208:209], v[208:209], 0, s[70:71]
	global_load_dwordx2 v[200:201], v[208:209], off
	v_lshl_add_u64 v[208:209], v[208:209], 0, s[70:71]
	global_load_dwordx2 v[202:203], v[208:209], off
	v_lshl_add_u64 v[208:209], v[208:209], 0, s[70:71]
	global_load_dwordx2 v[204:205], v[208:209], off
	v_lshl_add_u64 v[208:209], v[208:209], 0, s[70:71]
	global_load_dwordx2 v[206:207], v[208:209], off
	s_waitcnt vmcnt(7)
	v_mov_b32_e32 v64, v192
	v_mov_b32_e32 v65, v193
	v_lshlrev_b32_e32 v70, 16, v64
	v_and_b32_e32 v71, 0xffff0000, v64
	v_lshlrev_b32_e32 v72, 16, v65
	v_and_b32_e32 v73, 0xffff0000, v65
	s_waitcnt vmcnt(7) lgkmcnt(7)
	v_mov_b32_e32 v64, v212
	v_mov_b32_e32 v65, v213
	v_mov_b32_e32 v66, v214
	v_mov_b32_e32 v67, v215
	v_fmac_f32_e32 v70, v60, v64
	v_add_co_u32_e32 v64, vcc, s91, v120
	v_fmac_f32_e32 v71, v61, v65
	v_fmac_f32_e32 v72, v62, v66
	v_fmac_f32_e32 v73, v63, v67
	v_cvt_pk_bf16_f32 v60, v70, v71
	v_cvt_pk_bf16_f32 v61, v72, v73
	v_addc_co_u32_e32 v65, vcc, 0, v121, vcc
	global_store_dwordx2 v[68:69], v[60:61], off
	s_waitcnt vmcnt(7)
	v_mov_b32_e32 v60, v194
	v_mov_b32_e32 v61, v195
	v_lshlrev_b32_e32 v66, 16, v60
	v_and_b32_e32 v67, 0xffff0000, v60
	v_lshlrev_b32_e32 v68, 16, v61
	v_and_b32_e32 v69, 0xffff0000, v61
	s_waitcnt vmcnt(7) lgkmcnt(6)
	v_mov_b32_e32 v60, v212
	v_mov_b32_e32 v61, v213
	v_mov_b32_e32 v62, v214
	v_mov_b32_e32 v63, v215
	v_fmac_f32_e32 v66, v56, v60
	v_add_co_u32_e32 v60, vcc, s92, v120
	v_fmac_f32_e32 v67, v57, v61
	v_fmac_f32_e32 v68, v58, v62
	v_fmac_f32_e32 v69, v59, v63
	v_cvt_pk_bf16_f32 v56, v66, v67
	v_cvt_pk_bf16_f32 v57, v68, v69
	v_addc_co_u32_e32 v61, vcc, 0, v121, vcc
	global_store_dwordx2 v[64:65], v[56:57], off
	s_waitcnt vmcnt(7)
	v_mov_b32_e32 v56, v196
	v_mov_b32_e32 v57, v197
	v_lshlrev_b32_e32 v62, 16, v56
	v_and_b32_e32 v63, 0xffff0000, v56
	v_lshlrev_b32_e32 v64, 16, v57
	v_and_b32_e32 v65, 0xffff0000, v57
	s_waitcnt vmcnt(7) lgkmcnt(5)
	v_mov_b32_e32 v56, v212
	v_mov_b32_e32 v57, v213
	v_mov_b32_e32 v58, v214
	v_mov_b32_e32 v59, v215
	v_fmac_f32_e32 v62, v52, v56
	v_add_co_u32_e32 v56, vcc, s79, v120
	v_fmac_f32_e32 v63, v53, v57
	v_fmac_f32_e32 v64, v54, v58
	v_fmac_f32_e32 v65, v55, v59
	v_cvt_pk_bf16_f32 v52, v62, v63
	v_cvt_pk_bf16_f32 v53, v64, v65
	v_addc_co_u32_e32 v57, vcc, 0, v121, vcc
	global_store_dwordx2 v[60:61], v[52:53], off
	s_waitcnt vmcnt(7)
	v_mov_b32_e32 v52, v198
	v_mov_b32_e32 v53, v199
	v_lshlrev_b32_e32 v58, 16, v52
	v_and_b32_e32 v59, 0xffff0000, v52
	v_lshlrev_b32_e32 v60, 16, v53
	v_and_b32_e32 v61, 0xffff0000, v53
	s_waitcnt vmcnt(7) lgkmcnt(4)
	v_mov_b32_e32 v52, v212
	v_mov_b32_e32 v53, v213
	v_mov_b32_e32 v54, v214
	v_mov_b32_e32 v55, v215
	v_fmac_f32_e32 v58, v48, v52
	v_add_co_u32_e32 v52, vcc, s78, v120
	v_fmac_f32_e32 v59, v49, v53
	v_fmac_f32_e32 v60, v50, v54
	v_fmac_f32_e32 v61, v51, v55
	v_cvt_pk_bf16_f32 v48, v58, v59
	v_cvt_pk_bf16_f32 v49, v60, v61
	v_addc_co_u32_e32 v53, vcc, 0, v121, vcc
	global_store_dwordx2 v[56:57], v[48:49], off
	s_waitcnt vmcnt(7)
	v_mov_b32_e32 v48, v200
	v_mov_b32_e32 v49, v201
	v_lshlrev_b32_e32 v54, 16, v48
	v_and_b32_e32 v55, 0xffff0000, v48
	v_lshlrev_b32_e32 v56, 16, v49
	v_and_b32_e32 v57, 0xffff0000, v49
	s_waitcnt vmcnt(7) lgkmcnt(3)
	v_mov_b32_e32 v48, v212
	v_mov_b32_e32 v49, v213
	v_mov_b32_e32 v50, v214
	v_mov_b32_e32 v51, v215
	v_fmac_f32_e32 v54, v44, v48
	v_add_co_u32_e32 v48, vcc, s88, v120
	v_fmac_f32_e32 v55, v45, v49
	v_fmac_f32_e32 v56, v46, v50
	v_fmac_f32_e32 v57, v47, v51
	v_cvt_pk_bf16_f32 v44, v54, v55
	v_cvt_pk_bf16_f32 v45, v56, v57
	v_addc_co_u32_e32 v49, vcc, 0, v121, vcc
	global_store_dwordx2 v[52:53], v[44:45], off
	s_waitcnt vmcnt(7)
; DI void st4(u16* p, float a, float b, float c, float d) { u32x2 w = {cvtpk(a, b), cvtpk(c, d)}; *(u32x2*)p = w; }
;   DI void operator()(int m, int n, f32x4 v) const { st4(dst + (size_t)m * ld + n, v[0], v[1], v[2], v[3]); }
; DI void ld4bf(const u16* p, float* o) { const u32x2 w = *(const u32x2*)p; o[0] = __uint_as_float(w[0] << 16); o[1] = __uint_as_float(w[0] & 0xffff0000u); o[2] = __uint_as_float(w[1] << 16); o[3] = __uint_as_float(w[1] & 0xffff0000u); }
;   DI void operator()(int m, int n, f32x4 v) const {
;     float x[4]; ld4bf(xb + (size_t)m * 1024 + n, x);
;     const f32x4 g = *(const f32x4*)(gate + n);
;     st4(xb + (size_t)m * 1024 + n, x[0] + g[0] * v[0], x[1] + g[1] * v[1], x[2] + g[2] * v[2], x[3] + g[3] * v[3]);
;   }
	v_mov_b32_e32 v44, v202
	v_mov_b32_e32 v45, v203
	v_lshlrev_b32_e32 v50, 16, v44
	v_and_b32_e32 v51, 0xffff0000, v44
	v_lshlrev_b32_e32 v52, 16, v45
	v_and_b32_e32 v53, 0xffff0000, v45
	s_waitcnt vmcnt(7) lgkmcnt(2)
	v_mov_b32_e32 v44, v212
	v_mov_b32_e32 v45, v213
	v_mov_b32_e32 v46, v214
	v_mov_b32_e32 v47, v215
	v_fmac_f32_e32 v50, v40, v44
	v_add_co_u32_e32 v44, vcc, s94, v120
	v_fmac_f32_e32 v51, v41, v45
	v_fmac_f32_e32 v52, v42, v46
	v_fmac_f32_e32 v53, v43, v47
	v_cvt_pk_bf16_f32 v40, v50, v51
	v_cvt_pk_bf16_f32 v41, v52, v53
	v_addc_co_u32_e32 v45, vcc, 0, v121, vcc
	global_store_dwordx2 v[48:49], v[40:41], off
	s_waitcnt vmcnt(7)
	v_mov_b32_e32 v40, v204
	v_mov_b32_e32 v41, v205
	v_lshlrev_b32_e32 v46, 16, v40
	v_and_b32_e32 v47, 0xffff0000, v40
	v_lshlrev_b32_e32 v48, 16, v41
	v_and_b32_e32 v49, 0xffff0000, v41
	s_waitcnt vmcnt(7) lgkmcnt(1)
	v_mov_b32_e32 v40, v212
	v_mov_b32_e32 v41, v213
	v_mov_b32_e32 v42, v214
	v_mov_b32_e32 v43, v215
	v_fmac_f32_e32 v46, v36, v40
	v_add_co_u32_e32 v40, vcc, s95, v120
	v_fmac_f32_e32 v47, v37, v41
	v_fmac_f32_e32 v48, v38, v42
	v_fmac_f32_e32 v49, v39, v43
	v_cvt_pk_bf16_f32 v36, v46, v47
	v_cvt_pk_bf16_f32 v37, v48, v49
	v_addc_co_u32_e32 v41, vcc, 0, v121, vcc
	global_store_dwordx2 v[44:45], v[36:37], off
	s_waitcnt vmcnt(7)
	v_mov_b32_e32 v36, v206
	v_mov_b32_e32 v37, v207
	v_lshlrev_b32_e32 v42, 16, v36
	v_and_b32_e32 v43, 0xffff0000, v36
	v_lshlrev_b32_e32 v44, 16, v37
	v_and_b32_e32 v45, 0xffff0000, v37
	s_waitcnt vmcnt(7) lgkmcnt(0)
	v_mov_b32_e32 v36, v212
	v_mov_b32_e32 v37, v213
	v_mov_b32_e32 v38, v214
	v_mov_b32_e32 v39, v215
	v_fmac_f32_e32 v42, v32, v36
	v_fmac_f32_e32 v43, v33, v37
	v_fmac_f32_e32 v44, v34, v38
	v_fmac_f32_e32 v45, v35, v39
	v_cvt_pk_bf16_f32 v32, v42, v43
	v_cvt_pk_bf16_f32 v33, v44, v45
	global_store_dwordx2 v[40:41], v[32:33], off
	s_waitcnt lgkmcnt(0)
	ds_write2_b32 v130, v8, v12 offset1:16
	ds_write2_b32 v130, v9, v13 offset0:68 offset1:84
	ds_write2_b32 v130, v10, v14 offset0:136 offset1:152
	ds_write2_b32 v130, v11, v15 offset0:204 offset1:220
	ds_write2_b32 v130, v24, v28 offset0:32 offset1:48
	ds_write2_b32 v130, v25, v29 offset0:100 offset1:116
	ds_write2_b32 v130, v26, v30 offset0:168 offset1:184
	ds_write2_b32 v130, v27, v31 offset0:236 offset1:252
	ds_write2_b32 v123, v0, v4 offset0:64 offset1:80
	ds_write2_b32 v123, v1, v5 offset0:132 offset1:148
	ds_write2_b32 v123, v2, v6 offset0:200 offset1:216
	ds_write2_b32 v125, v3, v7 offset0:12 offset1:28
	ds_write2_b32 v123, v16, v20 offset0:96 offset1:112
	ds_write2_b32 v123, v17, v21 offset0:164 offset1:180
	ds_write2_b32 v123, v18, v22 offset0:232 offset1:248
	ds_write2_b32 v125, v19, v23 offset0:44 offset1:60
	v_add_co_u32_e32 v36, vcc, s12, v120
	s_waitcnt lgkmcnt(0)
	ds_read_b128 v[28:31], v124
	ds_read_b128 v[24:27], v124 offset:1088
	ds_read_b128 v[20:23], v124 offset:2176
	ds_read_b128 v[16:19], v124 offset:3264
	ds_read_b128 v[12:15], v124 offset:4352
	ds_read_b128 v[8:11], v124 offset:5440
	ds_read_b128 v[4:7], v124 offset:6528
	ds_read_b128 v[0:3], v124 offset:7616
	v_addc_co_u32_e32 v37, vcc, 0, v121, vcc
	s_mov_b64 s[70:71], 0x2000
	global_load_dwordx2 v[192:193], v[36:37], off
	v_lshl_add_u64 v[208:209], v[36:37], 0, s[70:71]
	global_load_dwordx2 v[194:195], v[208:209], off
	v_lshl_add_u64 v[208:209], v[208:209], 0, s[70:71]
	global_load_dwordx2 v[196:197], v[208:209], off
	v_lshl_add_u64 v[208:209], v[208:209], 0, s[70:71]
	global_load_dwordx2 v[198:199], v[208:209], off
	v_lshl_add_u64 v[208:209], v[208:209], 0, s[70:71]
	global_load_dwordx2 v[200:201], v[208:209], off
	v_lshl_add_u64 v[208:209], v[208:209], 0, s[70:71]
	global_load_dwordx2 v[202:203], v[208:209], off
	v_lshl_add_u64 v[208:209], v[208:209], 0, s[70:71]
	global_load_dwordx2 v[204:205], v[208:209], off
	v_lshl_add_u64 v[208:209], v[208:209], 0, s[70:71]
	global_load_dwordx2 v[206:207], v[208:209], off
	s_mov_b32 s12, 0x52000
	s_waitcnt vmcnt(7)
	v_mov_b32_e32 v32, v192
	v_mov_b32_e32 v33, v193
	v_lshlrev_b32_e32 v38, 16, v32
	v_and_b32_e32 v39, 0xffff0000, v32
	v_lshlrev_b32_e32 v40, 16, v33
	v_and_b32_e32 v41, 0xffff0000, v33
	s_waitcnt vmcnt(7) lgkmcnt(7)
	v_mov_b32_e32 v32, v212
	v_mov_b32_e32 v33, v213
	v_mov_b32_e32 v34, v214
	v_mov_b32_e32 v35, v215
	v_fmac_f32_e32 v38, v28, v32
	v_add_co_u32_e32 v32, vcc, s12, v120
	v_fmac_f32_e32 v39, v29, v33
	v_fmac_f32_e32 v40, v30, v34
	v_fmac_f32_e32 v41, v31, v35
	v_cvt_pk_bf16_f32 v28, v38, v39
	v_cvt_pk_bf16_f32 v29, v40, v41
	v_addc_co_u32_e32 v33, vcc, 0, v121, vcc
	global_store_dwordx2 v[36:37], v[28:29], off
	s_mov_b32 s12, 0x54000
	s_waitcnt vmcnt(7)
	v_mov_b32_e32 v28, v194
	v_mov_b32_e32 v29, v195
	v_lshlrev_b32_e32 v34, 16, v28
	v_and_b32_e32 v35, 0xffff0000, v28
	v_lshlrev_b32_e32 v36, 16, v29
	v_and_b32_e32 v37, 0xffff0000, v29
	s_waitcnt vmcnt(7) lgkmcnt(6)
; DI void st4(u16* p, float a, float b, float c, float d) { u32x2 w = {cvtpk(a, b), cvtpk(c, d)}; *(u32x2*)p = w; }
;   DI void operator()(int m, int n, f32x4 v) const { st4(dst + (size_t)m * ld + n, v[0], v[1], v[2], v[3]); }
; DI void ld4bf(const u16* p, float* o) { const u32x2 w = *(const u32x2*)p; o[0] = __uint_as_float(w[0] << 16); o[1] = __uint_as_float(w[0] & 0xffff0000u); o[2] = __uint_as_float(w[1] << 16); o[3] = __uint_as_float(w[1] & 0xffff0000u); }
; #define TILE_LOOP(q, x, NPX) for (int lin_ = (nb == 256 ? (bid >> 3) : bid), q = (nb == 256 ? lin_ : lin_ / 8), x = (nb == 256 ? (bid & 7) : lin_ % 8); \
;     (nb == 256 ? q < (NPX) : lin_ < 8 * (NPX)); lin_ += (nb == 256 ? 32 : nb), q = (nb == 256 ? lin_ : lin_ / 8), x = (nb == 256 ? x : lin_ % 8))
;   DI void operator()(int m, int n, f32x4 v) const {
;     float x[4]; ld4bf(xb + (size_t)m * 1024 + n, x);
;     const f32x4 g = *(const f32x4*)(gate + n);
;     st4(xb + (size_t)m * 1024 + n, x[0] + g[0] * v[0], x[1] + g[1] * v[1], x[2] + g[2] * v[2], x[3] + g[3] * v[3]);
;   }
; DI void phase_resid_gemm(int layer, int g, int kind, char* smem) {
;     ...
;   TILE_LOOP(q, x, npx) {
;     const int mt = (q >> 2) * 8 + x, nt = q & 3, s = seq0 + (mt >> 4);
;     const size_t to = (size_t)mt * 256 * 1024 + nt * 256;
;     const float* gate = modl + (size_t)s * 6144 + goff + nt * 256;
;     if (kind == 0) { EpiResidF e{xin + to, xb + to, gate}; gemm_tile<false>(A + (size_t)mt * 256 * K, K, B + (size_t)(nt * 256) * K, K, K, (u16*)smem, e); }
;     else { EpiResidB e{xb + to, gate}; gemm_tile<false>(A + (size_t)mt * 256 * K, K, B + (size_t)(nt * 256) * K, K, K, (u16*)smem, e); }
	v_mov_b32_e32 v28, v212
	v_mov_b32_e32 v29, v213
	v_mov_b32_e32 v30, v214
	v_mov_b32_e32 v31, v215
	v_fmac_f32_e32 v34, v24, v28
	v_add_co_u32_e32 v28, vcc, s12, v120
	v_fmac_f32_e32 v35, v25, v29
	v_fmac_f32_e32 v36, v26, v30
	v_fmac_f32_e32 v37, v27, v31
	v_cvt_pk_bf16_f32 v24, v34, v35
	v_cvt_pk_bf16_f32 v25, v36, v37
	v_addc_co_u32_e32 v29, vcc, 0, v121, vcc
	global_store_dwordx2 v[32:33], v[24:25], off
	s_mov_b32 s12, 0x56000
	s_waitcnt vmcnt(7)
	v_mov_b32_e32 v24, v196
	v_mov_b32_e32 v25, v197
	v_lshlrev_b32_e32 v30, 16, v24
	v_and_b32_e32 v31, 0xffff0000, v24
	v_lshlrev_b32_e32 v32, 16, v25
	v_and_b32_e32 v33, 0xffff0000, v25
	s_waitcnt vmcnt(7) lgkmcnt(5)
	v_mov_b32_e32 v24, v212
	v_mov_b32_e32 v25, v213
	v_mov_b32_e32 v26, v214
	v_mov_b32_e32 v27, v215
	v_fmac_f32_e32 v30, v20, v24
	v_add_co_u32_e32 v24, vcc, s12, v120
	v_fmac_f32_e32 v31, v21, v25
	v_fmac_f32_e32 v32, v22, v26
	v_fmac_f32_e32 v33, v23, v27
	v_cvt_pk_bf16_f32 v20, v30, v31
	v_cvt_pk_bf16_f32 v21, v32, v33
	v_addc_co_u32_e32 v25, vcc, 0, v121, vcc
	global_store_dwordx2 v[28:29], v[20:21], off
	s_mov_b32 s12, 0x58000
	s_waitcnt vmcnt(7)
	v_mov_b32_e32 v20, v198
	v_mov_b32_e32 v21, v199
	v_lshlrev_b32_e32 v26, 16, v20
	v_and_b32_e32 v27, 0xffff0000, v20
	v_lshlrev_b32_e32 v28, 16, v21
	v_and_b32_e32 v29, 0xffff0000, v21
	s_waitcnt vmcnt(7) lgkmcnt(4)
	v_mov_b32_e32 v20, v212
	v_mov_b32_e32 v21, v213
	v_mov_b32_e32 v22, v214
	v_mov_b32_e32 v23, v215
	v_fmac_f32_e32 v26, v16, v20
	v_add_co_u32_e32 v20, vcc, s12, v120
	v_fmac_f32_e32 v27, v17, v21
	v_fmac_f32_e32 v28, v18, v22
	v_fmac_f32_e32 v29, v19, v23
	v_cvt_pk_bf16_f32 v16, v26, v27
	v_cvt_pk_bf16_f32 v17, v28, v29
	v_addc_co_u32_e32 v21, vcc, 0, v121, vcc
	global_store_dwordx2 v[24:25], v[16:17], off
	s_mov_b32 s12, 0x5a000
	s_waitcnt vmcnt(7)
	v_mov_b32_e32 v16, v200
	v_mov_b32_e32 v17, v201
	v_lshlrev_b32_e32 v22, 16, v16
	v_and_b32_e32 v23, 0xffff0000, v16
	v_lshlrev_b32_e32 v24, 16, v17
	v_and_b32_e32 v25, 0xffff0000, v17
	s_waitcnt vmcnt(7) lgkmcnt(3)
	v_mov_b32_e32 v16, v212
	v_mov_b32_e32 v17, v213
	v_mov_b32_e32 v18, v214
	v_mov_b32_e32 v19, v215
	v_fmac_f32_e32 v22, v12, v16
	v_add_co_u32_e32 v16, vcc, s12, v120
	v_fmac_f32_e32 v23, v13, v17
	v_fmac_f32_e32 v24, v14, v18
	v_fmac_f32_e32 v25, v15, v19
	v_cvt_pk_bf16_f32 v12, v22, v23
	v_cvt_pk_bf16_f32 v13, v24, v25
	v_addc_co_u32_e32 v17, vcc, 0, v121, vcc
	global_store_dwordx2 v[20:21], v[12:13], off
	s_mov_b32 s12, 0x5c000
	s_waitcnt vmcnt(7)
	v_mov_b32_e32 v12, v202
	v_mov_b32_e32 v13, v203
	v_lshlrev_b32_e32 v18, 16, v12
	v_and_b32_e32 v19, 0xffff0000, v12
	v_lshlrev_b32_e32 v20, 16, v13
	v_and_b32_e32 v21, 0xffff0000, v13
	s_waitcnt vmcnt(7) lgkmcnt(2)
	v_mov_b32_e32 v12, v212
	v_mov_b32_e32 v13, v213
	v_mov_b32_e32 v14, v214
	v_mov_b32_e32 v15, v215
	v_fmac_f32_e32 v18, v8, v12
	v_add_co_u32_e32 v12, vcc, s12, v120
	v_fmac_f32_e32 v19, v9, v13
	v_fmac_f32_e32 v20, v10, v14
	v_fmac_f32_e32 v21, v11, v15
	v_cvt_pk_bf16_f32 v8, v18, v19
	v_cvt_pk_bf16_f32 v9, v20, v21
	v_addc_co_u32_e32 v13, vcc, 0, v121, vcc
	global_store_dwordx2 v[16:17], v[8:9], off
	s_waitcnt vmcnt(7)
	v_mov_b32_e32 v8, v204
	v_mov_b32_e32 v9, v205
	v_lshlrev_b32_e32 v14, 16, v8
	v_and_b32_e32 v15, 0xffff0000, v8
	v_lshlrev_b32_e32 v16, 16, v9
	v_and_b32_e32 v17, 0xffff0000, v9
	s_waitcnt vmcnt(7) lgkmcnt(1)
	v_mov_b32_e32 v8, v212
	v_mov_b32_e32 v9, v213
	v_mov_b32_e32 v10, v214
	v_mov_b32_e32 v11, v215
	v_fmac_f32_e32 v14, v4, v8
	v_add_co_u32_e32 v8, vcc, s39, v120
	v_fmac_f32_e32 v15, v5, v9
	v_fmac_f32_e32 v16, v6, v10
	v_fmac_f32_e32 v17, v7, v11
	v_cvt_pk_bf16_f32 v4, v14, v15
	v_cvt_pk_bf16_f32 v5, v16, v17
	v_addc_co_u32_e32 v9, vcc, 0, v121, vcc
	global_store_dwordx2 v[12:13], v[4:5], off
	s_waitcnt vmcnt(7)
	v_mov_b32_e32 v4, v206
	v_mov_b32_e32 v5, v207
	v_lshlrev_b32_e32 v10, 16, v4
	v_and_b32_e32 v11, 0xffff0000, v4
	v_lshlrev_b32_e32 v12, 16, v5
	v_and_b32_e32 v13, 0xffff0000, v5
	s_ashr_i32 s10, s22, 31
	s_lshr_b32 s10, s10, 29
	s_add_i32 s13, s22, s10
	s_ashr_i32 s12, s13, 3
	s_and_b64 s[10:11], s[6:7], exec
	s_cselect_b32 s12, s22, s12
	s_and_b32 s10, s13, -8
	s_sub_i32 s13, s22, s10
	s_and_b64 s[10:11], s[6:7], exec
	s_cselect_b32 s17, s17, s13
	s_cmp_lt_i32 s12, 64
	s_cselect_b64 s[10:11], -1, 0
	s_cmpk_lt_i32 s22, 0x200
	s_cselect_b64 s[18:19], -1, 0
	s_waitcnt vmcnt(7) lgkmcnt(0)
	v_mov_b32_e32 v4, v212
	v_mov_b32_e32 v5, v213
	v_mov_b32_e32 v6, v214
	v_mov_b32_e32 v7, v215
	v_fmac_f32_e32 v10, v0, v4
	v_fmac_f32_e32 v11, v1, v5
	v_fmac_f32_e32 v12, v2, v6
	v_fmac_f32_e32 v13, v3, v7
	v_cvt_pk_bf16_f32 v0, v10, v11
	v_cvt_pk_bf16_f32 v1, v12, v13
	global_store_dwordx2 v[8:9], v[0:1], off
	v_cndmask_b32_e64 v0, 0, 1, s[10:11]
	v_cndmask_b32_e64 v1, 0, 1, s[18:19]
	v_cndmask_b32_e64 v0, v1, v0, s[6:7]
	s_waitcnt lgkmcnt(0)
	v_and_b32_e32 v0, 1, v0
	v_cmp_eq_u32_e32 vcc, 1, v0
	s_barrier
	s_cbranch_vccz .LBB0_1235

; DI void st4(u16* p, float a, float b, float c, float d) { u32x2 w = {cvtpk(a, b), cvtpk(c, d)}; *(u32x2*)p = w; }
;   DI void operator()(int m, int n, f32x4 v) const { st4(dst + (size_t)m * ld + n, v[0], v[1], v[2], v[3]); }
; DI void ld4bf(const u16* p, float* o) { const u32x2 w = *(const u32x2*)p; o[0] = __uint_as_float(w[0] << 16); o[1] = __uint_as_float(w[0] & 0xffff0000u); o[2] = __uint_as_float(w[1] << 16); o[3] = __uint_as_float(w[1] & 0xffff0000u); }
;   DI void operator()(int m, int n, f32x4 v) const {
;     float x[4]; ld4bf(xb + (size_t)m * 1024 + n, x);
;     const f32x4 g = *(const f32x4*)(gate + n);
;     st4(xb + (size_t)m * 1024 + n, x[0] + g[0] * v[0], x[1] + g[1] * v[1], x[2] + g[2] * v[2], x[3] + g[3] * v[3]);
;   }
.LBB0_1496:
	s_or_b64 exec, exec, s[20:21]
	s_ashr_i32 s12, s22, 4
	s_add_i32 s12, s12, s10
	s_mul_hi_i32 s13, s12, 0x6000
	s_mulk_i32 s12, 0x6000
	v_cmp_gt_i32_e32 vcc, 3, v134
	s_add_u32 s12, s27, s12
	v_mul_lo_u32 v128, v134, s1
	v_cndmask_b32_e32 v129, v189, v190, vcc
	v_lshlrev_b32_e32 v134, 4, v132
	s_addc_u32 s13, s28, s13
	s_lshl_b32 s20, s71, 2
	v_add3_u32 v129, 16, v128, v129
	v_and_b32_e32 v128, 0x80, v134
	v_lshlrev_b32_e32 v130, 5, v133
	v_and_b32_e32 v133, 28, v135
	s_add_u32 s20, s12, s20
	v_or3_b32 v140, v128, v130, v133
	v_lshlrev_b32_e32 v130, 2, v132
	v_mul_u32_u24_e32 v132, 0x440, v131
	s_addc_u32 s21, s13, 0
	s_lshl_b64 s[12:13], s[22:23], 19
	v_add3_u32 v130, v129, v130, v132
	s_add_u32 s12, s29, s12
	ds_write2_b32 v130, v104, v108 offset1:16
	ds_write2_b32 v130, v105, v109 offset0:68 offset1:84
	ds_write2_b32 v130, v106, v110 offset0:136 offset1:152
	ds_write2_b32 v130, v107, v111 offset0:204 offset1:220
	ds_write2_b32 v130, v120, v124 offset0:32 offset1:48
	ds_write2_b32 v130, v121, v125 offset0:100 offset1:116
	ds_write2_b32 v130, v122, v126 offset0:168 offset1:184
	ds_write2_b32 v130, v123, v127 offset0:236 offset1:252
	v_add_u32_e32 v123, 0x1000, v130
	s_addc_u32 s13, s30, s13
	s_lshl_b32 s22, s71, 1
	v_or_b32_e32 v128, v136, v131
	ds_write2_b32 v123, v96, v100 offset0:64 offset1:80
	ds_write2_b32 v123, v97, v101 offset0:132 offset1:148
	ds_write2_b32 v123, v98, v102 offset0:200 offset1:216
	v_mul_u32_u24_e32 v96, 0x110, v131
	s_add_u32 s22, s12, s22
	v_add3_u32 v124, v129, v134, v96
	v_ashrrev_i32_e32 v129, 31, v128
	s_addc_u32 s23, s13, 0
	v_add_u32_e32 v125, 0x1400, v130
	v_lshlrev_b64 v[120:121], 11, v[128:129]
	ds_write2_b32 v125, v99, v103 offset0:12 offset1:28
	ds_write2_b32 v123, v112, v116 offset0:96 offset1:112
	ds_write2_b32 v123, v113, v117 offset0:164 offset1:180
	ds_write2_b32 v123, v114, v118 offset0:232 offset1:248
	ds_write2_b32 v125, v115, v119 offset0:44 offset1:60
	v_lshl_add_u64 v[120:121], s[22:23], 0, v[120:121]
	v_lshlrev_b32_e32 v176, 1, v140
	s_waitcnt lgkmcnt(0)
	v_lshl_add_u64 v[120:121], v[120:121], 0, v[176:177]
	ds_read_b128 v[132:135], v124
	ds_read_b128 v[136:139], v124 offset:1088
	ds_read_b128 v[116:119], v124 offset:2176
	ds_read_b128 v[112:115], v124 offset:3264
	ds_read_b128 v[108:111], v124 offset:4352
	ds_read_b128 v[104:107], v124 offset:5440
	ds_read_b128 v[100:103], v124 offset:6528
	ds_read_b128 v[96:99], v124 offset:7616
	v_mov_b32_e32 v216, 0x2000
	v_mov_b32_e32 v217, 0
	global_load_dwordx2 v[192:193], v[120:121], off
	v_lshl_add_u64 v[208:209], v[120:121], 0, v[216:217]
	global_load_dwordx2 v[194:195], v[208:209], off
	v_lshl_add_u64 v[208:209], v[208:209], 0, v[216:217]
	global_load_dwordx2 v[196:197], v[208:209], off
	v_lshl_add_u64 v[208:209], v[208:209], 0, v[216:217]
	global_load_dwordx2 v[198:199], v[208:209], off
	v_lshl_add_u64 v[208:209], v[208:209], 0, v[216:217]
	global_load_dwordx2 v[200:201], v[208:209], off
	v_lshl_add_u64 v[208:209], v[208:209], 0, v[216:217]
	global_load_dwordx2 v[202:203], v[208:209], off
	v_lshl_add_u64 v[208:209], v[208:209], 0, v[216:217]
	global_load_dwordx2 v[204:205], v[208:209], off
	v_lshl_add_u64 v[208:209], v[208:209], 0, v[216:217]
	global_load_dwordx2 v[206:207], v[208:209], off
	v_lshlrev_b32_e32 v122, 2, v140
	global_load_dwordx4 v[212:215], v122, s[20:21]
	s_mov_b32 s12, 0x50000
	s_add_i32 s26, s26, s3
	s_waitcnt vmcnt(0)
	v_mov_b32_e32 v126, v192
	v_mov_b32_e32 v127, v193
	v_mov_b32_e32 v140, v212
	v_mov_b32_e32 v141, v213
	v_mov_b32_e32 v142, v214
	v_mov_b32_e32 v143, v215
	v_lshlrev_b32_e32 v129, 16, v126
	v_and_b32_e32 v126, 0xffff0000, v126
	v_lshlrev_b32_e32 v131, 16, v127
	v_and_b32_e32 v127, 0xffff0000, v127
	s_waitcnt lgkmcnt(7)
	v_fmac_f32_e32 v126, v133, v141
	v_fmac_f32_e32 v129, v132, v140
	v_fmac_f32_e32 v127, v135, v143
	v_cvt_pk_bf16_f32 v126, v129, v126
	v_fmac_f32_e32 v131, v134, v142
	v_cvt_pk_bf16_f32 v127, v131, v127
	global_store_dwordx2 v[120:121], v[126:127], off
	v_or_b32_e32 v126, 4, v128
	v_ashrrev_i32_e32 v127, 31, v126
	v_lshlrev_b64 v[126:127], 11, v[126:127]
	v_lshl_add_u64 v[126:127], s[22:23], 0, v[126:127]
	v_lshl_add_u64 v[126:127], v[126:127], 0, v[176:177]
	s_waitcnt vmcnt(7)
	v_mov_b32_e32 v132, v194
	v_mov_b32_e32 v133, v195
	v_lshlrev_b32_e32 v129, 16, v132
	v_and_b32_e32 v131, 0xffff0000, v132
	v_lshlrev_b32_e32 v140, 16, v133
	v_and_b32_e32 v141, 0xffff0000, v133
	s_waitcnt vmcnt(7) lgkmcnt(6)
	v_mov_b32_e32 v132, v212
	v_mov_b32_e32 v133, v213
	v_mov_b32_e32 v134, v214
	v_mov_b32_e32 v135, v215
	v_fmac_f32_e32 v129, v136, v132
	v_fmac_f32_e32 v131, v137, v133
	v_fmac_f32_e32 v140, v138, v134
	v_fmac_f32_e32 v141, v139, v135
	v_cvt_pk_bf16_f32 v132, v129, v131
	v_cvt_pk_bf16_f32 v133, v140, v141
	global_store_dwordx2 v[126:127], v[132:133], off
	v_or_b32_e32 v126, 8, v128
	v_ashrrev_i32_e32 v127, 31, v126
	v_lshlrev_b64 v[126:127], 11, v[126:127]
	v_lshl_add_u64 v[126:127], s[22:23], 0, v[126:127]
	v_lshl_add_u64 v[126:127], v[126:127], 0, v[176:177]
	s_waitcnt vmcnt(7)
	v_mov_b32_e32 v132, v196
	v_mov_b32_e32 v133, v197
	v_lshlrev_b32_e32 v129, 16, v132
	v_and_b32_e32 v131, 0xffff0000, v132
	v_lshlrev_b32_e32 v136, 16, v133
	v_and_b32_e32 v137, 0xffff0000, v133
	s_waitcnt vmcnt(7) lgkmcnt(5)
	v_mov_b32_e32 v132, v212
	v_mov_b32_e32 v133, v213
	v_mov_b32_e32 v134, v214
	v_mov_b32_e32 v135, v215
	v_fmac_f32_e32 v129, v116, v132
	v_fmac_f32_e32 v131, v117, v133
	v_cvt_pk_bf16_f32 v116, v129, v131
	v_fmac_f32_e32 v136, v118, v134
	v_fmac_f32_e32 v137, v119, v135
	v_cvt_pk_bf16_f32 v117, v136, v137
	global_store_dwordx2 v[126:127], v[116:117], off
	v_or_b32_e32 v116, 12, v128
	v_ashrrev_i32_e32 v117, 31, v116
	v_lshlrev_b64 v[116:117], 11, v[116:117]
	v_lshl_add_u64 v[116:117], s[22:23], 0, v[116:117]
	v_lshl_add_u64 v[126:127], v[116:117], 0, v[176:177]
	s_waitcnt vmcnt(7)
; DI void st4(u16* p, float a, float b, float c, float d) { u32x2 w = {cvtpk(a, b), cvtpk(c, d)}; *(u32x2*)p = w; }
;   DI void operator()(int m, int n, f32x4 v) const { st4(dst + (size_t)m * ld + n, v[0], v[1], v[2], v[3]); }
; DI void ld4bf(const u16* p, float* o) { const u32x2 w = *(const u32x2*)p; o[0] = __uint_as_float(w[0] << 16); o[1] = __uint_as_float(w[0] & 0xffff0000u); o[2] = __uint_as_float(w[1] << 16); o[3] = __uint_as_float(w[1] & 0xffff0000u); }
;   DI void operator()(int m, int n, f32x4 v) const {
;     float x[4]; ld4bf(xb + (size_t)m * 1024 + n, x);
;     const f32x4 g = *(const f32x4*)(gate + n);
;     st4(xb + (size_t)m * 1024 + n, x[0] + g[0] * v[0], x[1] + g[1] * v[1], x[2] + g[2] * v[2], x[3] + g[3] * v[3]);
;   }
	v_mov_b32_e32 v116, v198
	v_mov_b32_e32 v117, v199
	v_lshlrev_b32_e32 v129, 16, v116
	v_and_b32_e32 v131, 0xffff0000, v116
	v_lshlrev_b32_e32 v132, 16, v117
	v_and_b32_e32 v133, 0xffff0000, v117
	s_waitcnt vmcnt(7) lgkmcnt(4)
	v_mov_b32_e32 v116, v212
	v_mov_b32_e32 v117, v213
	v_mov_b32_e32 v118, v214
	v_mov_b32_e32 v119, v215
	v_fmac_f32_e32 v129, v112, v116
	v_fmac_f32_e32 v131, v113, v117
	v_cvt_pk_bf16_f32 v112, v129, v131
	v_fmac_f32_e32 v132, v114, v118
	v_fmac_f32_e32 v133, v115, v119
	v_cvt_pk_bf16_f32 v113, v132, v133
	global_store_dwordx2 v[126:127], v[112:113], off
	v_or_b32_e32 v112, 16, v128
	v_ashrrev_i32_e32 v113, 31, v112
	v_lshlrev_b64 v[112:113], 11, v[112:113]
	v_lshl_add_u64 v[112:113], s[22:23], 0, v[112:113]
	v_lshl_add_u64 v[116:117], v[112:113], 0, v[176:177]
	s_waitcnt vmcnt(7)
	v_mov_b32_e32 v112, v200
	v_mov_b32_e32 v113, v201
	v_lshlrev_b32_e32 v118, 16, v112
	v_and_b32_e32 v119, 0xffff0000, v112
	v_lshlrev_b32_e32 v126, 16, v113
	v_and_b32_e32 v127, 0xffff0000, v113
	s_waitcnt vmcnt(7) lgkmcnt(3)
	v_mov_b32_e32 v112, v212
	v_mov_b32_e32 v113, v213
	v_mov_b32_e32 v114, v214
	v_mov_b32_e32 v115, v215
	v_fmac_f32_e32 v118, v108, v112
	v_fmac_f32_e32 v119, v109, v113
	v_cvt_pk_bf16_f32 v108, v118, v119
	v_fmac_f32_e32 v126, v110, v114
	v_fmac_f32_e32 v127, v111, v115
	v_cvt_pk_bf16_f32 v109, v126, v127
	global_store_dwordx2 v[116:117], v[108:109], off
	v_or_b32_e32 v108, 20, v128
	v_ashrrev_i32_e32 v109, 31, v108
	v_lshlrev_b64 v[108:109], 11, v[108:109]
	v_lshl_add_u64 v[108:109], s[22:23], 0, v[108:109]
	v_lshl_add_u64 v[112:113], v[108:109], 0, v[176:177]
	s_waitcnt vmcnt(7)
	v_mov_b32_e32 v108, v202
	v_mov_b32_e32 v109, v203
	v_lshlrev_b32_e32 v114, 16, v108
	v_and_b32_e32 v115, 0xffff0000, v108
	v_lshlrev_b32_e32 v116, 16, v109
	v_and_b32_e32 v117, 0xffff0000, v109
	s_waitcnt vmcnt(7) lgkmcnt(2)
	v_mov_b32_e32 v108, v212
	v_mov_b32_e32 v109, v213
	v_mov_b32_e32 v110, v214
	v_mov_b32_e32 v111, v215
	v_fmac_f32_e32 v114, v104, v108
	v_fmac_f32_e32 v115, v105, v109
	v_cvt_pk_bf16_f32 v104, v114, v115
	v_fmac_f32_e32 v116, v106, v110
	v_fmac_f32_e32 v117, v107, v111
	v_cvt_pk_bf16_f32 v105, v116, v117
	global_store_dwordx2 v[112:113], v[104:105], off
	v_or_b32_e32 v104, 24, v128
	v_ashrrev_i32_e32 v105, 31, v104
	v_lshlrev_b64 v[104:105], 11, v[104:105]
	v_lshl_add_u64 v[104:105], s[22:23], 0, v[104:105]
	v_lshl_add_u64 v[108:109], v[104:105], 0, v[176:177]
	s_waitcnt vmcnt(7)
	v_mov_b32_e32 v104, v204
	v_mov_b32_e32 v105, v205
	v_lshlrev_b32_e32 v110, 16, v104
	v_and_b32_e32 v111, 0xffff0000, v104
	v_lshlrev_b32_e32 v112, 16, v105
	v_and_b32_e32 v113, 0xffff0000, v105
	s_waitcnt vmcnt(7) lgkmcnt(1)
	v_mov_b32_e32 v104, v212
	v_mov_b32_e32 v105, v213
	v_mov_b32_e32 v106, v214
	v_mov_b32_e32 v107, v215
	v_fmac_f32_e32 v110, v100, v104
	v_fmac_f32_e32 v111, v101, v105
	v_cvt_pk_bf16_f32 v100, v110, v111
	v_fmac_f32_e32 v112, v102, v106
	v_fmac_f32_e32 v113, v103, v107
	v_cvt_pk_bf16_f32 v101, v112, v113
	global_store_dwordx2 v[108:109], v[100:101], off
	v_or_b32_e32 v100, 28, v128
	v_ashrrev_i32_e32 v101, 31, v100
	v_lshlrev_b64 v[100:101], 11, v[100:101]
	v_lshl_add_u64 v[100:101], s[22:23], 0, v[100:101]
	v_lshl_add_u64 v[104:105], v[100:101], 0, v[176:177]
	s_waitcnt vmcnt(7)
	v_mov_b32_e32 v100, v206
	v_mov_b32_e32 v101, v207
	v_lshlrev_b32_e32 v106, 16, v100
	v_and_b32_e32 v107, 0xffff0000, v100
	v_lshlrev_b32_e32 v108, 16, v101
	v_and_b32_e32 v109, 0xffff0000, v101
	s_waitcnt vmcnt(7) lgkmcnt(0)
	v_mov_b32_e32 v100, v212
	v_mov_b32_e32 v101, v213
	v_mov_b32_e32 v102, v214
	v_mov_b32_e32 v103, v215
	v_fmac_f32_e32 v106, v96, v100
	v_fmac_f32_e32 v107, v97, v101
	v_cvt_pk_bf16_f32 v96, v106, v107
	v_fmac_f32_e32 v108, v98, v102
	v_fmac_f32_e32 v109, v99, v103
	v_cvt_pk_bf16_f32 v97, v108, v109
	global_store_dwordx2 v[104:105], v[96:97], off
	v_or_b32_e32 v96, 32, v128
	v_ashrrev_i32_e32 v97, 31, v96
	v_lshlrev_b64 v[96:97], 11, v[96:97]
	s_waitcnt lgkmcnt(0)
	ds_write2_b32 v130, v72, v76 offset1:16
	ds_write2_b32 v130, v73, v77 offset0:68 offset1:84
	ds_write2_b32 v130, v74, v78 offset0:136 offset1:152
	ds_write2_b32 v130, v75, v79 offset0:204 offset1:220
	ds_write2_b32 v130, v88, v92 offset0:32 offset1:48
	ds_write2_b32 v130, v89, v93 offset0:100 offset1:116
	ds_write2_b32 v130, v90, v94 offset0:168 offset1:184
	ds_write2_b32 v130, v91, v95 offset0:236 offset1:252
	ds_write2_b32 v123, v64, v68 offset0:64 offset1:80
	ds_write2_b32 v123, v65, v69 offset0:132 offset1:148
	ds_write2_b32 v123, v66, v70 offset0:200 offset1:216
	ds_write2_b32 v125, v67, v71 offset0:12 offset1:28
	ds_write2_b32 v123, v80, v84 offset0:96 offset1:112
	ds_write2_b32 v123, v81, v85 offset0:164 offset1:180
	ds_write2_b32 v123, v82, v86 offset0:232 offset1:248
	ds_write2_b32 v125, v83, v87 offset0:44 offset1:60
	v_lshl_add_u64 v[96:97], s[22:23], 0, v[96:97]
	s_waitcnt lgkmcnt(0)
	v_lshl_add_u64 v[100:101], v[96:97], 0, v[176:177]
	ds_read_b128 v[92:95], v124
	ds_read_b128 v[88:91], v124 offset:1088
	ds_read_b128 v[84:87], v124 offset:2176
	ds_read_b128 v[80:83], v124 offset:3264
	ds_read_b128 v[76:79], v124 offset:4352
	ds_read_b128 v[72:75], v124 offset:5440
	ds_read_b128 v[68:71], v124 offset:6528
	ds_read_b128 v[64:67], v124 offset:7616
	v_mov_b32_e32 v216, 0x2000
	v_mov_b32_e32 v217, 0
	global_load_dwordx2 v[192:193], v[100:101], off
	v_lshl_add_u64 v[208:209], v[100:101], 0, v[216:217]
	global_load_dwordx2 v[194:195], v[208:209], off
	v_lshl_add_u64 v[208:209], v[208:209], 0, v[216:217]
	global_load_dwordx2 v[196:197], v[208:209], off
	v_lshl_add_u64 v[208:209], v[208:209], 0, v[216:217]
	global_load_dwordx2 v[198:199], v[208:209], off
	v_lshl_add_u64 v[208:209], v[208:209], 0, v[216:217]
	global_load_dwordx2 v[200:201], v[208:209], off
	v_lshl_add_u64 v[208:209], v[208:209], 0, v[216:217]
	global_load_dwordx2 v[202:203], v[208:209], off
	v_lshl_add_u64 v[208:209], v[208:209], 0, v[216:217]
	global_load_dwordx2 v[204:205], v[208:209], off
	v_lshl_add_u64 v[208:209], v[208:209], 0, v[216:217]
	global_load_dwordx2 v[206:207], v[208:209], off
	s_waitcnt vmcnt(7)
; DI void st4(u16* p, float a, float b, float c, float d) { u32x2 w = {cvtpk(a, b), cvtpk(c, d)}; *(u32x2*)p = w; }
;   DI void operator()(int m, int n, f32x4 v) const { st4(dst + (size_t)m * ld + n, v[0], v[1], v[2], v[3]); }
; DI void ld4bf(const u16* p, float* o) { const u32x2 w = *(const u32x2*)p; o[0] = __uint_as_float(w[0] << 16); o[1] = __uint_as_float(w[0] & 0xffff0000u); o[2] = __uint_as_float(w[1] << 16); o[3] = __uint_as_float(w[1] & 0xffff0000u); }
;   DI void operator()(int m, int n, f32x4 v) const {
;     float x[4]; ld4bf(xb + (size_t)m * 1024 + n, x);
;     const f32x4 g = *(const f32x4*)(gate + n);
;     st4(xb + (size_t)m * 1024 + n, x[0] + g[0] * v[0], x[1] + g[1] * v[1], x[2] + g[2] * v[2], x[3] + g[3] * v[3]);
;   }
	v_mov_b32_e32 v96, v192
	v_mov_b32_e32 v97, v193
	v_lshlrev_b32_e32 v102, 16, v96
	v_and_b32_e32 v103, 0xffff0000, v96
	v_lshlrev_b32_e32 v104, 16, v97
	v_and_b32_e32 v105, 0xffff0000, v97
	s_waitcnt vmcnt(7) lgkmcnt(7)
	v_mov_b32_e32 v96, v212
	v_mov_b32_e32 v97, v213
	v_mov_b32_e32 v98, v214
	v_mov_b32_e32 v99, v215
	v_fmac_f32_e32 v102, v92, v96
	v_fmac_f32_e32 v103, v93, v97
	v_cvt_pk_bf16_f32 v92, v102, v103
	v_fmac_f32_e32 v104, v94, v98
	v_fmac_f32_e32 v105, v95, v99
	v_cvt_pk_bf16_f32 v93, v104, v105
	global_store_dwordx2 v[100:101], v[92:93], off
	v_or_b32_e32 v92, 36, v128
	v_ashrrev_i32_e32 v93, 31, v92
	v_lshlrev_b64 v[92:93], 11, v[92:93]
	v_lshl_add_u64 v[92:93], s[22:23], 0, v[92:93]
	v_lshl_add_u64 v[96:97], v[92:93], 0, v[176:177]
	s_waitcnt vmcnt(7)
	v_mov_b32_e32 v92, v194
	v_mov_b32_e32 v93, v195
	v_lshlrev_b32_e32 v98, 16, v92
	v_and_b32_e32 v99, 0xffff0000, v92
	v_lshlrev_b32_e32 v100, 16, v93
	v_and_b32_e32 v101, 0xffff0000, v93
	s_waitcnt vmcnt(7) lgkmcnt(6)
	v_mov_b32_e32 v92, v212
	v_mov_b32_e32 v93, v213
	v_mov_b32_e32 v94, v214
	v_mov_b32_e32 v95, v215
	v_fmac_f32_e32 v98, v88, v92
	v_fmac_f32_e32 v99, v89, v93
	v_cvt_pk_bf16_f32 v88, v98, v99
	v_fmac_f32_e32 v100, v90, v94
	v_fmac_f32_e32 v101, v91, v95
	v_cvt_pk_bf16_f32 v89, v100, v101
	global_store_dwordx2 v[96:97], v[88:89], off
	v_or_b32_e32 v88, 40, v128
	v_ashrrev_i32_e32 v89, 31, v88
	v_lshlrev_b64 v[88:89], 11, v[88:89]
	v_lshl_add_u64 v[88:89], s[22:23], 0, v[88:89]
	v_lshl_add_u64 v[92:93], v[88:89], 0, v[176:177]
	s_waitcnt vmcnt(7)
	v_mov_b32_e32 v88, v196
	v_mov_b32_e32 v89, v197
	v_lshlrev_b32_e32 v94, 16, v88
	v_and_b32_e32 v95, 0xffff0000, v88
	v_lshlrev_b32_e32 v96, 16, v89
	v_and_b32_e32 v97, 0xffff0000, v89
	s_waitcnt vmcnt(7) lgkmcnt(5)
	v_mov_b32_e32 v88, v212
	v_mov_b32_e32 v89, v213
	v_mov_b32_e32 v90, v214
	v_mov_b32_e32 v91, v215
	v_fmac_f32_e32 v94, v84, v88
	v_fmac_f32_e32 v95, v85, v89
	v_cvt_pk_bf16_f32 v84, v94, v95
	v_fmac_f32_e32 v96, v86, v90
	v_fmac_f32_e32 v97, v87, v91
	v_cvt_pk_bf16_f32 v85, v96, v97
	global_store_dwordx2 v[92:93], v[84:85], off
	v_or_b32_e32 v84, 44, v128
	v_ashrrev_i32_e32 v85, 31, v84
	v_lshlrev_b64 v[84:85], 11, v[84:85]
	v_lshl_add_u64 v[84:85], s[22:23], 0, v[84:85]
	v_lshl_add_u64 v[88:89], v[84:85], 0, v[176:177]
	s_waitcnt vmcnt(7)
	v_mov_b32_e32 v84, v198
	v_mov_b32_e32 v85, v199
	v_lshlrev_b32_e32 v90, 16, v84
	v_and_b32_e32 v91, 0xffff0000, v84
	v_lshlrev_b32_e32 v92, 16, v85
	v_and_b32_e32 v93, 0xffff0000, v85
	s_waitcnt vmcnt(7) lgkmcnt(4)
	v_mov_b32_e32 v84, v212
	v_mov_b32_e32 v85, v213
	v_mov_b32_e32 v86, v214
	v_mov_b32_e32 v87, v215
	v_fmac_f32_e32 v90, v80, v84
	v_fmac_f32_e32 v91, v81, v85
	v_cvt_pk_bf16_f32 v80, v90, v91
	v_fmac_f32_e32 v92, v82, v86
	v_fmac_f32_e32 v93, v83, v87
	v_cvt_pk_bf16_f32 v81, v92, v93
	global_store_dwordx2 v[88:89], v[80:81], off
	v_or_b32_e32 v80, 48, v128
	v_ashrrev_i32_e32 v81, 31, v80
	v_lshlrev_b64 v[80:81], 11, v[80:81]
	v_lshl_add_u64 v[80:81], s[22:23], 0, v[80:81]
	v_lshl_add_u64 v[84:85], v[80:81], 0, v[176:177]
	s_waitcnt vmcnt(7)
	v_mov_b32_e32 v80, v200
	v_mov_b32_e32 v81, v201
	v_lshlrev_b32_e32 v86, 16, v80
	v_and_b32_e32 v87, 0xffff0000, v80
	v_lshlrev_b32_e32 v88, 16, v81
	v_and_b32_e32 v89, 0xffff0000, v81
	s_waitcnt vmcnt(7) lgkmcnt(3)
	v_mov_b32_e32 v80, v212
	v_mov_b32_e32 v81, v213
	v_mov_b32_e32 v82, v214
	v_mov_b32_e32 v83, v215
	v_fmac_f32_e32 v86, v76, v80
	v_fmac_f32_e32 v87, v77, v81
	v_cvt_pk_bf16_f32 v76, v86, v87
	v_fmac_f32_e32 v88, v78, v82
	v_fmac_f32_e32 v89, v79, v83
	v_cvt_pk_bf16_f32 v77, v88, v89
	global_store_dwordx2 v[84:85], v[76:77], off
	v_or_b32_e32 v76, 52, v128
	v_ashrrev_i32_e32 v77, 31, v76
	v_lshlrev_b64 v[76:77], 11, v[76:77]
	v_lshl_add_u64 v[76:77], s[22:23], 0, v[76:77]
	v_lshl_add_u64 v[80:81], v[76:77], 0, v[176:177]
	s_waitcnt vmcnt(7)
	v_mov_b32_e32 v76, v202
	v_mov_b32_e32 v77, v203
	v_lshlrev_b32_e32 v82, 16, v76
	v_and_b32_e32 v83, 0xffff0000, v76
	v_lshlrev_b32_e32 v84, 16, v77
	v_and_b32_e32 v85, 0xffff0000, v77
	s_waitcnt vmcnt(7) lgkmcnt(2)
	v_mov_b32_e32 v76, v212
	v_mov_b32_e32 v77, v213
	v_mov_b32_e32 v78, v214
	v_mov_b32_e32 v79, v215
	v_fmac_f32_e32 v82, v72, v76
	v_fmac_f32_e32 v83, v73, v77
	v_cvt_pk_bf16_f32 v72, v82, v83
	v_fmac_f32_e32 v84, v74, v78
	v_fmac_f32_e32 v85, v75, v79
	v_cvt_pk_bf16_f32 v73, v84, v85
	global_store_dwordx2 v[80:81], v[72:73], off
	v_or_b32_e32 v72, 56, v128
	v_ashrrev_i32_e32 v73, 31, v72
	v_lshlrev_b64 v[72:73], 11, v[72:73]
	v_lshl_add_u64 v[72:73], s[22:23], 0, v[72:73]
	v_lshl_add_u64 v[76:77], v[72:73], 0, v[176:177]
	s_waitcnt vmcnt(7)
	v_mov_b32_e32 v72, v204
	v_mov_b32_e32 v73, v205
	v_lshlrev_b32_e32 v78, 16, v72
	v_and_b32_e32 v79, 0xffff0000, v72
	v_lshlrev_b32_e32 v80, 16, v73
	v_and_b32_e32 v81, 0xffff0000, v73
	s_waitcnt vmcnt(7) lgkmcnt(1)
	v_mov_b32_e32 v72, v212
	v_mov_b32_e32 v73, v213
	v_mov_b32_e32 v74, v214
	v_mov_b32_e32 v75, v215
	v_fmac_f32_e32 v78, v68, v72
	v_fmac_f32_e32 v79, v69, v73
	v_cvt_pk_bf16_f32 v68, v78, v79
	v_fmac_f32_e32 v80, v70, v74
	v_fmac_f32_e32 v81, v71, v75
	v_cvt_pk_bf16_f32 v69, v80, v81
	global_store_dwordx2 v[76:77], v[68:69], off
	v_or_b32_e32 v68, 60, v128
	v_ashrrev_i32_e32 v69, 31, v68
	v_lshlrev_b64 v[68:69], 11, v[68:69]
	v_lshl_add_u64 v[68:69], s[22:23], 0, v[68:69]
	v_lshl_add_u64 v[72:73], v[68:69], 0, v[176:177]
	s_waitcnt vmcnt(7)
	v_mov_b32_e32 v68, v206
	v_mov_b32_e32 v69, v207
	v_lshlrev_b32_e32 v74, 16, v68
	v_and_b32_e32 v75, 0xffff0000, v68
	v_lshlrev_b32_e32 v76, 16, v69
	v_and_b32_e32 v77, 0xffff0000, v69
	s_waitcnt vmcnt(7) lgkmcnt(0)
; DI void st4(u16* p, float a, float b, float c, float d) { u32x2 w = {cvtpk(a, b), cvtpk(c, d)}; *(u32x2*)p = w; }
;   DI void operator()(int m, int n, f32x4 v) const { st4(dst + (size_t)m * ld + n, v[0], v[1], v[2], v[3]); }
; DI void ld4bf(const u16* p, float* o) { const u32x2 w = *(const u32x2*)p; o[0] = __uint_as_float(w[0] << 16); o[1] = __uint_as_float(w[0] & 0xffff0000u); o[2] = __uint_as_float(w[1] << 16); o[3] = __uint_as_float(w[1] & 0xffff0000u); }
;   DI void operator()(int m, int n, f32x4 v) const {
;     float x[4]; ld4bf(xb + (size_t)m * 1024 + n, x);
;     const f32x4 g = *(const f32x4*)(gate + n);
;     st4(xb + (size_t)m * 1024 + n, x[0] + g[0] * v[0], x[1] + g[1] * v[1], x[2] + g[2] * v[2], x[3] + g[3] * v[3]);
;   }
	v_mov_b32_e32 v68, v212
	v_mov_b32_e32 v69, v213
	v_mov_b32_e32 v70, v214
	v_mov_b32_e32 v71, v215
	v_fmac_f32_e32 v74, v64, v68
	v_fmac_f32_e32 v75, v65, v69
	v_fmac_f32_e32 v76, v66, v70
	v_fmac_f32_e32 v77, v67, v71
	v_cvt_pk_bf16_f32 v64, v74, v75
	v_cvt_pk_bf16_f32 v65, v76, v77
	global_store_dwordx2 v[72:73], v[64:65], off
	s_waitcnt lgkmcnt(0)
	ds_write2_b32 v130, v40, v44 offset1:16
	ds_write2_b32 v130, v41, v45 offset0:68 offset1:84
	ds_write2_b32 v130, v42, v46 offset0:136 offset1:152
	ds_write2_b32 v130, v43, v47 offset0:204 offset1:220
	ds_write2_b32 v130, v56, v60 offset0:32 offset1:48
	ds_write2_b32 v130, v57, v61 offset0:100 offset1:116
	ds_write2_b32 v130, v58, v62 offset0:168 offset1:184
	ds_write2_b32 v130, v59, v63 offset0:236 offset1:252
	ds_write2_b32 v123, v32, v36 offset0:64 offset1:80
	ds_write2_b32 v123, v33, v37 offset0:132 offset1:148
	ds_write2_b32 v123, v34, v38 offset0:200 offset1:216
	ds_write2_b32 v125, v35, v39 offset0:12 offset1:28
	ds_write2_b32 v123, v48, v52 offset0:96 offset1:112
	ds_write2_b32 v123, v49, v53 offset0:164 offset1:180
	ds_write2_b32 v123, v50, v54 offset0:232 offset1:248
	ds_write2_b32 v125, v51, v55 offset0:44 offset1:60
	v_add_co_u32_e32 v68, vcc, s90, v120
	s_waitcnt lgkmcnt(0)
	ds_read_b128 v[60:63], v124
	ds_read_b128 v[56:59], v124 offset:1088
	ds_read_b128 v[52:55], v124 offset:2176
	ds_read_b128 v[48:51], v124 offset:3264
	ds_read_b128 v[44:47], v124 offset:4352
	ds_read_b128 v[40:43], v124 offset:5440
	ds_read_b128 v[36:39], v124 offset:6528
	ds_read_b128 v[32:35], v124 offset:7616
	v_addc_co_u32_e32 v69, vcc, 0, v121, vcc
	v_mov_b32_e32 v216, 0x2000
	v_mov_b32_e32 v217, 0
	global_load_dwordx2 v[192:193], v[68:69], off
	v_lshl_add_u64 v[208:209], v[68:69], 0, v[216:217]
	global_load_dwordx2 v[194:195], v[208:209], off
	v_lshl_add_u64 v[208:209], v[208:209], 0, v[216:217]
	global_load_dwordx2 v[196:197], v[208:209], off
	v_lshl_add_u64 v[208:209], v[208:209], 0, v[216:217]
	global_load_dwordx2 v[198:199], v[208:209], off
	v_lshl_add_u64 v[208:209], v[208:209], 0, v[216:217]
	global_load_dwordx2 v[200:201], v[208:209], off
	v_lshl_add_u64 v[208:209], v[208:209], 0, v[216:217]
	global_load_dwordx2 v[202:203], v[208:209], off
	v_lshl_add_u64 v[208:209], v[208:209], 0, v[216:217]
	global_load_dwordx2 v[204:205], v[208:209], off
	v_lshl_add_u64 v[208:209], v[208:209], 0, v[216:217]
	global_load_dwordx2 v[206:207], v[208:209], off
	s_waitcnt vmcnt(7)
	v_mov_b32_e32 v64, v192
	v_mov_b32_e32 v65, v193
	v_lshlrev_b32_e32 v70, 16, v64
	v_and_b32_e32 v71, 0xffff0000, v64
	v_lshlrev_b32_e32 v72, 16, v65
	v_and_b32_e32 v73, 0xffff0000, v65
	s_waitcnt vmcnt(7) lgkmcnt(7)
	v_mov_b32_e32 v64, v212
	v_mov_b32_e32 v65, v213
	v_mov_b32_e32 v66, v214
	v_mov_b32_e32 v67, v215
	v_fmac_f32_e32 v70, v60, v64
	v_add_co_u32_e32 v64, vcc, s91, v120
	v_fmac_f32_e32 v71, v61, v65
	v_fmac_f32_e32 v72, v62, v66
	v_fmac_f32_e32 v73, v63, v67
	v_cvt_pk_bf16_f32 v60, v70, v71
	v_cvt_pk_bf16_f32 v61, v72, v73
	v_addc_co_u32_e32 v65, vcc, 0, v121, vcc
	global_store_dwordx2 v[68:69], v[60:61], off
	s_waitcnt vmcnt(7)
	v_mov_b32_e32 v60, v194
	v_mov_b32_e32 v61, v195
	v_lshlrev_b32_e32 v66, 16, v60
	v_and_b32_e32 v67, 0xffff0000, v60
	v_lshlrev_b32_e32 v68, 16, v61
	v_and_b32_e32 v69, 0xffff0000, v61
	s_waitcnt vmcnt(7) lgkmcnt(6)
	v_mov_b32_e32 v60, v212
	v_mov_b32_e32 v61, v213
	v_mov_b32_e32 v62, v214
	v_mov_b32_e32 v63, v215
	v_fmac_f32_e32 v66, v56, v60
	v_add_co_u32_e32 v60, vcc, s92, v120
	v_fmac_f32_e32 v67, v57, v61
	v_fmac_f32_e32 v68, v58, v62
	v_fmac_f32_e32 v69, v59, v63
	v_cvt_pk_bf16_f32 v56, v66, v67
	v_cvt_pk_bf16_f32 v57, v68, v69
	v_addc_co_u32_e32 v61, vcc, 0, v121, vcc
	global_store_dwordx2 v[64:65], v[56:57], off
	s_waitcnt vmcnt(7)
	v_mov_b32_e32 v56, v196
	v_mov_b32_e32 v57, v197
	v_lshlrev_b32_e32 v62, 16, v56
	v_and_b32_e32 v63, 0xffff0000, v56
	v_lshlrev_b32_e32 v64, 16, v57
	v_and_b32_e32 v65, 0xffff0000, v57
	s_waitcnt vmcnt(7) lgkmcnt(5)
	v_mov_b32_e32 v56, v212
	v_mov_b32_e32 v57, v213
	v_mov_b32_e32 v58, v214
	v_mov_b32_e32 v59, v215
	v_fmac_f32_e32 v62, v52, v56
	v_add_co_u32_e32 v56, vcc, s79, v120
	v_fmac_f32_e32 v63, v53, v57
	v_fmac_f32_e32 v64, v54, v58
	v_fmac_f32_e32 v65, v55, v59
	v_cvt_pk_bf16_f32 v52, v62, v63
	v_cvt_pk_bf16_f32 v53, v64, v65
	v_addc_co_u32_e32 v57, vcc, 0, v121, vcc
	global_store_dwordx2 v[60:61], v[52:53], off
	s_waitcnt vmcnt(7)
	v_mov_b32_e32 v52, v198
	v_mov_b32_e32 v53, v199
	v_lshlrev_b32_e32 v58, 16, v52
	v_and_b32_e32 v59, 0xffff0000, v52
	v_lshlrev_b32_e32 v60, 16, v53
	v_and_b32_e32 v61, 0xffff0000, v53
	s_waitcnt vmcnt(7) lgkmcnt(4)
	v_mov_b32_e32 v52, v212
	v_mov_b32_e32 v53, v213
	v_mov_b32_e32 v54, v214
	v_mov_b32_e32 v55, v215
	v_fmac_f32_e32 v58, v48, v52
	v_add_co_u32_e32 v52, vcc, s78, v120
	v_fmac_f32_e32 v59, v49, v53
	v_fmac_f32_e32 v60, v50, v54
	v_fmac_f32_e32 v61, v51, v55
	v_cvt_pk_bf16_f32 v48, v58, v59
	v_cvt_pk_bf16_f32 v49, v60, v61
	v_addc_co_u32_e32 v53, vcc, 0, v121, vcc
	global_store_dwordx2 v[56:57], v[48:49], off
	s_waitcnt vmcnt(7)
	v_mov_b32_e32 v48, v200
	v_mov_b32_e32 v49, v201
	v_lshlrev_b32_e32 v54, 16, v48
	v_and_b32_e32 v55, 0xffff0000, v48
	v_lshlrev_b32_e32 v56, 16, v49
	v_and_b32_e32 v57, 0xffff0000, v49
	s_waitcnt vmcnt(7) lgkmcnt(3)
	v_mov_b32_e32 v48, v212
	v_mov_b32_e32 v49, v213
	v_mov_b32_e32 v50, v214
	v_mov_b32_e32 v51, v215
	v_fmac_f32_e32 v54, v44, v48
	v_add_co_u32_e32 v48, vcc, s88, v120
	v_fmac_f32_e32 v55, v45, v49
	v_fmac_f32_e32 v56, v46, v50
	v_fmac_f32_e32 v57, v47, v51
	v_cvt_pk_bf16_f32 v44, v54, v55
	v_cvt_pk_bf16_f32 v45, v56, v57
	v_addc_co_u32_e32 v49, vcc, 0, v121, vcc
	global_store_dwordx2 v[52:53], v[44:45], off
	s_waitcnt vmcnt(7)
; DI void st4(u16* p, float a, float b, float c, float d) { u32x2 w = {cvtpk(a, b), cvtpk(c, d)}; *(u32x2*)p = w; }
;   DI void operator()(int m, int n, f32x4 v) const { st4(dst + (size_t)m * ld + n, v[0], v[1], v[2], v[3]); }
; DI void ld4bf(const u16* p, float* o) { const u32x2 w = *(const u32x2*)p; o[0] = __uint_as_float(w[0] << 16); o[1] = __uint_as_float(w[0] & 0xffff0000u); o[2] = __uint_as_float(w[1] << 16); o[3] = __uint_as_float(w[1] & 0xffff0000u); }
;   DI void operator()(int m, int n, f32x4 v) const {
;     float x[4]; ld4bf(xb + (size_t)m * 1024 + n, x);
;     const f32x4 g = *(const f32x4*)(gate + n);
;     st4(xb + (size_t)m * 1024 + n, x[0] + g[0] * v[0], x[1] + g[1] * v[1], x[2] + g[2] * v[2], x[3] + g[3] * v[3]);
;   }
	v_mov_b32_e32 v44, v202
	v_mov_b32_e32 v45, v203
	v_lshlrev_b32_e32 v50, 16, v44
	v_and_b32_e32 v51, 0xffff0000, v44
	v_lshlrev_b32_e32 v52, 16, v45
	v_and_b32_e32 v53, 0xffff0000, v45
	s_waitcnt vmcnt(7) lgkmcnt(2)
	v_mov_b32_e32 v44, v212
	v_mov_b32_e32 v45, v213
	v_mov_b32_e32 v46, v214
	v_mov_b32_e32 v47, v215
	v_fmac_f32_e32 v50, v40, v44
	v_add_co_u32_e32 v44, vcc, s94, v120
	v_fmac_f32_e32 v51, v41, v45
	v_fmac_f32_e32 v52, v42, v46
	v_fmac_f32_e32 v53, v43, v47
	v_cvt_pk_bf16_f32 v40, v50, v51
	v_cvt_pk_bf16_f32 v41, v52, v53
	v_addc_co_u32_e32 v45, vcc, 0, v121, vcc
	global_store_dwordx2 v[48:49], v[40:41], off
	s_waitcnt vmcnt(7)
	v_mov_b32_e32 v40, v204
	v_mov_b32_e32 v41, v205
	v_lshlrev_b32_e32 v46, 16, v40
	v_and_b32_e32 v47, 0xffff0000, v40
	v_lshlrev_b32_e32 v48, 16, v41
	v_and_b32_e32 v49, 0xffff0000, v41
	s_waitcnt vmcnt(7) lgkmcnt(1)
	v_mov_b32_e32 v40, v212
	v_mov_b32_e32 v41, v213
	v_mov_b32_e32 v42, v214
	v_mov_b32_e32 v43, v215
	v_fmac_f32_e32 v46, v36, v40
	v_add_co_u32_e32 v40, vcc, s95, v120
	v_fmac_f32_e32 v47, v37, v41
	v_fmac_f32_e32 v48, v38, v42
	v_fmac_f32_e32 v49, v39, v43
	v_cvt_pk_bf16_f32 v36, v46, v47
	v_cvt_pk_bf16_f32 v37, v48, v49
	v_addc_co_u32_e32 v41, vcc, 0, v121, vcc
	global_store_dwordx2 v[44:45], v[36:37], off
	s_waitcnt vmcnt(7)
	v_mov_b32_e32 v36, v206
	v_mov_b32_e32 v37, v207
	v_lshlrev_b32_e32 v42, 16, v36
	v_and_b32_e32 v43, 0xffff0000, v36
	v_lshlrev_b32_e32 v44, 16, v37
	v_and_b32_e32 v45, 0xffff0000, v37
	s_waitcnt vmcnt(7) lgkmcnt(0)
	v_mov_b32_e32 v36, v212
	v_mov_b32_e32 v37, v213
	v_mov_b32_e32 v38, v214
	v_mov_b32_e32 v39, v215
	v_fmac_f32_e32 v42, v32, v36
	v_fmac_f32_e32 v43, v33, v37
	v_fmac_f32_e32 v44, v34, v38
	v_fmac_f32_e32 v45, v35, v39
	v_cvt_pk_bf16_f32 v32, v42, v43
	v_cvt_pk_bf16_f32 v33, v44, v45
	global_store_dwordx2 v[40:41], v[32:33], off
	s_waitcnt lgkmcnt(0)
	ds_write2_b32 v130, v8, v12 offset1:16
	ds_write2_b32 v130, v9, v13 offset0:68 offset1:84
	ds_write2_b32 v130, v10, v14 offset0:136 offset1:152
	ds_write2_b32 v130, v11, v15 offset0:204 offset1:220
	ds_write2_b32 v130, v24, v28 offset0:32 offset1:48
	ds_write2_b32 v130, v25, v29 offset0:100 offset1:116
	ds_write2_b32 v130, v26, v30 offset0:168 offset1:184
	ds_write2_b32 v130, v27, v31 offset0:236 offset1:252
	ds_write2_b32 v123, v0, v4 offset0:64 offset1:80
	ds_write2_b32 v123, v1, v5 offset0:132 offset1:148
	ds_write2_b32 v123, v2, v6 offset0:200 offset1:216
	ds_write2_b32 v125, v3, v7 offset0:12 offset1:28
	ds_write2_b32 v123, v16, v20 offset0:96 offset1:112
	ds_write2_b32 v123, v17, v21 offset0:164 offset1:180
	ds_write2_b32 v123, v18, v22 offset0:232 offset1:248
	ds_write2_b32 v125, v19, v23 offset0:44 offset1:60
	v_add_co_u32_e32 v36, vcc, s12, v120
	s_waitcnt lgkmcnt(0)
	ds_read_b128 v[28:31], v124
	ds_read_b128 v[24:27], v124 offset:1088
	ds_read_b128 v[20:23], v124 offset:2176
	ds_read_b128 v[16:19], v124 offset:3264
	ds_read_b128 v[12:15], v124 offset:4352
	ds_read_b128 v[8:11], v124 offset:5440
	ds_read_b128 v[4:7], v124 offset:6528
	ds_read_b128 v[0:3], v124 offset:7616
	v_addc_co_u32_e32 v37, vcc, 0, v121, vcc
	v_mov_b32_e32 v216, 0x2000
	v_mov_b32_e32 v217, 0
	global_load_dwordx2 v[192:193], v[36:37], off
	v_lshl_add_u64 v[208:209], v[36:37], 0, v[216:217]
	global_load_dwordx2 v[194:195], v[208:209], off
	v_lshl_add_u64 v[208:209], v[208:209], 0, v[216:217]
	global_load_dwordx2 v[196:197], v[208:209], off
	v_lshl_add_u64 v[208:209], v[208:209], 0, v[216:217]
	global_load_dwordx2 v[198:199], v[208:209], off
	v_lshl_add_u64 v[208:209], v[208:209], 0, v[216:217]
	global_load_dwordx2 v[200:201], v[208:209], off
	v_lshl_add_u64 v[208:209], v[208:209], 0, v[216:217]
	global_load_dwordx2 v[202:203], v[208:209], off
	v_lshl_add_u64 v[208:209], v[208:209], 0, v[216:217]
	global_load_dwordx2 v[204:205], v[208:209], off
	v_lshl_add_u64 v[208:209], v[208:209], 0, v[216:217]
	global_load_dwordx2 v[206:207], v[208:209], off
	s_mov_b32 s12, 0x52000
	s_waitcnt vmcnt(7)
	v_mov_b32_e32 v32, v192
	v_mov_b32_e32 v33, v193
	v_lshlrev_b32_e32 v38, 16, v32
	v_and_b32_e32 v39, 0xffff0000, v32
	v_lshlrev_b32_e32 v40, 16, v33
	v_and_b32_e32 v41, 0xffff0000, v33
	s_waitcnt vmcnt(7) lgkmcnt(7)
	v_mov_b32_e32 v32, v212
	v_mov_b32_e32 v33, v213
	v_mov_b32_e32 v34, v214
	v_mov_b32_e32 v35, v215
	v_fmac_f32_e32 v38, v28, v32
	v_add_co_u32_e32 v32, vcc, s12, v120
	v_fmac_f32_e32 v39, v29, v33
	v_fmac_f32_e32 v40, v30, v34
	v_fmac_f32_e32 v41, v31, v35
	v_cvt_pk_bf16_f32 v28, v38, v39
	v_cvt_pk_bf16_f32 v29, v40, v41
	v_addc_co_u32_e32 v33, vcc, 0, v121, vcc
	global_store_dwordx2 v[36:37], v[28:29], off
	s_mov_b32 s12, 0x54000
	s_waitcnt vmcnt(7)
	v_mov_b32_e32 v28, v194
	v_mov_b32_e32 v29, v195
	v_lshlrev_b32_e32 v34, 16, v28
	v_and_b32_e32 v35, 0xffff0000, v28
	v_lshlrev_b32_e32 v36, 16, v29
	v_and_b32_e32 v37, 0xffff0000, v29
	s_waitcnt vmcnt(7) lgkmcnt(6)
; DI void st4(u16* p, float a, float b, float c, float d) { u32x2 w = {cvtpk(a, b), cvtpk(c, d)}; *(u32x2*)p = w; }
;   DI void operator()(int m, int n, f32x4 v) const { st4(dst + (size_t)m * ld + n, v[0], v[1], v[2], v[3]); }
; DI void ld4bf(const u16* p, float* o) { const u32x2 w = *(const u32x2*)p; o[0] = __uint_as_float(w[0] << 16); o[1] = __uint_as_float(w[0] & 0xffff0000u); o[2] = __uint_as_float(w[1] << 16); o[3] = __uint_as_float(w[1] & 0xffff0000u); }
; #define TILE_LOOP(q, x, NPX) for (int lin_ = (nb == 256 ? (bid >> 3) : bid), q = (nb == 256 ? lin_ : lin_ / 8), x = (nb == 256 ? (bid & 7) : lin_ % 8); \
;     (nb == 256 ? q < (NPX) : lin_ < 8 * (NPX)); lin_ += (nb == 256 ? 32 : nb), q = (nb == 256 ? lin_ : lin_ / 8), x = (nb == 256 ? x : lin_ % 8))
;   DI void operator()(int m, int n, f32x4 v) const {
;     float x[4]; ld4bf(xb + (size_t)m * 1024 + n, x);
;     const f32x4 g = *(const f32x4*)(gate + n);
;     st4(xb + (size_t)m * 1024 + n, x[0] + g[0] * v[0], x[1] + g[1] * v[1], x[2] + g[2] * v[2], x[3] + g[3] * v[3]);
;   }
; DI void phase_resid_gemm(int layer, int g, int kind, char* smem) {
;     ...
;   TILE_LOOP(q, x, npx) {
;     const int mt = (q >> 2) * 8 + x, nt = q & 3, s = seq0 + (mt >> 4);
;     const size_t to = (size_t)mt * 256 * 1024 + nt * 256;
;     const float* gate = modl + (size_t)s * 6144 + goff + nt * 256;
;     if (kind == 0) { EpiResidF e{xin + to, xb + to, gate}; gemm_tile<false>(A + (size_t)mt * 256 * K, K, B + (size_t)(nt * 256) * K, K, K, (u16*)smem, e); }
;     else { EpiResidB e{xb + to, gate}; gemm_tile<false>(A + (size_t)mt * 256 * K, K, B + (size_t)(nt * 256) * K, K, K, (u16*)smem, e); }
	v_mov_b32_e32 v28, v212
	v_mov_b32_e32 v29, v213
	v_mov_b32_e32 v30, v214
	v_mov_b32_e32 v31, v215
	v_fmac_f32_e32 v34, v24, v28
	v_add_co_u32_e32 v28, vcc, s12, v120
	v_fmac_f32_e32 v35, v25, v29
	v_fmac_f32_e32 v36, v26, v30
	v_fmac_f32_e32 v37, v27, v31
	v_cvt_pk_bf16_f32 v24, v34, v35
	v_cvt_pk_bf16_f32 v25, v36, v37
	v_addc_co_u32_e32 v29, vcc, 0, v121, vcc
	global_store_dwordx2 v[32:33], v[24:25], off
	s_mov_b32 s12, 0x56000
	s_waitcnt vmcnt(7)
	v_mov_b32_e32 v24, v196
	v_mov_b32_e32 v25, v197
	v_lshlrev_b32_e32 v30, 16, v24
	v_and_b32_e32 v31, 0xffff0000, v24
	v_lshlrev_b32_e32 v32, 16, v25
	v_and_b32_e32 v33, 0xffff0000, v25
	s_waitcnt vmcnt(7) lgkmcnt(5)
	v_mov_b32_e32 v24, v212
	v_mov_b32_e32 v25, v213
	v_mov_b32_e32 v26, v214
	v_mov_b32_e32 v27, v215
	v_fmac_f32_e32 v30, v20, v24
	v_add_co_u32_e32 v24, vcc, s12, v120
	v_fmac_f32_e32 v31, v21, v25
	v_fmac_f32_e32 v32, v22, v26
	v_fmac_f32_e32 v33, v23, v27
	v_cvt_pk_bf16_f32 v20, v30, v31
	v_cvt_pk_bf16_f32 v21, v32, v33
	v_addc_co_u32_e32 v25, vcc, 0, v121, vcc
	global_store_dwordx2 v[28:29], v[20:21], off
	s_mov_b32 s12, 0x58000
	s_waitcnt vmcnt(7)
	v_mov_b32_e32 v20, v198
	v_mov_b32_e32 v21, v199
	v_lshlrev_b32_e32 v26, 16, v20
	v_and_b32_e32 v27, 0xffff0000, v20
	v_lshlrev_b32_e32 v28, 16, v21
	v_and_b32_e32 v29, 0xffff0000, v21
	s_waitcnt vmcnt(7) lgkmcnt(4)
	v_mov_b32_e32 v20, v212
	v_mov_b32_e32 v21, v213
	v_mov_b32_e32 v22, v214
	v_mov_b32_e32 v23, v215
	v_fmac_f32_e32 v26, v16, v20
	v_add_co_u32_e32 v20, vcc, s12, v120
	v_fmac_f32_e32 v27, v17, v21
	v_fmac_f32_e32 v28, v18, v22
	v_fmac_f32_e32 v29, v19, v23
	v_cvt_pk_bf16_f32 v16, v26, v27
	v_cvt_pk_bf16_f32 v17, v28, v29
	v_addc_co_u32_e32 v21, vcc, 0, v121, vcc
	global_store_dwordx2 v[24:25], v[16:17], off
	s_mov_b32 s12, 0x5a000
	s_waitcnt vmcnt(7)
	v_mov_b32_e32 v16, v200
	v_mov_b32_e32 v17, v201
	v_lshlrev_b32_e32 v22, 16, v16
	v_and_b32_e32 v23, 0xffff0000, v16
	v_lshlrev_b32_e32 v24, 16, v17
	v_and_b32_e32 v25, 0xffff0000, v17
	s_waitcnt vmcnt(7) lgkmcnt(3)
	v_mov_b32_e32 v16, v212
	v_mov_b32_e32 v17, v213
	v_mov_b32_e32 v18, v214
	v_mov_b32_e32 v19, v215
	v_fmac_f32_e32 v22, v12, v16
	v_add_co_u32_e32 v16, vcc, s12, v120
	v_fmac_f32_e32 v23, v13, v17
	v_fmac_f32_e32 v24, v14, v18
	v_fmac_f32_e32 v25, v15, v19
	v_cvt_pk_bf16_f32 v12, v22, v23
	v_cvt_pk_bf16_f32 v13, v24, v25
	v_addc_co_u32_e32 v17, vcc, 0, v121, vcc
	global_store_dwordx2 v[20:21], v[12:13], off
	s_mov_b32 s12, 0x5c000
	s_waitcnt vmcnt(7)
	v_mov_b32_e32 v12, v202
	v_mov_b32_e32 v13, v203
	v_lshlrev_b32_e32 v18, 16, v12
	v_and_b32_e32 v19, 0xffff0000, v12
	v_lshlrev_b32_e32 v20, 16, v13
	v_and_b32_e32 v21, 0xffff0000, v13
	s_waitcnt vmcnt(7) lgkmcnt(2)
	v_mov_b32_e32 v12, v212
	v_mov_b32_e32 v13, v213
	v_mov_b32_e32 v14, v214
	v_mov_b32_e32 v15, v215
	v_fmac_f32_e32 v18, v8, v12
	v_add_co_u32_e32 v12, vcc, s12, v120
	v_fmac_f32_e32 v19, v9, v13
	v_fmac_f32_e32 v20, v10, v14
	v_fmac_f32_e32 v21, v11, v15
	v_cvt_pk_bf16_f32 v8, v18, v19
	v_cvt_pk_bf16_f32 v9, v20, v21
	v_addc_co_u32_e32 v13, vcc, 0, v121, vcc
	global_store_dwordx2 v[16:17], v[8:9], off
	s_ashr_i32 s12, s26, 31
	s_lshr_b32 s12, s12, 29
	s_waitcnt vmcnt(7)
	v_mov_b32_e32 v8, v204
	v_mov_b32_e32 v9, v205
	v_lshlrev_b32_e32 v14, 16, v8
	v_and_b32_e32 v15, 0xffff0000, v8
	v_lshlrev_b32_e32 v16, 16, v9
	v_and_b32_e32 v17, 0xffff0000, v9
	s_waitcnt vmcnt(7) lgkmcnt(1)
	v_mov_b32_e32 v8, v212
	v_mov_b32_e32 v9, v213
	v_mov_b32_e32 v10, v214
	v_mov_b32_e32 v11, v215
	v_fmac_f32_e32 v14, v4, v8
	v_add_co_u32_e32 v8, vcc, s39, v120
	v_fmac_f32_e32 v15, v5, v9
	v_fmac_f32_e32 v16, v6, v10
	v_fmac_f32_e32 v17, v7, v11
	v_cvt_pk_bf16_f32 v4, v14, v15
	v_cvt_pk_bf16_f32 v5, v16, v17
	v_addc_co_u32_e32 v9, vcc, 0, v121, vcc
	global_store_dwordx2 v[12:13], v[4:5], off
	s_waitcnt vmcnt(7)
	v_mov_b32_e32 v4, v206
	v_mov_b32_e32 v5, v207
	v_lshlrev_b32_e32 v10, 16, v4
	v_and_b32_e32 v11, 0xffff0000, v4
	v_lshlrev_b32_e32 v12, 16, v5
	v_and_b32_e32 v13, 0xffff0000, v5
	s_add_i32 s20, s26, s12
	s_ashr_i32 s21, s20, 3
	s_and_b64 s[12:13], s[6:7], exec
	s_cselect_b32 s24, s26, s21
	s_and_b32 s12, s20, -8
	s_sub_i32 s20, s26, s12
	s_and_b64 s[12:13], s[6:7], exec
	s_cselect_b32 s11, s11, s20
	s_cmp_lt_i32 s24, 32
	s_cselect_b64 s[12:13], -1, 0
	s_cmpk_lt_i32 s26, 0x100
	s_cselect_b64 s[20:21], -1, 0
	s_waitcnt vmcnt(7) lgkmcnt(0)
	v_mov_b32_e32 v4, v212
	v_mov_b32_e32 v5, v213
	v_mov_b32_e32 v6, v214
	v_mov_b32_e32 v7, v215
	v_fmac_f32_e32 v10, v0, v4
	v_fmac_f32_e32 v11, v1, v5
	v_fmac_f32_e32 v12, v2, v6
	v_fmac_f32_e32 v13, v3, v7
	v_cvt_pk_bf16_f32 v0, v10, v11
	v_cvt_pk_bf16_f32 v1, v12, v13
	global_store_dwordx2 v[8:9], v[0:1], off
	v_cndmask_b32_e64 v0, 0, 1, s[12:13]
	v_cndmask_b32_e64 v1, 0, 1, s[20:21]
	v_cndmask_b32_e64 v0, v1, v0, s[6:7]
	s_waitcnt lgkmcnt(0)
	v_and_b32_e32 v0, 1, v0
	v_cmp_eq_u32_e32 vcc, 1, v0
	s_barrier
	s_cbranch_vccz .LBB0_1503
